# combo: B0 reads one phase early + dup-wait removal + prep sunk below barrier + setprio0 after barrier in all GEMM K-loops
# speedup vs baseline: 1.0100x; 1.0038x over previous
; #define PG8_STAGE(bufoff, gbase, voff) do { _Pragma("unroll") for (int _i = 0; _i < 2; ++_i) \
;     __builtin_amdgcn_global_load_lds((const unsigned*)((const char*)(gbase) + (voff)[_i]), (LAS unsigned*)(lds + (bufoff) + ldsw + _i * 8192), 16, 0, 0); } while (0)
; #define PG8_LDA(dst, b, h) do { _Pragma("unroll") for (int m = 0; m < 4; ++m) _Pragma("unroll") for (int k = 0; k < 2; ++k) dst[m][k] = *(const LAS bf16x8*)(lds + PG8_SA(b, h) + aoff + m * 2048 + k * 1024); } while (0)
; #define PG8_LDB(dst, b, h) do { _Pragma("unroll") for (int n = 0; n < 2; ++n) _Pragma("unroll") for (int k = 0; k < 2; ++k) dst[n][k] = *(const LAS bf16x8*)(lds + PG8_SB(b, h) + boff + n * 2048 + k * 1024); } while (0)
; #define PG8_MMA(ai, bj, At, Bt) do { __builtin_amdgcn_s_setprio(1); _Pragma("unroll") for (int m = 0; m < 4; ++m) _Pragma("unroll") for (int n = 0; n < 2; ++n) _Pragma("unroll") for (int k = 0; k < 2; ++k) \
;     acc[ai][bj][m][n] = __builtin_amdgcn_mfma_f32_16x16x32_bf16(Bt[n][k], At[m][k], acc[ai][bj][m][n], 0, 0, 0); __builtin_amdgcn_s_setprio(0); } while (0)
; #define PG8_WAIT_V(n) asm volatile("s_waitcnt vmcnt(" #n ")" ::: "memory")
; #define PG8_WAIT_L(n) asm volatile("s_waitcnt lgkmcnt(" #n ")" ::: "memory")
; #define PG8_BAR __builtin_amdgcn_s_barrier()
; #define PG8_SCHED __builtin_amdgcn_sched_barrier(0)
; template <class Epi, class Sched = StaticOrder>
; DI void gemm_phase(LAS unsigned char* lds, const Gemm g, const Sched& S, const Epi& E) {
;     ...
;       PG8_LDB(B0, 0, 0); PG8_SCHED; PG8_LDA(At, 0, 0); PG8_STAGE(PG8_SA(1, 1), a1 + hstep, voffA);
;       PG8_WAIT_L(8); PG8_BAR; PG8_WAIT_L(0); PG8_MMA(0, 0, At, B0); PG8_BAR; PG8_SCHED;
;       PG8_LDB(B1, 0, 1); PG8_STAGE(PG8_SB(0, 0), b2, voffB);
;       PG8_BAR; PG8_WAIT_L(0); PG8_MMA(0, 1, At, B1); PG8_BAR;
;       PG8_LDA(At, 0, 1); PG8_STAGE(PG8_SA(0, 0), a2, voffA);
;       PG8_BAR; PG8_WAIT_L(0); PG8_MMA(1, 0, At, B0); PG8_BAR; PG8_SCHED;
;       PG8_STAGE(PG8_SB(0, 1), b2 + hstep, voffB);
;       PG8_WAIT_V(6); PG8_BAR; PG8_MMA(1, 1, At, B1); PG8_BAR;
.LBB0_346:
	s_add_u32 s8, s6, 0xfff80080
	s_addc_u32 s9, s7, -1
	s_cmp_eq_u32 s52, 28
	s_cselect_b32 s11, s31, s9
	s_cselect_b32 s10, s42, s8
	s_cselect_b32 s9, s29, s45
	s_cselect_b32 s8, s43, s44
	v_lshl_add_u64 v[202:203], s[6:7], 0, v[146:147]
	s_add_i32 m0, s48, 0xc000
	ds_read_b128 v[162:165], v174
	ds_read_b128 v[166:169], v174 offset:1024
	ds_read_b128 v[178:181], v174 offset:2048
	ds_read_b128 v[182:185], v174 offset:3072
	ds_read_b128 v[186:189], v174 offset:4096
	ds_read_b128 v[190:193], v174 offset:5120
	ds_read_b128 v[194:197], v174 offset:6144
	ds_read_b128 v[198:201], v174 offset:7168
	global_load_lds_dwordx4 v[202:203], off
	v_lshl_add_u64 v[202:203], s[6:7], 0, v[148:149]
	s_add_i32 m0, s48, 0xe000
	s_nop 0
	global_load_lds_dwordx4 v[202:203], off
	s_waitcnt lgkmcnt(8)
	s_barrier
	s_waitcnt lgkmcnt(0)
	s_setprio 1
	v_mfma_f32_16x16x32_bf16 v[124:127], v[128:131], v[162:165], v[124:127]
	v_mfma_f32_16x16x32_bf16 v[120:123], v[154:157], v[162:165], v[120:123]
	v_mfma_f32_16x16x32_bf16 v[108:111], v[128:131], v[178:181], v[108:111]
	v_mfma_f32_16x16x32_bf16 v[104:107], v[154:157], v[178:181], v[104:107]
	v_mfma_f32_16x16x32_bf16 v[100:103], v[128:131], v[186:189], v[100:103]
	v_mfma_f32_16x16x32_bf16 v[92:95], v[154:157], v[186:189], v[92:95]
	v_mfma_f32_16x16x32_bf16 v[84:87], v[128:131], v[194:197], v[84:87]
	v_mfma_f32_16x16x32_bf16 v[76:79], v[154:157], v[194:197], v[76:79]
	v_mfma_f32_16x16x32_bf16 v[124:127], v[132:135], v[166:169], v[124:127]
	v_mfma_f32_16x16x32_bf16 v[120:123], v[158:161], v[166:169], v[120:123]
	v_mfma_f32_16x16x32_bf16 v[108:111], v[132:135], v[182:185], v[108:111]
	v_mfma_f32_16x16x32_bf16 v[104:107], v[158:161], v[182:185], v[104:107]
	v_mfma_f32_16x16x32_bf16 v[100:103], v[132:135], v[190:193], v[100:103]
	v_mfma_f32_16x16x32_bf16 v[92:95], v[158:161], v[190:193], v[92:95]
	v_mfma_f32_16x16x32_bf16 v[84:87], v[132:135], v[198:201], v[84:87]
	v_mfma_f32_16x16x32_bf16 v[76:79], v[158:161], v[198:201], v[76:79]
	s_barrier
	s_setprio 0
	s_add_i32 s53, s65, s41
	v_lshl_add_u64 v[220:221], s[8:9], 0, v[140:141]
	s_mov_b32 m0, s53
	ds_read_b128 v[202:205], v175
	ds_read_b128 v[206:209], v175 offset:1024
	ds_read_b128 v[212:215], v175 offset:2048
	ds_read_b128 v[216:219], v175 offset:3072
	global_load_lds_dwordx4 v[220:221], off
	v_lshl_add_u64 v[222:223], s[8:9], 0, v[136:137]
	s_add_i32 m0, s53, 0x2000
	s_nop 0
	global_load_lds_dwordx4 v[222:223], off
	s_barrier
	s_waitcnt lgkmcnt(0)
	s_setprio 1
	v_mfma_f32_16x16x32_bf16 v[116:119], v[202:205], v[162:165], v[116:119]
	v_mfma_f32_16x16x32_bf16 v[112:115], v[212:215], v[162:165], v[112:115]
	v_mfma_f32_16x16x32_bf16 v[96:99], v[202:205], v[178:181], v[96:99]
	v_mfma_f32_16x16x32_bf16 v[88:91], v[212:215], v[178:181], v[88:91]
	v_mfma_f32_16x16x32_bf16 v[80:83], v[202:205], v[186:189], v[80:83]
	v_mfma_f32_16x16x32_bf16 v[72:75], v[212:215], v[186:189], v[72:75]
	v_mfma_f32_16x16x32_bf16 v[68:71], v[202:205], v[194:197], v[68:71]
	v_mfma_f32_16x16x32_bf16 v[64:67], v[212:215], v[194:197], v[64:67]
	v_mfma_f32_16x16x32_bf16 v[116:119], v[206:209], v[166:169], v[116:119]
	v_mfma_f32_16x16x32_bf16 v[112:115], v[216:219], v[166:169], v[112:115]
	v_mfma_f32_16x16x32_bf16 v[96:99], v[206:209], v[182:185], v[96:99]
	v_mfma_f32_16x16x32_bf16 v[88:91], v[216:219], v[182:185], v[88:91]
	v_mfma_f32_16x16x32_bf16 v[80:83], v[206:209], v[190:193], v[80:83]
	v_mfma_f32_16x16x32_bf16 v[72:75], v[216:219], v[190:193], v[72:75]
	v_mfma_f32_16x16x32_bf16 v[68:71], v[206:209], v[198:201], v[68:71]
	v_mfma_f32_16x16x32_bf16 v[64:67], v[216:219], v[198:201], v[64:67]
	s_barrier
	s_setprio 0
	s_mov_b32 m0, s48
	v_lshl_add_u64 v[224:225], s[10:11], 0, v[142:143]
	ds_read_b128 v[162:165], v174 offset:16384
	ds_read_b128 v[166:169], v174 offset:17408
	ds_read_b128 v[178:181], v174 offset:18432
	ds_read_b128 v[182:185], v174 offset:19456
	ds_read_b128 v[186:189], v174 offset:20480
	ds_read_b128 v[190:193], v174 offset:21504
	ds_read_b128 v[194:197], v174 offset:22528
	ds_read_b128 v[198:201], v174 offset:23552
	global_load_lds_dwordx4 v[224:225], off
	v_lshl_add_u64 v[226:227], s[10:11], 0, v[138:139]
	s_mov_b32 m0, s49
	s_nop 0
	global_load_lds_dwordx4 v[226:227], off
	s_waitcnt vmcnt(10)
	s_barrier
	s_waitcnt lgkmcnt(0)
	s_setprio 1
	v_mfma_f32_16x16x32_bf16 v[60:63], v[128:131], v[162:165], v[60:63]
	v_mfma_f32_16x16x32_bf16 v[56:59], v[154:157], v[162:165], v[56:59]
	v_mfma_f32_16x16x32_bf16 v[52:55], v[128:131], v[178:181], v[52:55]
	v_mfma_f32_16x16x32_bf16 v[44:47], v[154:157], v[178:181], v[44:47]
	v_mfma_f32_16x16x32_bf16 v[36:39], v[128:131], v[186:189], v[36:39]
	v_mfma_f32_16x16x32_bf16 v[28:31], v[154:157], v[186:189], v[28:31]
	v_mfma_f32_16x16x32_bf16 v[20:23], v[128:131], v[194:197], v[20:23]
	v_mfma_f32_16x16x32_bf16 v[12:15], v[154:157], v[194:197], v[12:15]
	v_mfma_f32_16x16x32_bf16 v[60:63], v[132:135], v[166:169], v[60:63]
	v_mfma_f32_16x16x32_bf16 v[56:59], v[158:161], v[166:169], v[56:59]
	v_mfma_f32_16x16x32_bf16 v[52:55], v[132:135], v[182:185], v[52:55]
	v_mfma_f32_16x16x32_bf16 v[44:47], v[158:161], v[182:185], v[44:47]
	v_mfma_f32_16x16x32_bf16 v[36:39], v[132:135], v[190:193], v[36:39]
	v_mfma_f32_16x16x32_bf16 v[28:31], v[158:161], v[190:193], v[28:31]
	v_mfma_f32_16x16x32_bf16 v[20:23], v[132:135], v[198:201], v[20:23]
	v_mfma_f32_16x16x32_bf16 v[12:15], v[158:161], v[198:201], v[12:15]
	s_barrier
; #define PG8_STAGE(bufoff, gbase, voff) do { _Pragma("unroll") for (int _i = 0; _i < 2; ++_i) \
;     __builtin_amdgcn_global_load_lds((const unsigned*)((const char*)(gbase) + (voff)[_i]), (LAS unsigned*)(lds + (bufoff) + ldsw + _i * 8192), 16, 0, 0); } while (0)
; #define PG8_LDA(dst, b, h) do { _Pragma("unroll") for (int m = 0; m < 4; ++m) _Pragma("unroll") for (int k = 0; k < 2; ++k) dst[m][k] = *(const LAS bf16x8*)(lds + PG8_SA(b, h) + aoff + m * 2048 + k * 1024); } while (0)
; #define PG8_LDB(dst, b, h) do { _Pragma("unroll") for (int n = 0; n < 2; ++n) _Pragma("unroll") for (int k = 0; k < 2; ++k) dst[n][k] = *(const LAS bf16x8*)(lds + PG8_SB(b, h) + boff + n * 2048 + k * 1024); } while (0)
; #define PG8_MMA(ai, bj, At, Bt) do { __builtin_amdgcn_s_setprio(1); _Pragma("unroll") for (int m = 0; m < 4; ++m) _Pragma("unroll") for (int n = 0; n < 2; ++n) _Pragma("unroll") for (int k = 0; k < 2; ++k) \
;     acc[ai][bj][m][n] = __builtin_amdgcn_mfma_f32_16x16x32_bf16(Bt[n][k], At[m][k], acc[ai][bj][m][n], 0, 0, 0); __builtin_amdgcn_s_setprio(0); } while (0)
; #define PG8_WAIT_V(n) asm volatile("s_waitcnt vmcnt(" #n ")" ::: "memory")
; #define PG8_WAIT_L(n) asm volatile("s_waitcnt lgkmcnt(" #n ")" ::: "memory")
; #define PG8_BAR __builtin_amdgcn_s_barrier()
; #define PG8_SCHED __builtin_amdgcn_sched_barrier(0)
; template <class Epi, class Sched = StaticOrder>
; DI void gemm_phase(LAS unsigned char* lds, const Gemm g, const Sched& S, const Epi& E) {
;     ...
;       PG8_STAGE(PG8_SB(0, 1), b2 + hstep, voffB);
;       PG8_WAIT_V(6); PG8_BAR; PG8_MMA(1, 1, At, B1); PG8_BAR;
;       PG8_LDB(B0, 1, 0); PG8_SCHED; PG8_LDA(At, 1, 0); PG8_STAGE(PG8_SA(0, 1), a2 + hstep, voffA);
;       PG8_WAIT_L(8); PG8_BAR; PG8_WAIT_L(0); PG8_MMA(0, 0, At, B0); PG8_BAR; PG8_SCHED;
;       PG8_LDB(B1, 1, 1); PG8_STAGE(PG8_SB(1, 0), b3, voffB);
;       PG8_BAR; PG8_WAIT_L(0); PG8_MMA(0, 1, At, B1); PG8_BAR;
;       PG8_LDA(At, 1, 1); PG8_STAGE(PG8_SA(1, 0), a3, voffA);
	s_setprio 0
	s_add_u32 s54, s8, 0x80000
	s_addc_u32 s55, s9, 0
	s_add_i32 s53, s72, s41
	v_lshl_add_u64 v[128:129], s[54:55], 0, v[140:141]
	s_mov_b32 m0, s53
	s_nop 0
	global_load_lds_dwordx4 v[128:129], off
	v_lshl_add_u64 v[128:129], s[54:55], 0, v[136:137]
	s_add_i32 m0, s53, 0x2000
	s_nop 0
	global_load_lds_dwordx4 v[128:129], off
	s_add_i32 s53, 0, 0x18000
	v_add_u32_e32 v158, s53, v171
	ds_read_b128 v[128:131], v158
	ds_read_b128 v[132:135], v158 offset:1024
	ds_read_b128 v[154:157], v158 offset:2048
	ds_read_b128 v[158:161], v158 offset:3072
	s_waitcnt vmcnt(6)
	s_barrier
	s_setprio 1
	v_mfma_f32_16x16x32_bf16 v[48:51], v[202:205], v[162:165], v[48:51]
	v_mfma_f32_16x16x32_bf16 v[40:43], v[212:215], v[162:165], v[40:43]
	v_mfma_f32_16x16x32_bf16 v[32:35], v[202:205], v[178:181], v[32:35]
	v_mfma_f32_16x16x32_bf16 v[24:27], v[212:215], v[178:181], v[24:27]
	v_mfma_f32_16x16x32_bf16 v[16:19], v[202:205], v[186:189], v[16:19]
	v_mfma_f32_16x16x32_bf16 v[8:11], v[212:215], v[186:189], v[8:11]
	v_mfma_f32_16x16x32_bf16 v[4:7], v[202:205], v[194:197], v[4:7]
	v_mfma_f32_16x16x32_bf16 v[0:3], v[212:215], v[194:197], v[0:3]
	v_mfma_f32_16x16x32_bf16 v[48:51], v[206:209], v[166:169], v[48:51]
	v_mfma_f32_16x16x32_bf16 v[40:43], v[216:219], v[166:169], v[40:43]
	v_mfma_f32_16x16x32_bf16 v[32:35], v[206:209], v[182:185], v[32:35]
	v_mfma_f32_16x16x32_bf16 v[24:27], v[216:219], v[182:185], v[24:27]
	v_mfma_f32_16x16x32_bf16 v[16:19], v[206:209], v[190:193], v[16:19]
	v_mfma_f32_16x16x32_bf16 v[8:11], v[216:219], v[190:193], v[8:11]
	v_mfma_f32_16x16x32_bf16 v[4:7], v[206:209], v[198:201], v[4:7]
	v_mfma_f32_16x16x32_bf16 v[0:3], v[216:219], v[198:201], v[0:3]
	s_barrier
	s_setprio 0
	s_add_u32 s10, s10, 0x80000
	s_addc_u32 s11, s11, 0
	s_mov_b32 m0, s50
	v_lshl_add_u64 v[202:203], s[10:11], 0, v[142:143]
	ds_read_b128 v[162:165], v174 offset:32768
	ds_read_b128 v[166:169], v174 offset:33792
	ds_read_b128 v[178:181], v174 offset:34816
	ds_read_b128 v[182:185], v174 offset:35840
	ds_read_b128 v[186:189], v174 offset:36864
	ds_read_b128 v[190:193], v174 offset:37888
	ds_read_b128 v[194:197], v174 offset:38912
	ds_read_b128 v[198:201], v174 offset:39936
	global_load_lds_dwordx4 v[202:203], off
	v_lshl_add_u64 v[202:203], s[10:11], 0, v[138:139]
	s_mov_b32 m0, s51
	s_nop 0
	global_load_lds_dwordx4 v[202:203], off
	s_waitcnt lgkmcnt(8)
	s_barrier
	s_waitcnt lgkmcnt(0)
	s_setprio 1
	v_mfma_f32_16x16x32_bf16 v[124:127], v[128:131], v[162:165], v[124:127]
	v_mfma_f32_16x16x32_bf16 v[120:123], v[154:157], v[162:165], v[120:123]
	v_mfma_f32_16x16x32_bf16 v[108:111], v[128:131], v[178:181], v[108:111]
	v_mfma_f32_16x16x32_bf16 v[104:107], v[154:157], v[178:181], v[104:107]
	v_mfma_f32_16x16x32_bf16 v[100:103], v[128:131], v[186:189], v[100:103]
	v_mfma_f32_16x16x32_bf16 v[92:95], v[154:157], v[186:189], v[92:95]
	v_mfma_f32_16x16x32_bf16 v[84:87], v[128:131], v[194:197], v[84:87]
	v_mfma_f32_16x16x32_bf16 v[76:79], v[154:157], v[194:197], v[76:79]
	v_mfma_f32_16x16x32_bf16 v[124:127], v[132:135], v[166:169], v[124:127]
	v_mfma_f32_16x16x32_bf16 v[120:123], v[158:161], v[166:169], v[120:123]
	v_mfma_f32_16x16x32_bf16 v[108:111], v[132:135], v[182:185], v[108:111]
	v_mfma_f32_16x16x32_bf16 v[104:107], v[158:161], v[182:185], v[104:107]
	v_mfma_f32_16x16x32_bf16 v[100:103], v[132:135], v[190:193], v[100:103]
	v_mfma_f32_16x16x32_bf16 v[92:95], v[158:161], v[190:193], v[92:95]
	v_mfma_f32_16x16x32_bf16 v[84:87], v[132:135], v[198:201], v[84:87]
	v_mfma_f32_16x16x32_bf16 v[76:79], v[158:161], v[198:201], v[76:79]
	s_barrier
	s_setprio 0
	s_add_i32 s10, 0, 0x1c000
	s_add_i32 s11, s53, s41
	v_add_u32_e32 v177, s10, v171
	v_lshl_add_u64 v[220:221], v[220:221], 0, s[22:23]
	s_mov_b32 m0, s11
	ds_read_b128 v[202:205], v177
	ds_read_b128 v[206:209], v177 offset:1024
	ds_read_b128 v[212:215], v177 offset:2048
	ds_read_b128 v[216:219], v177 offset:3072
	global_load_lds_dwordx4 v[220:221], off
	v_lshl_add_u64 v[220:221], v[222:223], 0, s[22:23]
	s_add_i32 m0, s11, 0x2000
	s_nop 0
	global_load_lds_dwordx4 v[220:221], off
	s_barrier
	s_waitcnt lgkmcnt(0)
	s_setprio 1
	v_mfma_f32_16x16x32_bf16 v[116:119], v[202:205], v[162:165], v[116:119]
	v_mfma_f32_16x16x32_bf16 v[112:115], v[212:215], v[162:165], v[112:115]
	v_mfma_f32_16x16x32_bf16 v[96:99], v[202:205], v[178:181], v[96:99]
	v_mfma_f32_16x16x32_bf16 v[88:91], v[212:215], v[178:181], v[88:91]
	v_mfma_f32_16x16x32_bf16 v[80:83], v[202:205], v[186:189], v[80:83]
	v_mfma_f32_16x16x32_bf16 v[72:75], v[212:215], v[186:189], v[72:75]
	v_mfma_f32_16x16x32_bf16 v[68:71], v[202:205], v[194:197], v[68:71]
	v_mfma_f32_16x16x32_bf16 v[64:67], v[212:215], v[194:197], v[64:67]
	v_mfma_f32_16x16x32_bf16 v[116:119], v[206:209], v[166:169], v[116:119]
	v_mfma_f32_16x16x32_bf16 v[112:115], v[216:219], v[166:169], v[112:115]
	v_mfma_f32_16x16x32_bf16 v[96:99], v[206:209], v[182:185], v[96:99]
	v_mfma_f32_16x16x32_bf16 v[88:91], v[216:219], v[182:185], v[88:91]
	v_mfma_f32_16x16x32_bf16 v[80:83], v[206:209], v[190:193], v[80:83]
	v_mfma_f32_16x16x32_bf16 v[72:75], v[216:219], v[190:193], v[72:75]
	v_mfma_f32_16x16x32_bf16 v[68:71], v[206:209], v[198:201], v[68:71]
	v_mfma_f32_16x16x32_bf16 v[64:67], v[216:219], v[198:201], v[64:67]
	s_barrier
	s_setprio 0
	s_mov_b32 m0, s56
	v_lshl_add_u64 v[220:221], v[224:225], 0, s[22:23]
	ds_read_b128 v[162:165], v174 offset:49152
	ds_read_b128 v[166:169], v174 offset:50176
	ds_read_b128 v[178:181], v174 offset:51200
	ds_read_b128 v[182:185], v174 offset:52224
	ds_read_b128 v[186:189], v174 offset:53248
	ds_read_b128 v[190:193], v174 offset:54272
	ds_read_b128 v[194:197], v174 offset:55296
	ds_read_b128 v[198:201], v174 offset:56320
	global_load_lds_dwordx4 v[220:221], off
	v_lshl_add_u64 v[220:221], v[226:227], 0, s[22:23]
	s_mov_b32 m0, s57
	s_nop 0
	global_load_lds_dwordx4 v[220:221], off
	s_waitcnt vmcnt(10)
	s_barrier
; #define PG8_STAGE(bufoff, gbase, voff) do { _Pragma("unroll") for (int _i = 0; _i < 2; ++_i) \
;     __builtin_amdgcn_global_load_lds((const unsigned*)((const char*)(gbase) + (voff)[_i]), (LAS unsigned*)(lds + (bufoff) + ldsw + _i * 8192), 16, 0, 0); } while (0)
; #define PG8_LDA(dst, b, h) do { _Pragma("unroll") for (int m = 0; m < 4; ++m) _Pragma("unroll") for (int k = 0; k < 2; ++k) dst[m][k] = *(const LAS bf16x8*)(lds + PG8_SA(b, h) + aoff + m * 2048 + k * 1024); } while (0)
; #define PG8_MMA(ai, bj, At, Bt) do { __builtin_amdgcn_s_setprio(1); _Pragma("unroll") for (int m = 0; m < 4; ++m) _Pragma("unroll") for (int n = 0; n < 2; ++n) _Pragma("unroll") for (int k = 0; k < 2; ++k) \
;     acc[ai][bj][m][n] = __builtin_amdgcn_mfma_f32_16x16x32_bf16(Bt[n][k], At[m][k], acc[ai][bj][m][n], 0, 0, 0); __builtin_amdgcn_s_setprio(0); } while (0)
; #define PG8_WAIT_V(n) asm volatile("s_waitcnt vmcnt(" #n ")" ::: "memory")
; #define PG8_WAIT_L(n) asm volatile("s_waitcnt lgkmcnt(" #n ")" ::: "memory")
; #define PG8_BAR __builtin_amdgcn_s_barrier()
; #define PG8_SCHED __builtin_amdgcn_sched_barrier(0)
;   DI void operator()(const f32x4 (&acc)[2][2][4][2], const Unit& u, int wr, int wc, int fr, int fq) const {
;     const int row0 = u.pm * BM + wr * 64 + fr, col0 = u.pn * BM + wc * 32 + 8 * fq;
;     float rsv[2][4];
; #pragma unroll
;     for (int ai = 0; ai < 2; ++ai)
; #pragma unroll
;       for (int m = 0; m < 4; ++m) rsv[ai][m] = row_rstd(ssq, row0 + ai * HALF + m * 16, fq);
; template <class Epi, class Sched = StaticOrder>
; DI void gemm_phase(LAS unsigned char* lds, const Gemm g, const Sched& S, const Epi& E) {
;     ...
;       PG8_LDA(At, 1, 1); PG8_STAGE(PG8_SA(1, 0), a3, voffA);
;       PG8_BAR; PG8_WAIT_L(0); PG8_MMA(1, 0, At, B0); PG8_BAR; PG8_SCHED;
;       PG8_STAGE(PG8_SB(1, 1), b3 + hstep, voffB);
;       PG8_WAIT_V(6); PG8_BAR; PG8_MMA(1, 1, At, B1); PG8_BAR;
;     }
;     E(acc, cur, wr, wc, fr, fq);
	s_waitcnt lgkmcnt(0)
	s_setprio 1
	v_mfma_f32_16x16x32_bf16 v[60:63], v[128:131], v[162:165], v[60:63]
	v_mfma_f32_16x16x32_bf16 v[56:59], v[154:157], v[162:165], v[56:59]
	v_mfma_f32_16x16x32_bf16 v[52:55], v[128:131], v[178:181], v[52:55]
	v_mfma_f32_16x16x32_bf16 v[44:47], v[154:157], v[178:181], v[44:47]
	v_mfma_f32_16x16x32_bf16 v[36:39], v[128:131], v[186:189], v[36:39]
	v_mfma_f32_16x16x32_bf16 v[28:31], v[154:157], v[186:189], v[28:31]
	v_mfma_f32_16x16x32_bf16 v[20:23], v[128:131], v[194:197], v[20:23]
	v_mfma_f32_16x16x32_bf16 v[12:15], v[154:157], v[194:197], v[12:15]
	v_mfma_f32_16x16x32_bf16 v[60:63], v[132:135], v[166:169], v[60:63]
	v_mfma_f32_16x16x32_bf16 v[56:59], v[158:161], v[166:169], v[56:59]
	v_mfma_f32_16x16x32_bf16 v[52:55], v[132:135], v[182:185], v[52:55]
	v_mfma_f32_16x16x32_bf16 v[44:47], v[158:161], v[182:185], v[44:47]
	v_mfma_f32_16x16x32_bf16 v[36:39], v[132:135], v[190:193], v[36:39]
	v_mfma_f32_16x16x32_bf16 v[28:31], v[158:161], v[190:193], v[28:31]
	v_mfma_f32_16x16x32_bf16 v[20:23], v[132:135], v[198:201], v[20:23]
	v_mfma_f32_16x16x32_bf16 v[12:15], v[158:161], v[198:201], v[12:15]
	s_barrier
	s_setprio 0
	s_add_u32 s8, s8, 0x80080
	s_addc_u32 s9, s9, 0
	s_add_i32 s10, s10, s41
	v_lshl_add_u64 v[128:129], s[8:9], 0, v[140:141]
	s_mov_b32 m0, s10
	s_nop 0
	global_load_lds_dwordx4 v[128:129], off
	v_lshl_add_u64 v[128:129], s[8:9], 0, v[136:137]
	s_add_i32 m0, s10, 0x2000
	s_nop 0
	global_load_lds_dwordx4 v[128:129], off
	ds_read_b128 v[128:131], v173
	ds_read_b128 v[132:135], v173 offset:1024
	ds_read_b128 v[154:157], v173 offset:2048
	ds_read_b128 v[158:161], v173 offset:3072
	s_waitcnt vmcnt(6)
	s_barrier
	s_setprio 1
	v_mfma_f32_16x16x32_bf16 v[48:51], v[202:205], v[162:165], v[48:51]
	v_mfma_f32_16x16x32_bf16 v[40:43], v[212:215], v[162:165], v[40:43]
	v_mfma_f32_16x16x32_bf16 v[32:35], v[202:205], v[178:181], v[32:35]
	v_mfma_f32_16x16x32_bf16 v[24:27], v[212:215], v[178:181], v[24:27]
	v_mfma_f32_16x16x32_bf16 v[16:19], v[202:205], v[186:189], v[16:19]
	v_mfma_f32_16x16x32_bf16 v[8:11], v[212:215], v[186:189], v[8:11]
	v_mfma_f32_16x16x32_bf16 v[4:7], v[202:205], v[194:197], v[4:7]
	v_mfma_f32_16x16x32_bf16 v[0:3], v[212:215], v[194:197], v[0:3]
	v_mfma_f32_16x16x32_bf16 v[48:51], v[206:209], v[166:169], v[48:51]
	v_mfma_f32_16x16x32_bf16 v[40:43], v[216:219], v[166:169], v[40:43]
	v_mfma_f32_16x16x32_bf16 v[32:35], v[206:209], v[182:185], v[32:35]
	v_mfma_f32_16x16x32_bf16 v[24:27], v[216:219], v[182:185], v[24:27]
	v_mfma_f32_16x16x32_bf16 v[16:19], v[206:209], v[190:193], v[16:19]
	v_mfma_f32_16x16x32_bf16 v[8:11], v[216:219], v[190:193], v[8:11]
	v_mfma_f32_16x16x32_bf16 v[4:7], v[206:209], v[198:201], v[4:7]
	v_mfma_f32_16x16x32_bf16 v[0:3], v[216:219], v[198:201], v[0:3]
	s_add_i32 s52, s52, 2
	s_add_u32 s6, s6, 0x100
	s_addc_u32 s7, s7, 0
	s_add_u32 s44, s44, 0x100
	s_addc_u32 s45, s45, 0
	s_cmp_gt_u32 s52, 29
	s_barrier
	s_setprio 0
	s_cbranch_scc0 .LBB0_346
	s_waitcnt lgkmcnt(0)
	v_lshl_add_u32 v168, s4, 8, v170
	v_ashrrev_i32_e32 v169, 31, v168
	v_or_b32_e32 v154, 16, v168
	v_lshlrev_b64 v[128:129], 7, v[168:169]
	v_ashrrev_i32_e32 v155, 31, v154
	v_lshl_add_u64 v[128:129], v[144:145], 0, v[128:129]
	v_lshlrev_b64 v[156:157], 7, v[154:155]
	global_load_dwordx4 v[132:135], v[128:129], off
	s_nop 0
	global_load_dwordx4 v[128:131], v[128:129], off offset:16
	v_lshl_add_u64 v[156:157], v[144:145], 0, v[156:157]
	global_load_dwordx4 v[178:181], v[156:157], off
	global_load_dwordx4 v[182:185], v[156:157], off offset:16
	v_or_b32_e32 v160, 32, v168
	v_ashrrev_i32_e32 v161, 31, v160
	v_lshlrev_b64 v[156:157], 7, v[160:161]
	v_lshl_add_u64 v[156:157], v[144:145], 0, v[156:157]
	global_load_dwordx4 v[186:189], v[156:157], off
	global_load_dwordx4 v[190:193], v[156:157], off offset:16
	v_or_b32_e32 v156, 48, v168
	v_ashrrev_i32_e32 v157, 31, v156
	v_lshlrev_b64 v[158:159], 7, v[156:157]
	v_lshl_add_u64 v[158:159], v[144:145], 0, v[158:159]
	global_load_dwordx4 v[194:197], v[158:159], off
	global_load_dwordx4 v[198:201], v[158:159], off offset:16
	v_add_u32_e32 v164, 0x80, v168
	v_ashrrev_i32_e32 v165, 31, v164
	v_lshlrev_b64 v[158:159], 7, v[164:165]
	v_lshl_add_u64 v[158:159], v[144:145], 0, v[158:159]
	global_load_dwordx4 v[202:205], v[158:159], off
	global_load_dwordx4 v[206:209], v[158:159], off offset:16
	v_add_u32_e32 v158, 0x90, v168
	v_ashrrev_i32_e32 v159, 31, v158
	v_lshlrev_b64 v[162:163], 7, v[158:159]
	v_lshl_add_u64 v[162:163], v[144:145], 0, v[162:163]
	global_load_dwordx4 v[212:215], v[162:163], off
	global_load_dwordx4 v[216:219], v[162:163], off offset:16
	v_add_u32_e32 v166, 0xa0, v168
	v_ashrrev_i32_e32 v167, 31, v166
	v_lshlrev_b64 v[162:163], 7, v[166:167]
	v_lshl_add_u64 v[162:163], v[144:145], 0, v[162:163]
	global_load_dwordx4 v[220:223], v[162:163], off
	global_load_dwordx4 v[224:227], v[162:163], off offset:16
	v_add_u32_e32 v162, 0xb0, v168
	v_ashrrev_i32_e32 v163, 31, v162
	v_lshlrev_b64 v[228:229], 7, v[162:163]
	v_lshl_add_u64 v[232:233], v[144:145], 0, v[228:229]
	global_load_dwordx4 v[228:231], v[232:233], off
	s_nop 0
	global_load_dwordx4 v[232:235], v[232:233], off offset:16
	s_waitcnt vmcnt(0)
; DI unsigned pack2(float lo, float hi) { f32x2 v = {lo, hi}; bf16v2 r = __builtin_convertvector(v, bf16v2); return __builtin_bit_cast(unsigned, r); }
;   DI void operator()(const f32x4 (&acc)[2][2][4][2], const Unit& u, int wr, int wc, int fr, int fq) const {
;     const int row0 = u.pm * BM + wr * 64 + fr, col0 = u.pn * BM + wc * 32 + 8 * fq;
;     float rsv[2][4];
; #pragma unroll
;     for (int ai = 0; ai < 2; ++ai)
; #pragma unroll
;       for (int m = 0; m < 4; ++m) rsv[ai][m] = row_rstd(ssq, row0 + ai * HALF + m * 16, fq);
; #pragma unroll
;     for (int ai = 0; ai < 2; ++ai)
; #pragma unroll
;       for (int m = 0; m < 4; ++m) {
;         const int row = row0 + ai * HALF + m * 16;
;         const float rs = rsv[ai][m];
;         bf16_t* rowp = O + (size_t)row * ldc + col0;
; #pragma unroll
;         for (int bj = 0; bj < 2; ++bj) {
;           const f32x4 v0 = acc[ai][bj][m][0] * rs, v1 = acc[ai][bj][m][1] * rs;
;           u32x4 w; w.x = pack2(v0[0], v0[1]); w.y = pack2(v0[2], v0[3]); w.z = pack2(v1[0], v1[1]); w.w = pack2(v1[2], v1[3]);
;           *(u32x4*)(rowp + bj * HALF) = w;
	v_mov_b32_e32 v236, v132
	v_mov_b32_e32 v237, v128
	v_mov_b32_e32 v128, v133
	v_mov_b32_e32 v132, v134
	v_mov_b32_e32 v133, v130
	v_mov_b32_e32 v130, v135
	v_pk_add_f32 v[130:131], v[132:133], v[130:131]
	v_mov_b32_e32 v132, v178
	v_mov_b32_e32 v133, v182
	v_mov_b32_e32 v182, v179
	v_mov_b32_e32 v134, v180
	v_mov_b32_e32 v135, v184
	v_mov_b32_e32 v184, v181
	v_pk_add_f32 v[128:129], v[236:237], v[128:129]
	v_pk_add_f32 v[132:133], v[132:133], v[182:183]
	v_pk_add_f32 v[134:135], v[134:135], v[184:185]
	v_pk_add_f32 v[128:129], v[128:129], v[130:131]
	v_pk_add_f32 v[130:131], v[132:133], v[134:135]
	v_mov_b32_e32 v133, v128
	v_mov_b32_e32 v132, v130
	v_and_b32_e32 v130, 64, v176
	v_add_u32_e32 v155, 64, v130
	v_xor_b32_e32 v130, 16, v176
	v_cmp_lt_i32_e32 vcc, v130, v155
	v_mov_b32_e32 v128, v131
	v_pk_add_f32 v[128:129], v[132:133], v[128:129]
	v_cndmask_b32_e32 v130, v176, v130, vcc
	v_lshlrev_b32_e32 v157, 2, v130
	ds_bpermute_b32 v131, v157, v129
	ds_bpermute_b32 v130, v157, v128
	v_mov_b32_e32 v178, v186
	v_mov_b32_e32 v179, v190
	v_mov_b32_e32 v190, v187
	v_mov_b32_e32 v186, v194
	s_waitcnt lgkmcnt(0)
	v_pk_add_f32 v[128:129], v[128:129], v[130:131]
	v_xor_b32_e32 v130, 32, v176
	v_cmp_lt_i32_e32 vcc, v130, v155
	v_mov_b32_e32 v187, v198
	v_mov_b32_e32 v198, v195
	v_cndmask_b32_e32 v130, v176, v130, vcc
	v_lshlrev_b32_e32 v155, 2, v130
	ds_bpermute_b32 v131, v155, v129
	ds_bpermute_b32 v130, v155, v128
	v_pk_add_f32 v[182:183], v[186:187], v[198:199]
	v_mov_b32_e32 v180, v188
	v_mov_b32_e32 v181, v192
	v_mov_b32_e32 v192, v189
	s_waitcnt lgkmcnt(0)
	v_pk_add_f32 v[128:129], v[128:129], v[130:131]
	v_mov_b64_e32 v[130:131], s[26:27]
	v_pk_fma_f32 v[128:129], v[128:129], s[24:25], v[130:131] op_sel_hi:[1,0,0]
	v_mov_b32_e32 v188, v196
	v_mul_f32_e32 v159, 0x4b800000, v129
	v_cmp_gt_f32_e32 vcc, s73, v129
	v_mov_b32_e32 v189, v200
	v_mov_b32_e32 v200, v197
	v_cndmask_b32_e32 v129, v129, v159, vcc
	v_rsq_f32_e32 v129, v129
	v_pk_add_f32 v[178:179], v[178:179], v[190:191]
	v_pk_add_f32 v[180:181], v[180:181], v[192:193]
	v_pk_add_f32 v[184:185], v[188:189], v[200:201]
	v_mul_f32_e32 v159, 0x45800000, v129
	v_cndmask_b32_e32 v198, v129, v159, vcc
	v_pk_mul_f32 v[126:127], v[126:127], v[198:199] op_sel_hi:[1,0]
	v_pk_mul_f32 v[124:125], v[124:125], v[198:199] op_sel_hi:[1,0]
	v_pk_mul_f32 v[122:123], v[122:123], v[198:199] op_sel_hi:[1,0]
	v_pk_mul_f32 v[120:121], v[120:121], v[198:199] op_sel_hi:[1,0]
	v_cvt_pk_bf16_f32 v124, v124, v125
	v_cvt_pk_bf16_f32 v125, v126, v127
	v_cvt_pk_bf16_f32 v127, v122, v123
	v_lshl_or_b32 v122, s5, 8, v172
	v_cvt_pk_bf16_f32 v126, v120, v121
	v_ashrrev_i32_e32 v123, 31, v122
	v_mov_b64_e32 v[120:121], s[2:3]
	v_mad_i64_i32 v[168:169], s[4:5], v168, s76, v[120:121]
	v_lshlrev_b64 v[122:123], 1, v[122:123]
	v_lshl_add_u64 v[168:169], v[168:169], 0, v[122:123]
	global_store_dwordx4 v[168:169], v[124:127], off
	v_mov_b32_e32 v194, v202
	v_mov_b32_e32 v195, v206
	v_pk_add_f32 v[124:125], v[178:179], v[180:181]
	v_pk_add_f32 v[126:127], v[182:183], v[184:185]
	v_mov_b32_e32 v179, v124
	v_mov_b32_e32 v178, v126
	v_mov_b32_e32 v124, v127
	v_pk_add_f32 v[124:125], v[178:179], v[124:125]
	ds_bpermute_b32 v127, v157, v125
	ds_bpermute_b32 v126, v157, v124
	v_mov_b32_e32 v206, v203
	v_mov_b32_e32 v196, v204
	v_mov_b32_e32 v197, v208
	v_mov_b32_e32 v208, v205
	v_mov_b32_e32 v202, v212
	v_mov_b32_e32 v203, v216
	v_mov_b32_e32 v216, v213
	v_mov_b32_e32 v204, v214
	v_mov_b32_e32 v205, v218
	v_mov_b32_e32 v218, v215
	v_pk_add_f32 v[186:187], v[194:195], v[206:207]
	v_pk_add_f32 v[188:189], v[196:197], v[208:209]
	v_pk_add_f32 v[190:191], v[202:203], v[216:217]
	v_pk_add_f32 v[192:193], v[204:205], v[218:219]
	v_pk_mul_f32 v[178:179], v[114:115], v[198:199] op_sel_hi:[1,0]
	s_waitcnt lgkmcnt(0)
	v_pk_add_f32 v[114:115], v[124:125], v[126:127]
	v_pk_add_f32 v[126:127], v[186:187], v[188:189]
	v_pk_add_f32 v[180:181], v[190:191], v[192:193]
	v_mov_b32_e32 v183, v126
	v_mov_b32_e32 v182, v180
	v_mov_b32_e32 v126, v181
	v_pk_add_f32 v[126:127], v[182:183], v[126:127]
	ds_bpermute_b32 v125, v155, v115
	ds_bpermute_b32 v124, v155, v114
	ds_bpermute_b32 v181, v157, v127
	ds_bpermute_b32 v180, v157, v126
	v_mul_f32_e32 v129, 0x4b800000, v128
	v_cmp_gt_f32_e32 vcc, s73, v128
	s_waitcnt lgkmcnt(2)
	v_pk_add_f32 v[114:115], v[114:115], v[124:125]
	v_mov_b32_e32 v194, v220
	s_waitcnt lgkmcnt(0)
	v_pk_add_f32 v[124:125], v[126:127], v[180:181]
	ds_bpermute_b32 v127, v155, v125
	ds_bpermute_b32 v126, v155, v124
	v_pk_fma_f32 v[114:115], v[114:115], s[24:25], v[130:131] op_sel_hi:[1,0,0]
	v_cndmask_b32_e32 v159, v128, v129, vcc
	v_mul_f32_e32 v128, 0x4b800000, v115
	v_cmp_gt_f32_e64 s[4:5], s73, v115
	v_cmp_gt_f32_e64 s[6:7], s73, v114
	v_mov_b32_e32 v195, v224
	v_cndmask_b32_e64 v161, v115, v128, s[4:5]
	v_mul_f32_e32 v115, 0x4b800000, v114
	v_mov_b32_e32 v224, v221
	v_mov_b32_e32 v196, v222
	v_mov_b32_e32 v197, v226
	v_mov_b32_e32 v226, v223
	v_cndmask_b32_e64 v163, v114, v115, s[6:7]
	s_waitcnt lgkmcnt(0)
	v_pk_add_f32 v[114:115], v[124:125], v[126:127]
	v_pk_add_f32 v[132:133], v[194:195], v[224:225]
	v_pk_add_f32 v[134:135], v[196:197], v[226:227]
	v_mov_b32_e32 v194, v228
	v_mov_b32_e32 v195, v232
	v_mov_b32_e32 v232, v229
	v_mov_b32_e32 v196, v230
	v_mov_b32_e32 v197, v234
	v_mov_b32_e32 v234, v231
	v_pk_fma_f32 v[114:115], v[114:115], s[24:25], v[130:131] op_sel_hi:[1,0,0]
	v_pk_add_f32 v[194:195], v[194:195], v[232:233]
	v_pk_add_f32 v[196:197], v[196:197], v[234:235]
	v_mul_f32_e32 v124, 0x4b800000, v115
	v_cmp_gt_f32_e64 s[8:9], s73, v115
	v_pk_add_f32 v[126:127], v[194:195], v[196:197]
	v_cmp_gt_f32_e64 s[10:11], s73, v114
	v_cndmask_b32_e64 v165, v115, v124, s[8:9]
	v_pk_add_f32 v[124:125], v[132:133], v[134:135]
	v_mov_b32_e32 v128, v126
	v_mov_b32_e32 v129, v124
	v_mov_b32_e32 v124, v127
	v_pk_add_f32 v[124:125], v[128:129], v[124:125]
	ds_bpermute_b32 v127, v157, v125
	ds_bpermute_b32 v126, v157, v124
	v_rsq_f32_e32 v128, v159
	v_mul_f32_e32 v115, 0x4b800000, v114
	v_cndmask_b32_e64 v129, v114, v115, s[10:11]
	v_pk_mul_f32 v[116:117], v[116:117], v[198:199] op_sel_hi:[1,0]
	s_waitcnt lgkmcnt(0)
; DI unsigned pack2(float lo, float hi) { f32x2 v = {lo, hi}; bf16v2 r = __builtin_convertvector(v, bf16v2); return __builtin_bit_cast(unsigned, r); }
;   DI void operator()(const f32x4 (&acc)[2][2][4][2], const Unit& u, int wr, int wc, int fr, int fq) const {
;     ...
;     for (int ai = 0; ai < 2; ++ai)
; #pragma unroll
;       for (int m = 0; m < 4; ++m) {
;         const int row = row0 + ai * HALF + m * 16;
;         const float rs = rsv[ai][m];
;         bf16_t* rowp = O + (size_t)row * ldc + col0;
; #pragma unroll
;         for (int bj = 0; bj < 2; ++bj) {
;           const f32x4 v0 = acc[ai][bj][m][0] * rs, v1 = acc[ai][bj][m][1] * rs;
;           u32x4 w; w.x = pack2(v0[0], v0[1]); w.y = pack2(v0[2], v0[3]); w.z = pack2(v1[0], v1[1]); w.w = pack2(v1[2], v1[3]);
;           *(u32x4*)(rowp + bj * HALF) = w;
;         }
	v_pk_add_f32 v[114:115], v[124:125], v[126:127]
	ds_bpermute_b32 v125, v155, v115
	ds_bpermute_b32 v124, v155, v114
	v_mul_f32_e32 v126, 0x45800000, v128
	v_rsq_f32_e32 v127, v161
	v_cndmask_b32_e32 v126, v128, v126, vcc
	v_rsq_f32_e32 v128, v163
	s_waitcnt lgkmcnt(0)
	v_pk_add_f32 v[114:115], v[114:115], v[124:125]
	v_mul_f32_e32 v124, 0x45800000, v127
	v_cndmask_b32_e64 v124, v127, v124, s[4:5]
	v_mul_f32_e32 v127, 0x45800000, v128
	v_pk_fma_f32 v[114:115], v[114:115], s[24:25], v[130:131] op_sel_hi:[1,0,0]
	v_rsq_f32_e32 v125, v165
	v_cndmask_b32_e64 v128, v128, v127, s[6:7]
	v_rsq_f32_e32 v127, v129
	v_mul_f32_e32 v129, 0x4b800000, v115
	v_cmp_gt_f32_e32 vcc, s73, v115
	v_cmp_gt_f32_e64 s[4:5], s73, v114
	v_pk_mul_f32 v[118:119], v[118:119], v[198:199] op_sel_hi:[1,0]
	v_cndmask_b32_e32 v129, v115, v129, vcc
	v_mul_f32_e32 v115, 0x4b800000, v114
	v_cndmask_b32_e64 v131, v114, v115, s[4:5]
	v_cvt_pk_bf16_f32 v114, v116, v117
	v_rsq_f32_e32 v117, v129
	v_cvt_pk_bf16_f32 v115, v118, v119
	v_rsq_f32_e32 v119, v131
	v_mul_f32_e32 v116, 0x45800000, v125
	v_pk_mul_f32 v[112:113], v[112:113], v[198:199] op_sel_hi:[1,0]
	v_cndmask_b32_e64 v118, v125, v116, s[8:9]
	v_mul_f32_e32 v116, 0x45800000, v127
	v_cndmask_b32_e64 v130, v127, v116, s[10:11]
	v_cvt_pk_bf16_f32 v116, v112, v113
	v_mul_f32_e32 v112, 0x45800000, v117
	v_cndmask_b32_e32 v132, v117, v112, vcc
	v_mul_f32_e32 v112, 0x45800000, v119
	v_cvt_pk_bf16_f32 v117, v178, v179
	v_cndmask_b32_e64 v112, v119, v112, s[4:5]
	global_store_dwordx4 v[168:169], v[114:117], off offset:256
	v_pk_mul_f32 v[110:111], v[110:111], v[126:127] op_sel_hi:[1,0]
	v_pk_mul_f32 v[108:109], v[108:109], v[126:127] op_sel_hi:[1,0]
	v_mad_i64_i32 v[114:115], s[4:5], v154, s76, v[120:121]
	v_pk_mul_f32 v[116:117], v[106:107], v[126:127] op_sel_hi:[1,0]
	v_pk_mul_f32 v[106:107], v[104:105], v[126:127] op_sel_hi:[1,0]
	v_lshl_add_u64 v[114:115], v[114:115], 0, v[122:123]
	v_cvt_pk_bf16_f32 v104, v108, v109
	v_cvt_pk_bf16_f32 v105, v110, v111
	v_cvt_pk_bf16_f32 v106, v106, v107
	v_cvt_pk_bf16_f32 v107, v116, v117
	global_store_dwordx4 v[114:115], v[104:107], off
	v_pk_mul_f32 v[98:99], v[98:99], v[126:127] op_sel_hi:[1,0]
	v_pk_mul_f32 v[96:97], v[96:97], v[126:127] op_sel_hi:[1,0]
	v_pk_mul_f32 v[104:105], v[90:91], v[126:127] op_sel_hi:[1,0]
	v_pk_mul_f32 v[90:91], v[88:89], v[126:127] op_sel_hi:[1,0]
	v_cvt_pk_bf16_f32 v88, v96, v97
	v_cvt_pk_bf16_f32 v89, v98, v99
	v_cvt_pk_bf16_f32 v90, v90, v91
	v_cvt_pk_bf16_f32 v91, v104, v105
	global_store_dwordx4 v[114:115], v[88:91], off offset:256
	v_pk_mul_f32 v[94:95], v[94:95], v[124:125] op_sel_hi:[1,0]
	v_pk_mul_f32 v[92:93], v[92:93], v[124:125] op_sel_hi:[1,0]
	v_mad_i64_i32 v[88:89], s[4:5], v160, s76, v[120:121]
	v_lshl_add_u64 v[96:97], v[88:89], 0, v[122:123]
	v_pk_mul_f32 v[90:91], v[102:103], v[124:125] op_sel_hi:[1,0]
	v_pk_mul_f32 v[88:89], v[100:101], v[124:125] op_sel_hi:[1,0]
	v_pk_mul_f32 v[82:83], v[82:83], v[124:125] op_sel_hi:[1,0]
	v_cvt_pk_bf16_f32 v88, v88, v89
	v_cvt_pk_bf16_f32 v89, v90, v91
	v_cvt_pk_bf16_f32 v90, v92, v93
	v_cvt_pk_bf16_f32 v91, v94, v95
	global_store_dwordx4 v[96:97], v[88:91], off
	v_pk_mul_f32 v[80:81], v[80:81], v[124:125] op_sel_hi:[1,0]
	v_pk_mul_f32 v[78:79], v[78:79], v[128:129] op_sel_hi:[1,0]
	v_pk_mul_f32 v[88:89], v[74:75], v[124:125] op_sel_hi:[1,0]
	v_pk_mul_f32 v[74:75], v[72:73], v[124:125] op_sel_hi:[1,0]
	v_cvt_pk_bf16_f32 v72, v80, v81
	v_cvt_pk_bf16_f32 v73, v82, v83
	v_cvt_pk_bf16_f32 v74, v74, v75
	v_cvt_pk_bf16_f32 v75, v88, v89
	global_store_dwordx4 v[96:97], v[72:75], off offset:256
	v_pk_mul_f32 v[76:77], v[76:77], v[128:129] op_sel_hi:[1,0]
	v_pk_mul_f32 v[70:71], v[70:71], v[128:129] op_sel_hi:[1,0]
	v_mad_i64_i32 v[72:73], s[4:5], v156, s76, v[120:121]
	v_lshl_add_u64 v[80:81], v[72:73], 0, v[122:123]
	v_pk_mul_f32 v[74:75], v[86:87], v[128:129] op_sel_hi:[1,0]
	v_pk_mul_f32 v[72:73], v[84:85], v[128:129] op_sel_hi:[1,0]
	v_pk_mul_f32 v[68:69], v[68:69], v[128:129] op_sel_hi:[1,0]
	v_cvt_pk_bf16_f32 v72, v72, v73
	v_cvt_pk_bf16_f32 v73, v74, v75
	v_cvt_pk_bf16_f32 v74, v76, v77
	v_cvt_pk_bf16_f32 v75, v78, v79
	global_store_dwordx4 v[80:81], v[72:75], off
	v_pk_mul_f32 v[62:63], v[62:63], v[118:119] op_sel_hi:[1,0]
; DI unsigned pack2(float lo, float hi) { f32x2 v = {lo, hi}; bf16v2 r = __builtin_convertvector(v, bf16v2); return __builtin_bit_cast(unsigned, r); }
; #define PG8_WAIT_V(n) asm volatile("s_waitcnt vmcnt(" #n ")" ::: "memory")
; #define PG8_BAR __builtin_amdgcn_s_barrier()
;   DI void operator()(const f32x4 (&acc)[2][2][4][2], const Unit& u, int wr, int wc, int fr, int fq) const {
;     ...
;     for (int ai = 0; ai < 2; ++ai)
; #pragma unroll
;       for (int m = 0; m < 4; ++m) {
;         const int row = row0 + ai * HALF + m * 16;
;         const float rs = rsv[ai][m];
;         bf16_t* rowp = O + (size_t)row * ldc + col0;
; #pragma unroll
;         for (int bj = 0; bj < 2; ++bj) {
;           const f32x4 v0 = acc[ai][bj][m][0] * rs, v1 = acc[ai][bj][m][1] * rs;
;           u32x4 w; w.x = pack2(v0[0], v0[1]); w.y = pack2(v0[2], v0[3]); w.z = pack2(v1[0], v1[1]); w.w = pack2(v1[2], v1[3]);
;           *(u32x4*)(rowp + bj * HALF) = w;
;         }
; template <class Epi, class Sched = StaticOrder>
; DI void gemm_phase(LAS unsigned char* lds, const Gemm g, const Sched& S, const Epi& E) {
;     ...
;     E(acc, cur, wr, wc, fr, fq);
;     if (!has_next) break;
; #pragma unroll
;     for (int a = 0; a < 2; ++a)
; #pragma unroll
;       for (int b = 0; b < 2; ++b)
; #pragma unroll
;         for (int m = 0; m < 4; ++m)
; #pragma unroll
;           for (int n = 0; n < 2; ++n) acc[a][b][m][n] = (f32x4){0.f, 0.f, 0.f, 0.f};
;     cur = nxt; cA = nA; cB = nB; ++ui;
;   }
;   PG8_WAIT_V(0);
;   if (wr == 0) PG8_BAR;
	v_pk_mul_f32 v[60:61], v[60:61], v[118:119] op_sel_hi:[1,0]
	v_pk_mul_f32 v[72:73], v[66:67], v[128:129] op_sel_hi:[1,0]
	v_pk_mul_f32 v[66:67], v[64:65], v[128:129] op_sel_hi:[1,0]
	v_cvt_pk_bf16_f32 v64, v68, v69
	v_cvt_pk_bf16_f32 v65, v70, v71
	v_cvt_pk_bf16_f32 v66, v66, v67
	v_cvt_pk_bf16_f32 v67, v72, v73
	global_store_dwordx4 v[80:81], v[64:67], off offset:256
	v_pk_mul_f32 v[50:51], v[50:51], v[118:119] op_sel_hi:[1,0]
	v_pk_mul_f32 v[48:49], v[48:49], v[118:119] op_sel_hi:[1,0]
	v_mad_i64_i32 v[64:65], s[4:5], v164, s76, v[120:121]
	v_pk_mul_f32 v[66:67], v[58:59], v[118:119] op_sel_hi:[1,0]
	v_pk_mul_f32 v[58:59], v[56:57], v[118:119] op_sel_hi:[1,0]
	v_lshl_add_u64 v[64:65], v[64:65], 0, v[122:123]
	v_cvt_pk_bf16_f32 v56, v60, v61
	v_cvt_pk_bf16_f32 v57, v62, v63
	v_cvt_pk_bf16_f32 v58, v58, v59
	v_cvt_pk_bf16_f32 v59, v66, v67
	global_store_dwordx4 v[64:65], v[56:59], off
	v_pk_mul_f32 v[46:47], v[46:47], v[130:131] op_sel_hi:[1,0]
	v_pk_mul_f32 v[44:45], v[44:45], v[130:131] op_sel_hi:[1,0]
	v_pk_mul_f32 v[56:57], v[42:43], v[118:119] op_sel_hi:[1,0]
	v_pk_mul_f32 v[42:43], v[40:41], v[118:119] op_sel_hi:[1,0]
	v_cvt_pk_bf16_f32 v40, v48, v49
	v_cvt_pk_bf16_f32 v41, v50, v51
	v_cvt_pk_bf16_f32 v42, v42, v43
	v_cvt_pk_bf16_f32 v43, v56, v57
	global_store_dwordx4 v[64:65], v[40:43], off offset:256
	v_pk_mul_f32 v[34:35], v[34:35], v[130:131] op_sel_hi:[1,0]
	v_pk_mul_f32 v[32:33], v[32:33], v[130:131] op_sel_hi:[1,0]
	v_mad_i64_i32 v[40:41], s[4:5], v158, s76, v[120:121]
	v_lshl_add_u64 v[48:49], v[40:41], 0, v[122:123]
	v_pk_mul_f32 v[42:43], v[54:55], v[130:131] op_sel_hi:[1,0]
	v_pk_mul_f32 v[40:41], v[52:53], v[130:131] op_sel_hi:[1,0]
	v_pk_mul_f32 v[30:31], v[30:31], v[132:133] op_sel_hi:[1,0]
	v_cvt_pk_bf16_f32 v40, v40, v41
	v_cvt_pk_bf16_f32 v41, v42, v43
	v_cvt_pk_bf16_f32 v42, v44, v45
	v_cvt_pk_bf16_f32 v43, v46, v47
	global_store_dwordx4 v[48:49], v[40:43], off
	v_pk_mul_f32 v[28:29], v[28:29], v[132:133] op_sel_hi:[1,0]
	v_pk_mul_f32 v[18:19], v[18:19], v[132:133] op_sel_hi:[1,0]
	v_pk_mul_f32 v[40:41], v[26:27], v[130:131] op_sel_hi:[1,0]
	v_pk_mul_f32 v[26:27], v[24:25], v[130:131] op_sel_hi:[1,0]
	v_cvt_pk_bf16_f32 v24, v32, v33
	v_cvt_pk_bf16_f32 v25, v34, v35
	v_cvt_pk_bf16_f32 v26, v26, v27
	v_cvt_pk_bf16_f32 v27, v40, v41
	global_store_dwordx4 v[48:49], v[24:27], off offset:256
	v_pk_mul_f32 v[16:17], v[16:17], v[132:133] op_sel_hi:[1,0]
	v_pk_mul_f32 v[14:15], v[14:15], v[112:113] op_sel_hi:[1,0]
	v_mad_i64_i32 v[24:25], s[4:5], v166, s76, v[120:121]
	v_lshl_add_u64 v[32:33], v[24:25], 0, v[122:123]
	v_pk_mul_f32 v[26:27], v[38:39], v[132:133] op_sel_hi:[1,0]
	v_pk_mul_f32 v[24:25], v[36:37], v[132:133] op_sel_hi:[1,0]
	v_pk_mul_f32 v[12:13], v[12:13], v[112:113] op_sel_hi:[1,0]
	v_cvt_pk_bf16_f32 v24, v24, v25
	v_cvt_pk_bf16_f32 v25, v26, v27
	v_cvt_pk_bf16_f32 v26, v28, v29
	v_cvt_pk_bf16_f32 v27, v30, v31
	global_store_dwordx4 v[32:33], v[24:27], off
	v_pk_mul_f32 v[6:7], v[6:7], v[112:113] op_sel_hi:[1,0]
	v_pk_mul_f32 v[4:5], v[4:5], v[112:113] op_sel_hi:[1,0]
	v_pk_mul_f32 v[24:25], v[10:11], v[132:133] op_sel_hi:[1,0]
	v_pk_mul_f32 v[10:11], v[8:9], v[132:133] op_sel_hi:[1,0]
	v_cvt_pk_bf16_f32 v8, v16, v17
	v_cvt_pk_bf16_f32 v9, v18, v19
	v_cvt_pk_bf16_f32 v10, v10, v11
	v_cvt_pk_bf16_f32 v11, v24, v25
	global_store_dwordx4 v[32:33], v[8:11], off offset:256
	s_and_b64 vcc, exec, s[0:1]
	s_mov_b64 s[8:9], s[36:37]
	v_mad_i64_i32 v[8:9], s[4:5], v162, s76, v[120:121]
	v_lshl_add_u64 v[16:17], v[8:9], 0, v[122:123]
	v_pk_mul_f32 v[10:11], v[22:23], v[112:113] op_sel_hi:[1,0]
	v_pk_mul_f32 v[8:9], v[20:21], v[112:113] op_sel_hi:[1,0]
	s_mov_b32 s5, s28
	v_cvt_pk_bf16_f32 v8, v8, v9
	v_cvt_pk_bf16_f32 v9, v10, v11
	v_cvt_pk_bf16_f32 v10, v12, v13
	v_cvt_pk_bf16_f32 v11, v14, v15
	global_store_dwordx4 v[16:17], v[8:11], off
	s_mov_b32 s4, s30
	s_mov_b64 s[6:7], s[34:35]
	v_pk_mul_f32 v[8:9], v[2:3], v[112:113] op_sel_hi:[1,0]
	v_pk_mul_f32 v[2:3], v[0:1], v[112:113] op_sel_hi:[1,0]
	v_cvt_pk_bf16_f32 v0, v4, v5
	v_cvt_pk_bf16_f32 v1, v6, v7
	v_cvt_pk_bf16_f32 v2, v2, v3
	v_cvt_pk_bf16_f32 v3, v8, v9
	global_store_dwordx4 v[16:17], v[0:3], off offset:256
	s_cbranch_vccz .LBB0_343
	s_waitcnt vmcnt(0)
	s_cmpk_gt_u32 s27, 0xff
	s_cbranch_scc1 .LBB0_350
	s_barrier

; #define PG8_STAGE(bufoff, gbase, voff) do { _Pragma("unroll") for (int _i = 0; _i < 2; ++_i) \
;     __builtin_amdgcn_global_load_lds((const unsigned*)((const char*)(gbase) + (voff)[_i]), (LAS unsigned*)(lds + (bufoff) + ldsw + _i * 8192), 16, 0, 0); } while (0)
; #define PG8_LDA(dst, b, h) do { _Pragma("unroll") for (int m = 0; m < 4; ++m) _Pragma("unroll") for (int k = 0; k < 2; ++k) dst[m][k] = *(const LAS bf16x8*)(lds + PG8_SA(b, h) + aoff + m * 2048 + k * 1024); } while (0)
; #define PG8_LDB(dst, b, h) do { _Pragma("unroll") for (int n = 0; n < 2; ++n) _Pragma("unroll") for (int k = 0; k < 2; ++k) dst[n][k] = *(const LAS bf16x8*)(lds + PG8_SB(b, h) + boff + n * 2048 + k * 1024); } while (0)
; #define PG8_MMA(ai, bj, At, Bt) do { __builtin_amdgcn_s_setprio(1); _Pragma("unroll") for (int m = 0; m < 4; ++m) _Pragma("unroll") for (int n = 0; n < 2; ++n) _Pragma("unroll") for (int k = 0; k < 2; ++k) \
;     acc[ai][bj][m][n] = __builtin_amdgcn_mfma_f32_16x16x32_bf16(Bt[n][k], At[m][k], acc[ai][bj][m][n], 0, 0, 0); __builtin_amdgcn_s_setprio(0); } while (0)
; #define PG8_WAIT_V(n) asm volatile("s_waitcnt vmcnt(" #n ")" ::: "memory")
; #define PG8_WAIT_L(n) asm volatile("s_waitcnt lgkmcnt(" #n ")" ::: "memory")
; #define PG8_BAR __builtin_amdgcn_s_barrier()
; #define PG8_SCHED __builtin_amdgcn_sched_barrier(0)
; template <class Epi, class Sched = StaticOrder>
; DI void gemm_phase(LAS unsigned char* lds, const Gemm g, const Sched& S, const Epi& E) {
;     ...
;       PG8_LDB(B0, 0, 0); PG8_SCHED; PG8_LDA(At, 0, 0); PG8_STAGE(PG8_SA(1, 1), a1 + hstep, voffA);
;       PG8_WAIT_L(8); PG8_BAR; PG8_WAIT_L(0); PG8_MMA(0, 0, At, B0); PG8_BAR; PG8_SCHED;
;       PG8_LDB(B1, 0, 1); PG8_STAGE(PG8_SB(0, 0), b2, voffB);
;       PG8_BAR; PG8_WAIT_L(0); PG8_MMA(0, 1, At, B1); PG8_BAR;
;       PG8_LDA(At, 0, 1); PG8_STAGE(PG8_SA(0, 0), a2, voffA);
;       PG8_BAR; PG8_WAIT_L(0); PG8_MMA(1, 0, At, B0); PG8_BAR; PG8_SCHED;
;       PG8_STAGE(PG8_SB(0, 1), b2 + hstep, voffB);
;       PG8_WAIT_V(6); PG8_BAR; PG8_MMA(1, 1, At, B1); PG8_BAR;
.LBB0_728:
	s_add_u32 s24, s22, 0xfff80080
	s_addc_u32 s25, s23, -1
	s_cmp_eq_u32 s53, 28
	s_cselect_b32 s27, s17, s25
	s_cselect_b32 s26, s43, s24
	s_cselect_b32 s25, s15, s52
	s_cselect_b32 s24, s44, s45
	v_lshl_add_u64 v[192:193], s[22:23], 0, v[184:185]
	s_add_i32 m0, s37, 0xc000
	ds_read_b128 v[144:147], v208
	ds_read_b128 v[148:151], v208 offset:1024
	ds_read_b128 v[152:155], v208 offset:2048
	ds_read_b128 v[156:159], v208 offset:3072
	ds_read_b128 v[160:163], v208 offset:4096
	ds_read_b128 v[164:167], v208 offset:5120
	ds_read_b128 v[168:171], v208 offset:6144
	ds_read_b128 v[172:175], v208 offset:7168
	global_load_lds_dwordx4 v[192:193], off
	v_lshl_add_u64 v[192:193], s[22:23], 0, v[186:187]
	s_add_i32 m0, s37, 0xe000
	s_nop 0
	global_load_lds_dwordx4 v[192:193], off
	s_waitcnt lgkmcnt(8)
	s_barrier
	s_waitcnt lgkmcnt(0)
	s_setprio 1
	v_mfma_f32_16x16x32_bf16 v[124:127], v[128:131], v[144:147], v[124:127]
	v_mfma_f32_16x16x32_bf16 v[120:123], v[136:139], v[144:147], v[120:123]
	v_mfma_f32_16x16x32_bf16 v[108:111], v[128:131], v[152:155], v[108:111]
	v_mfma_f32_16x16x32_bf16 v[104:107], v[136:139], v[152:155], v[104:107]
	v_mfma_f32_16x16x32_bf16 v[92:95], v[128:131], v[160:163], v[92:95]
	v_mfma_f32_16x16x32_bf16 v[88:91], v[136:139], v[160:163], v[88:91]
	v_mfma_f32_16x16x32_bf16 v[76:79], v[128:131], v[168:171], v[76:79]
	v_mfma_f32_16x16x32_bf16 v[72:75], v[136:139], v[168:171], v[72:75]
	v_mfma_f32_16x16x32_bf16 v[124:127], v[132:135], v[148:151], v[124:127]
	v_mfma_f32_16x16x32_bf16 v[120:123], v[140:143], v[148:151], v[120:123]
	v_mfma_f32_16x16x32_bf16 v[108:111], v[132:135], v[156:159], v[108:111]
	v_mfma_f32_16x16x32_bf16 v[104:107], v[140:143], v[156:159], v[104:107]
	v_mfma_f32_16x16x32_bf16 v[92:95], v[132:135], v[164:167], v[92:95]
	v_mfma_f32_16x16x32_bf16 v[88:91], v[140:143], v[164:167], v[88:91]
	v_mfma_f32_16x16x32_bf16 v[76:79], v[132:135], v[172:175], v[76:79]
	v_mfma_f32_16x16x32_bf16 v[72:75], v[140:143], v[172:175], v[72:75]
	s_barrier
	s_setprio 0
	s_add_i32 s54, s50, s35
	v_lshl_add_u64 v[216:217], s[24:25], 0, v[180:181]
	s_mov_b32 m0, s54
	ds_read_b128 v[192:195], v209
	ds_read_b128 v[196:199], v209 offset:1024
	ds_read_b128 v[200:203], v209 offset:2048
	ds_read_b128 v[212:215], v209 offset:3072
	global_load_lds_dwordx4 v[216:217], off
	v_lshl_add_u64 v[218:219], s[24:25], 0, v[176:177]
	s_add_i32 m0, s54, 0x2000
	s_nop 0
	global_load_lds_dwordx4 v[218:219], off
	s_barrier
	s_waitcnt lgkmcnt(0)
	s_setprio 1
	v_mfma_f32_16x16x32_bf16 v[116:119], v[192:195], v[144:147], v[116:119]
	v_mfma_f32_16x16x32_bf16 v[112:115], v[200:203], v[144:147], v[112:115]
	v_mfma_f32_16x16x32_bf16 v[100:103], v[192:195], v[152:155], v[100:103]
	v_mfma_f32_16x16x32_bf16 v[96:99], v[200:203], v[152:155], v[96:99]
	v_mfma_f32_16x16x32_bf16 v[84:87], v[192:195], v[160:163], v[84:87]
	v_mfma_f32_16x16x32_bf16 v[80:83], v[200:203], v[160:163], v[80:83]
	v_mfma_f32_16x16x32_bf16 v[68:71], v[192:195], v[168:171], v[68:71]
	v_mfma_f32_16x16x32_bf16 v[64:67], v[200:203], v[168:171], v[64:67]
	v_mfma_f32_16x16x32_bf16 v[116:119], v[196:199], v[148:151], v[116:119]
	v_mfma_f32_16x16x32_bf16 v[112:115], v[212:215], v[148:151], v[112:115]
	v_mfma_f32_16x16x32_bf16 v[100:103], v[196:199], v[156:159], v[100:103]
	v_mfma_f32_16x16x32_bf16 v[96:99], v[212:215], v[156:159], v[96:99]
	v_mfma_f32_16x16x32_bf16 v[84:87], v[196:199], v[164:167], v[84:87]
	v_mfma_f32_16x16x32_bf16 v[80:83], v[212:215], v[164:167], v[80:83]
	v_mfma_f32_16x16x32_bf16 v[68:71], v[196:199], v[172:175], v[68:71]
	v_mfma_f32_16x16x32_bf16 v[64:67], v[212:215], v[172:175], v[64:67]
	s_barrier
	s_setprio 0
	s_mov_b32 m0, s37
	v_lshl_add_u64 v[220:221], s[26:27], 0, v[182:183]
	ds_read_b128 v[144:147], v208 offset:16384
	ds_read_b128 v[148:151], v208 offset:17408
	ds_read_b128 v[152:155], v208 offset:18432
	ds_read_b128 v[156:159], v208 offset:19456
	ds_read_b128 v[160:163], v208 offset:20480
	ds_read_b128 v[164:167], v208 offset:21504
	ds_read_b128 v[168:171], v208 offset:22528
	ds_read_b128 v[172:175], v208 offset:23552
	global_load_lds_dwordx4 v[220:221], off
	v_lshl_add_u64 v[222:223], s[26:27], 0, v[178:179]
	s_mov_b32 m0, s38
	s_nop 0
	global_load_lds_dwordx4 v[222:223], off
	s_waitcnt vmcnt(10)
	s_barrier
	s_waitcnt lgkmcnt(0)
	s_setprio 1
	v_mfma_f32_16x16x32_bf16 v[60:63], v[128:131], v[144:147], v[60:63]
	v_mfma_f32_16x16x32_bf16 v[56:59], v[136:139], v[144:147], v[56:59]
	v_mfma_f32_16x16x32_bf16 v[44:47], v[128:131], v[152:155], v[44:47]
	v_mfma_f32_16x16x32_bf16 v[40:43], v[136:139], v[152:155], v[40:43]
	v_mfma_f32_16x16x32_bf16 v[28:31], v[128:131], v[160:163], v[28:31]
	v_mfma_f32_16x16x32_bf16 v[24:27], v[136:139], v[160:163], v[24:27]
	v_mfma_f32_16x16x32_bf16 v[12:15], v[128:131], v[168:171], v[12:15]
	v_mfma_f32_16x16x32_bf16 v[8:11], v[136:139], v[168:171], v[8:11]
	v_mfma_f32_16x16x32_bf16 v[60:63], v[132:135], v[148:151], v[60:63]
	v_mfma_f32_16x16x32_bf16 v[56:59], v[140:143], v[148:151], v[56:59]
	v_mfma_f32_16x16x32_bf16 v[44:47], v[132:135], v[156:159], v[44:47]
	v_mfma_f32_16x16x32_bf16 v[40:43], v[140:143], v[156:159], v[40:43]
	v_mfma_f32_16x16x32_bf16 v[28:31], v[132:135], v[164:167], v[28:31]
	v_mfma_f32_16x16x32_bf16 v[24:27], v[140:143], v[164:167], v[24:27]
	v_mfma_f32_16x16x32_bf16 v[12:15], v[132:135], v[172:175], v[12:15]
	v_mfma_f32_16x16x32_bf16 v[8:11], v[140:143], v[172:175], v[8:11]
	s_barrier
; #define PG8_STAGE(bufoff, gbase, voff) do { _Pragma("unroll") for (int _i = 0; _i < 2; ++_i) \
;     __builtin_amdgcn_global_load_lds((const unsigned*)((const char*)(gbase) + (voff)[_i]), (LAS unsigned*)(lds + (bufoff) + ldsw + _i * 8192), 16, 0, 0); } while (0)
; #define PG8_LDA(dst, b, h) do { _Pragma("unroll") for (int m = 0; m < 4; ++m) _Pragma("unroll") for (int k = 0; k < 2; ++k) dst[m][k] = *(const LAS bf16x8*)(lds + PG8_SA(b, h) + aoff + m * 2048 + k * 1024); } while (0)
; #define PG8_LDB(dst, b, h) do { _Pragma("unroll") for (int n = 0; n < 2; ++n) _Pragma("unroll") for (int k = 0; k < 2; ++k) dst[n][k] = *(const LAS bf16x8*)(lds + PG8_SB(b, h) + boff + n * 2048 + k * 1024); } while (0)
; #define PG8_MMA(ai, bj, At, Bt) do { __builtin_amdgcn_s_setprio(1); _Pragma("unroll") for (int m = 0; m < 4; ++m) _Pragma("unroll") for (int n = 0; n < 2; ++n) _Pragma("unroll") for (int k = 0; k < 2; ++k) \
;     acc[ai][bj][m][n] = __builtin_amdgcn_mfma_f32_16x16x32_bf16(Bt[n][k], At[m][k], acc[ai][bj][m][n], 0, 0, 0); __builtin_amdgcn_s_setprio(0); } while (0)
; #define PG8_WAIT_V(n) asm volatile("s_waitcnt vmcnt(" #n ")" ::: "memory")
; #define PG8_WAIT_L(n) asm volatile("s_waitcnt lgkmcnt(" #n ")" ::: "memory")
; #define PG8_BAR __builtin_amdgcn_s_barrier()
; #define PG8_SCHED __builtin_amdgcn_sched_barrier(0)
; template <class Epi, class Sched = StaticOrder>
; DI void gemm_phase(LAS unsigned char* lds, const Gemm g, const Sched& S, const Epi& E) {
;     ...
;       PG8_STAGE(PG8_SB(0, 1), b2 + hstep, voffB);
;       PG8_WAIT_V(6); PG8_BAR; PG8_MMA(1, 1, At, B1); PG8_BAR;
;       PG8_LDB(B0, 1, 0); PG8_SCHED; PG8_LDA(At, 1, 0); PG8_STAGE(PG8_SA(0, 1), a2 + hstep, voffA);
;       PG8_WAIT_L(8); PG8_BAR; PG8_WAIT_L(0); PG8_MMA(0, 0, At, B0); PG8_BAR; PG8_SCHED;
;       PG8_LDB(B1, 1, 1); PG8_STAGE(PG8_SB(1, 0), b3, voffB);
;       PG8_BAR; PG8_WAIT_L(0); PG8_MMA(0, 1, At, B1); PG8_BAR;
;       PG8_LDA(At, 1, 1); PG8_STAGE(PG8_SA(1, 0), a3, voffA);
	s_setprio 0
	s_add_u32 s54, s24, 0x80000
	s_addc_u32 s55, s25, 0
	s_add_i32 s57, s51, s35
	v_lshl_add_u64 v[128:129], s[54:55], 0, v[180:181]
	s_mov_b32 m0, s57
	s_nop 0
	global_load_lds_dwordx4 v[128:129], off
	v_lshl_add_u64 v[128:129], s[54:55], 0, v[176:177]
	s_add_i32 m0, s57, 0x2000
	s_nop 0
	global_load_lds_dwordx4 v[128:129], off
	s_add_i32 s54, 0, 0x18000
	v_add_u32_e32 v140, s54, v205
	ds_read_b128 v[128:131], v140
	ds_read_b128 v[132:135], v140 offset:1024
	ds_read_b128 v[136:139], v140 offset:2048
	ds_read_b128 v[140:143], v140 offset:3072
	s_waitcnt vmcnt(6)
	s_barrier
	s_setprio 1
	v_mfma_f32_16x16x32_bf16 v[52:55], v[192:195], v[144:147], v[52:55]
	v_mfma_f32_16x16x32_bf16 v[48:51], v[200:203], v[144:147], v[48:51]
	v_mfma_f32_16x16x32_bf16 v[36:39], v[192:195], v[152:155], v[36:39]
	v_mfma_f32_16x16x32_bf16 v[32:35], v[200:203], v[152:155], v[32:35]
	v_mfma_f32_16x16x32_bf16 v[20:23], v[192:195], v[160:163], v[20:23]
	v_mfma_f32_16x16x32_bf16 v[16:19], v[200:203], v[160:163], v[16:19]
	v_mfma_f32_16x16x32_bf16 v[4:7], v[192:195], v[168:171], v[4:7]
	v_mfma_f32_16x16x32_bf16 v[0:3], v[200:203], v[168:171], v[0:3]
	v_mfma_f32_16x16x32_bf16 v[52:55], v[196:199], v[148:151], v[52:55]
	v_mfma_f32_16x16x32_bf16 v[48:51], v[212:215], v[148:151], v[48:51]
	v_mfma_f32_16x16x32_bf16 v[36:39], v[196:199], v[156:159], v[36:39]
	v_mfma_f32_16x16x32_bf16 v[32:35], v[212:215], v[156:159], v[32:35]
	v_mfma_f32_16x16x32_bf16 v[20:23], v[196:199], v[164:167], v[20:23]
	v_mfma_f32_16x16x32_bf16 v[16:19], v[212:215], v[164:167], v[16:19]
	v_mfma_f32_16x16x32_bf16 v[4:7], v[196:199], v[172:175], v[4:7]
	v_mfma_f32_16x16x32_bf16 v[0:3], v[212:215], v[172:175], v[0:3]
	s_barrier
	s_setprio 0
	s_add_u32 s26, s26, 0x80000
	s_addc_u32 s27, s27, 0
	s_mov_b32 m0, s39
	v_lshl_add_u64 v[192:193], s[26:27], 0, v[182:183]
	ds_read_b128 v[144:147], v208 offset:32768
	ds_read_b128 v[148:151], v208 offset:33792
	ds_read_b128 v[152:155], v208 offset:34816
	ds_read_b128 v[156:159], v208 offset:35840
	ds_read_b128 v[160:163], v208 offset:36864
	ds_read_b128 v[164:167], v208 offset:37888
	ds_read_b128 v[168:171], v208 offset:38912
	ds_read_b128 v[172:175], v208 offset:39936
	global_load_lds_dwordx4 v[192:193], off
	v_lshl_add_u64 v[192:193], s[26:27], 0, v[178:179]
	s_mov_b32 m0, s40
	s_nop 0
	global_load_lds_dwordx4 v[192:193], off
	s_waitcnt lgkmcnt(8)
	s_barrier
	s_waitcnt lgkmcnt(0)
	s_setprio 1
	v_mfma_f32_16x16x32_bf16 v[124:127], v[128:131], v[144:147], v[124:127]
	v_mfma_f32_16x16x32_bf16 v[120:123], v[136:139], v[144:147], v[120:123]
	v_mfma_f32_16x16x32_bf16 v[108:111], v[128:131], v[152:155], v[108:111]
	v_mfma_f32_16x16x32_bf16 v[104:107], v[136:139], v[152:155], v[104:107]
	v_mfma_f32_16x16x32_bf16 v[92:95], v[128:131], v[160:163], v[92:95]
	v_mfma_f32_16x16x32_bf16 v[88:91], v[136:139], v[160:163], v[88:91]
	v_mfma_f32_16x16x32_bf16 v[76:79], v[128:131], v[168:171], v[76:79]
	v_mfma_f32_16x16x32_bf16 v[72:75], v[136:139], v[168:171], v[72:75]
	v_mfma_f32_16x16x32_bf16 v[124:127], v[132:135], v[148:151], v[124:127]
	v_mfma_f32_16x16x32_bf16 v[120:123], v[140:143], v[148:151], v[120:123]
	v_mfma_f32_16x16x32_bf16 v[108:111], v[132:135], v[156:159], v[108:111]
	v_mfma_f32_16x16x32_bf16 v[104:107], v[140:143], v[156:159], v[104:107]
	v_mfma_f32_16x16x32_bf16 v[92:95], v[132:135], v[164:167], v[92:95]
	v_mfma_f32_16x16x32_bf16 v[88:91], v[140:143], v[164:167], v[88:91]
	v_mfma_f32_16x16x32_bf16 v[76:79], v[132:135], v[172:175], v[76:79]
	v_mfma_f32_16x16x32_bf16 v[72:75], v[140:143], v[172:175], v[72:75]
	s_barrier
	s_setprio 0
	s_add_i32 s26, 0, 0x1c000
	s_add_i32 s27, s54, s35
	v_add_u32_e32 v212, s26, v205
	v_lshl_add_u64 v[216:217], v[216:217], 0, s[10:11]
	s_mov_b32 m0, s27
	ds_read_b128 v[192:195], v212
	ds_read_b128 v[196:199], v212 offset:1024
	ds_read_b128 v[200:203], v212 offset:2048
	ds_read_b128 v[212:215], v212 offset:3072
	global_load_lds_dwordx4 v[216:217], off
	v_lshl_add_u64 v[216:217], v[218:219], 0, s[10:11]
	s_add_i32 m0, s27, 0x2000
	s_nop 0
	global_load_lds_dwordx4 v[216:217], off
	s_barrier
	s_waitcnt lgkmcnt(0)
	s_setprio 1
	v_mfma_f32_16x16x32_bf16 v[116:119], v[192:195], v[144:147], v[116:119]
	v_mfma_f32_16x16x32_bf16 v[112:115], v[200:203], v[144:147], v[112:115]
	v_mfma_f32_16x16x32_bf16 v[100:103], v[192:195], v[152:155], v[100:103]
	v_mfma_f32_16x16x32_bf16 v[96:99], v[200:203], v[152:155], v[96:99]
	v_mfma_f32_16x16x32_bf16 v[84:87], v[192:195], v[160:163], v[84:87]
	v_mfma_f32_16x16x32_bf16 v[80:83], v[200:203], v[160:163], v[80:83]
	v_mfma_f32_16x16x32_bf16 v[68:71], v[192:195], v[168:171], v[68:71]
	v_mfma_f32_16x16x32_bf16 v[64:67], v[200:203], v[168:171], v[64:67]
	v_mfma_f32_16x16x32_bf16 v[116:119], v[196:199], v[148:151], v[116:119]
	v_mfma_f32_16x16x32_bf16 v[112:115], v[212:215], v[148:151], v[112:115]
	v_mfma_f32_16x16x32_bf16 v[100:103], v[196:199], v[156:159], v[100:103]
	v_mfma_f32_16x16x32_bf16 v[96:99], v[212:215], v[156:159], v[96:99]
	v_mfma_f32_16x16x32_bf16 v[84:87], v[196:199], v[164:167], v[84:87]
	v_mfma_f32_16x16x32_bf16 v[80:83], v[212:215], v[164:167], v[80:83]
	v_mfma_f32_16x16x32_bf16 v[68:71], v[196:199], v[172:175], v[68:71]
	v_mfma_f32_16x16x32_bf16 v[64:67], v[212:215], v[172:175], v[64:67]
	s_barrier
	s_setprio 0
	s_mov_b32 m0, s46
	v_lshl_add_u64 v[216:217], v[220:221], 0, s[10:11]
	ds_read_b128 v[144:147], v208 offset:49152
	ds_read_b128 v[148:151], v208 offset:50176
	ds_read_b128 v[152:155], v208 offset:51200
	ds_read_b128 v[156:159], v208 offset:52224
	ds_read_b128 v[160:163], v208 offset:53248
	ds_read_b128 v[164:167], v208 offset:54272
	ds_read_b128 v[168:171], v208 offset:55296
	ds_read_b128 v[172:175], v208 offset:56320
	global_load_lds_dwordx4 v[216:217], off
	v_lshl_add_u64 v[216:217], v[222:223], 0, s[10:11]
	s_mov_b32 m0, s47
	s_nop 0
	global_load_lds_dwordx4 v[216:217], off
	s_waitcnt vmcnt(10)
	s_barrier
; #define PG8_STAGE(bufoff, gbase, voff) do { _Pragma("unroll") for (int _i = 0; _i < 2; ++_i) \
;     __builtin_amdgcn_global_load_lds((const unsigned*)((const char*)(gbase) + (voff)[_i]), (LAS unsigned*)(lds + (bufoff) + ldsw + _i * 8192), 16, 0, 0); } while (0)
; #define PG8_LDA(dst, b, h) do { _Pragma("unroll") for (int m = 0; m < 4; ++m) _Pragma("unroll") for (int k = 0; k < 2; ++k) dst[m][k] = *(const LAS bf16x8*)(lds + PG8_SA(b, h) + aoff + m * 2048 + k * 1024); } while (0)
; #define PG8_MMA(ai, bj, At, Bt) do { __builtin_amdgcn_s_setprio(1); _Pragma("unroll") for (int m = 0; m < 4; ++m) _Pragma("unroll") for (int n = 0; n < 2; ++n) _Pragma("unroll") for (int k = 0; k < 2; ++k) \
;     acc[ai][bj][m][n] = __builtin_amdgcn_mfma_f32_16x16x32_bf16(Bt[n][k], At[m][k], acc[ai][bj][m][n], 0, 0, 0); __builtin_amdgcn_s_setprio(0); } while (0)
; #define PG8_WAIT_V(n) asm volatile("s_waitcnt vmcnt(" #n ")" ::: "memory")
; #define PG8_WAIT_L(n) asm volatile("s_waitcnt lgkmcnt(" #n ")" ::: "memory")
; #define PG8_BAR __builtin_amdgcn_s_barrier()
; #define PG8_SCHED __builtin_amdgcn_sched_barrier(0)
; template <class Epi, class Sched = StaticOrder>
; DI void gemm_phase(LAS unsigned char* lds, const Gemm g, const Sched& S, const Epi& E) {
;     ...
;       PG8_LDA(At, 1, 1); PG8_STAGE(PG8_SA(1, 0), a3, voffA);
;       PG8_BAR; PG8_WAIT_L(0); PG8_MMA(1, 0, At, B0); PG8_BAR; PG8_SCHED;
;       PG8_STAGE(PG8_SB(1, 1), b3 + hstep, voffB);
;       PG8_WAIT_V(6); PG8_BAR; PG8_MMA(1, 1, At, B1); PG8_BAR;
	s_waitcnt lgkmcnt(0)
	s_setprio 1
	v_mfma_f32_16x16x32_bf16 v[60:63], v[128:131], v[144:147], v[60:63]
	v_mfma_f32_16x16x32_bf16 v[56:59], v[136:139], v[144:147], v[56:59]
	v_mfma_f32_16x16x32_bf16 v[44:47], v[128:131], v[152:155], v[44:47]
	v_mfma_f32_16x16x32_bf16 v[40:43], v[136:139], v[152:155], v[40:43]
	v_mfma_f32_16x16x32_bf16 v[28:31], v[128:131], v[160:163], v[28:31]
	v_mfma_f32_16x16x32_bf16 v[24:27], v[136:139], v[160:163], v[24:27]
	v_mfma_f32_16x16x32_bf16 v[12:15], v[128:131], v[168:171], v[12:15]
	v_mfma_f32_16x16x32_bf16 v[8:11], v[136:139], v[168:171], v[8:11]
	v_mfma_f32_16x16x32_bf16 v[60:63], v[132:135], v[148:151], v[60:63]
	v_mfma_f32_16x16x32_bf16 v[56:59], v[140:143], v[148:151], v[56:59]
	v_mfma_f32_16x16x32_bf16 v[44:47], v[132:135], v[156:159], v[44:47]
	v_mfma_f32_16x16x32_bf16 v[40:43], v[140:143], v[156:159], v[40:43]
	v_mfma_f32_16x16x32_bf16 v[28:31], v[132:135], v[164:167], v[28:31]
	v_mfma_f32_16x16x32_bf16 v[24:27], v[140:143], v[164:167], v[24:27]
	v_mfma_f32_16x16x32_bf16 v[12:15], v[132:135], v[172:175], v[12:15]
	v_mfma_f32_16x16x32_bf16 v[8:11], v[140:143], v[172:175], v[8:11]
	s_barrier
	s_setprio 0
	s_add_u32 s24, s24, 0x80080
	s_addc_u32 s25, s25, 0
	s_add_i32 s26, s26, s35
	v_lshl_add_u64 v[128:129], s[24:25], 0, v[180:181]
	s_mov_b32 m0, s26
	s_nop 0
	global_load_lds_dwordx4 v[128:129], off
	v_lshl_add_u64 v[128:129], s[24:25], 0, v[176:177]
	s_add_i32 m0, s26, 0x2000
	s_nop 0
	global_load_lds_dwordx4 v[128:129], off
	ds_read_b128 v[128:131], v207
	ds_read_b128 v[132:135], v207 offset:1024
	ds_read_b128 v[136:139], v207 offset:2048
	ds_read_b128 v[140:143], v207 offset:3072
	s_waitcnt vmcnt(6)
	s_barrier
	s_setprio 1
	v_mfma_f32_16x16x32_bf16 v[52:55], v[192:195], v[144:147], v[52:55]
	v_mfma_f32_16x16x32_bf16 v[48:51], v[200:203], v[144:147], v[48:51]
	v_mfma_f32_16x16x32_bf16 v[36:39], v[192:195], v[152:155], v[36:39]
	v_mfma_f32_16x16x32_bf16 v[32:35], v[200:203], v[152:155], v[32:35]
	v_mfma_f32_16x16x32_bf16 v[20:23], v[192:195], v[160:163], v[20:23]
	v_mfma_f32_16x16x32_bf16 v[16:19], v[200:203], v[160:163], v[16:19]
	v_mfma_f32_16x16x32_bf16 v[4:7], v[192:195], v[168:171], v[4:7]
	v_mfma_f32_16x16x32_bf16 v[0:3], v[200:203], v[168:171], v[0:3]
	v_mfma_f32_16x16x32_bf16 v[52:55], v[196:199], v[148:151], v[52:55]
	v_mfma_f32_16x16x32_bf16 v[48:51], v[212:215], v[148:151], v[48:51]
	v_mfma_f32_16x16x32_bf16 v[36:39], v[196:199], v[156:159], v[36:39]
	v_mfma_f32_16x16x32_bf16 v[32:35], v[212:215], v[156:159], v[32:35]
	v_mfma_f32_16x16x32_bf16 v[20:23], v[196:199], v[164:167], v[20:23]
	v_mfma_f32_16x16x32_bf16 v[16:19], v[212:215], v[164:167], v[16:19]
	v_mfma_f32_16x16x32_bf16 v[4:7], v[196:199], v[172:175], v[4:7]
	v_mfma_f32_16x16x32_bf16 v[0:3], v[212:215], v[172:175], v[0:3]
	s_add_i32 s53, s53, 2
	s_add_u32 s22, s22, 0x100
	s_addc_u32 s23, s23, 0
	s_add_u32 s45, s45, 0x100
	s_addc_u32 s52, s52, 0
	s_cmp_gt_u32 s53, 29
	s_barrier
	s_setprio 0
	s_cbranch_scc0 .LBB0_728
; DI unsigned pack2(float lo, float hi) { f32x2 v = {lo, hi}; bf16v2 r = __builtin_convertvector(v, bf16v2); return __builtin_bit_cast(unsigned, r); }
;   DI void operator()(const f32x4 (&acc)[2][2][4][2], const Unit& u, int wr, int wc, int fr, int fq) const {
;     const int row0 = u.pm * BM + wr * 64 + fr, col0 = u.pn * BM + wc * 32 + 8 * fq;
; #pragma unroll
;     for (int ai = 0; ai < 2; ++ai) {
;       f32x4 bv[4][2][2];
; #pragma unroll
;       for (int m = 0; m < 4; ++m)
; #pragma unroll
;         for (int bj = 0; bj < 2; ++bj) {
;           const float* bp = base + (size_t)(row0 + ai * HALF + m * 16) * 2048 + col0 + bj * HALF;
;           bv[m][bj][0] = *(const f32x4*)bp; bv[m][bj][1] = *(const f32x4*)(bp + 4);
;         }
; #pragma unroll
;       for (int m = 0; m < 4; ++m) {
;         const int row = row0 + ai * HALF + m * 16;
;         const size_t off = (size_t)row * 2048 + col0;
;         float ss = 0.f;
; #pragma unroll
;         for (int bj = 0; bj < 2; ++bj) {
;           const f32x4 v0 = acc[ai][bj][m][0] + bv[m][bj][0], v1 = acc[ai][bj][m][1] + bv[m][bj][1];
;           *(f32x4*)(C + off + bj * HALF) = v0; *(f32x4*)(C + off + bj * HALF + 4) = v1;
;           if (xb) {
;             u32x4 w; w.x = pack2(v0[0], v0[1]); w.y = pack2(v0[2], v0[3]); w.z = pack2(v1[0], v1[1]); w.w = pack2(v1[2], v1[3]);
;             *(u32x4*)(xb + off + bj * HALF) = w;
;             ss += v0[0] * v0[0] + v0[1] * v0[1] + v0[2] * v0[2] + v0[3] * v0[3] + v1[0] * v1[0] + v1[1] * v1[1] + v1[2] * v1[2] + v1[3] * v1[3];
;           }
;         }
;         if (xb) {
;           ss += __shfl_xor(ss, 16); ss += __shfl_xor(ss, 32);
;           if (fq == 0) ssq[(size_t)row * 32 + u.pn * 4 + wc] = ss;
;         }
	s_waitcnt lgkmcnt(0)
	v_lshl_add_u32 v196, s12, 8, v204
	v_lshl_or_b32 v192, s42, 8, v206
	v_ashrrev_i32_e32 v193, 31, v192
	v_ashrrev_i32_e32 v197, 31, v196
	v_lshl_add_u64 v[194:195], v[192:193], 2, s[60:61]
	v_lshlrev_b64 v[128:129], 13, v[196:197]
	v_lshl_add_u64 v[128:129], v[194:195], 0, v[128:129]
	global_load_dwordx4 v[214:217], v[128:129], off
	global_load_dwordx4 v[218:221], v[128:129], off offset:16
	global_load_dwordx4 v[222:225], v[128:129], off offset:512
	global_load_dwordx4 v[226:229], v[128:129], off offset:528
	v_or_b32_e32 v202, 16, v196
	v_or_b32_e32 v200, 32, v196
	v_or_b32_e32 v198, 48, v196
	v_ashrrev_i32_e32 v203, 31, v202
	v_ashrrev_i32_e32 v201, 31, v200
	v_ashrrev_i32_e32 v199, 31, v198
	v_lshlrev_b64 v[128:129], 13, v[202:203]
	v_lshlrev_b64 v[130:131], 13, v[200:201]
	v_lshlrev_b64 v[132:133], 13, v[198:199]
	v_lshl_add_u64 v[128:129], v[194:195], 0, v[128:129]
	v_lshl_add_u64 v[130:131], v[194:195], 0, v[130:131]
	v_lshl_add_u64 v[132:133], v[194:195], 0, v[132:133]
	global_load_dwordx4 v[168:171], v[128:129], off offset:16
	global_load_dwordx4 v[172:175], v[128:129], off
	global_load_dwordx4 v[160:163], v[128:129], off offset:528
	global_load_dwordx4 v[164:167], v[128:129], off offset:512
	global_load_dwordx4 v[152:155], v[130:131], off offset:16
	global_load_dwordx4 v[156:159], v[130:131], off
	global_load_dwordx4 v[144:147], v[130:131], off offset:528
	global_load_dwordx4 v[148:151], v[130:131], off offset:512
	global_load_dwordx4 v[136:139], v[132:133], off offset:16
	global_load_dwordx4 v[140:143], v[132:133], off
	s_nop 0
	global_load_dwordx4 v[128:131], v[132:133], off offset:528
	s_nop 0
	global_load_dwordx4 v[132:135], v[132:133], off offset:512
	v_and_b32_e32 v212, 64, v211
	v_xor_b32_e32 v230, 16, v211
	v_add_u32_e32 v232, 64, v212
	v_xor_b32_e32 v231, 32, v211
	v_cmp_lt_i32_e32 vcc, v230, v232
	v_lshlrev_b64 v[212:213], 11, v[196:197]
	v_readlane_b32 s64, v243, 3
	v_cndmask_b32_e32 v233, v211, v230, vcc
	v_cmp_lt_i32_e32 vcc, v231, v232
	v_readlane_b32 s78, v243, 17
	v_readlane_b32 s79, v243, 18
	v_cndmask_b32_e32 v234, v211, v231, vcc
	v_lshl_add_u64 v[230:231], v[212:213], 0, v[192:193]
	v_lshlrev_b32_e32 v212, 2, v233
	v_lshl_add_u64 v[232:233], v[230:231], 2, s[78:79]
	v_lshl_add_u64 v[230:231], v[230:231], 1, s[2:3]
	s_lshl_b32 s22, s42, 2
	s_ashr_i32 s23, s22, 31
	v_readlane_b32 s65, v243, 4
	v_readlane_b32 s66, v243, 5
	v_readlane_b32 s67, v243, 6
	v_readlane_b32 s68, v243, 7
	v_readlane_b32 s69, v243, 8
	v_readlane_b32 s70, v243, 9
	v_readlane_b32 s71, v243, 10
	v_readlane_b32 s72, v243, 11
	v_readlane_b32 s73, v243, 12
	v_readlane_b32 s74, v243, 13
	v_readlane_b32 s75, v243, 14
	v_readlane_b32 s76, v243, 15
	v_readlane_b32 s77, v243, 16
	s_waitcnt vmcnt(0)
	v_pk_add_f32 v[126:127], v[126:127], v[216:217]
	v_pk_add_f32 v[124:125], v[124:125], v[214:215]
	v_pk_add_f32 v[116:117], v[116:117], v[222:223]
	v_pk_add_f32 v[122:123], v[122:123], v[220:221]
	v_pk_add_f32 v[120:121], v[120:121], v[218:219]
	v_pk_add_f32 v[214:215], v[112:113], v[226:227]
	global_store_dwordx4 v[232:233], v[124:127], off
	global_store_dwordx4 v[232:233], v[120:123], off offset:16
	v_cvt_pk_bf16_f32 v112, v124, v125
	v_mul_f32_e32 v125, v125, v125
	v_mul_f32_e32 v213, v117, v117
	v_pk_add_f32 v[118:119], v[118:119], v[224:225]
	v_fmac_f32_e32 v125, v124, v124
	v_fmac_f32_e32 v213, v116, v116
	v_fmac_f32_e32 v125, v126, v126
	v_fmac_f32_e32 v213, v118, v118
	v_fmac_f32_e32 v125, v127, v127
	v_fmac_f32_e32 v213, v119, v119
	v_fmac_f32_e32 v125, v120, v120
	v_fmac_f32_e32 v213, v214, v214
	v_pk_add_f32 v[216:217], v[114:115], v[228:229]
	v_fmac_f32_e32 v125, v121, v121
	v_fmac_f32_e32 v213, v215, v215
	v_fmac_f32_e32 v125, v122, v122
	v_fmac_f32_e32 v213, v216, v216
	v_fmac_f32_e32 v125, v123, v123
	v_fmac_f32_e32 v213, v217, v217
	v_cvt_pk_bf16_f32 v114, v120, v121
	v_add_f32_e32 v120, v125, v213
	ds_bpermute_b32 v121, v212, v120
	v_cvt_pk_bf16_f32 v113, v126, v127
	v_cvt_pk_bf16_f32 v115, v122, v123
	global_store_dwordx4 v[230:231], v[112:115], off
	global_store_dwordx4 v[232:233], v[116:119], off offset:512
	global_store_dwordx4 v[232:233], v[214:217], off offset:528
	v_cvt_pk_bf16_f32 v122, v116, v117
	s_waitcnt lgkmcnt(0)
	v_add_f32_e32 v112, v120, v121
	v_lshlrev_b32_e32 v120, 2, v234
	ds_bpermute_b32 v113, v120, v112
	v_cvt_pk_bf16_f32 v123, v118, v119
	v_cvt_pk_bf16_f32 v124, v214, v215
	v_cvt_pk_bf16_f32 v125, v216, v217
	global_store_dwordx4 v[230:231], v[122:125], off offset:256
	s_and_saveexec_b64 s[24:25], s[0:1]
	s_cbranch_execz .LBB0_731
	s_waitcnt lgkmcnt(0)
	v_add_f32_e32 v114, v112, v113
	v_lshlrev_b64 v[112:113], 7, v[196:197]
	v_lshl_add_u64 v[112:113], s[8:9], 0, v[112:113]
	v_lshl_add_u64 v[112:113], s[22:23], 2, v[112:113]
	s_lshl_b32 s12, s41, 2
	v_lshl_add_u64 v[112:113], v[112:113], 0, s[12:13]
	global_store_dword v[112:113], v114, off

; #define PG8_STAGE(bufoff, gbase, voff) do { _Pragma("unroll") for (int _i = 0; _i < 2; ++_i) \
;     __builtin_amdgcn_global_load_lds((const unsigned*)((const char*)(gbase) + (voff)[_i]), (LAS unsigned*)(lds + (bufoff) + ldsw + _i * 8192), 16, 0, 0); } while (0)
; #define PG8_LDA(dst, b, h) do { _Pragma("unroll") for (int m = 0; m < 4; ++m) _Pragma("unroll") for (int k = 0; k < 2; ++k) dst[m][k] = *(const LAS bf16x8*)(lds + PG8_SA(b, h) + aoff + m * 2048 + k * 1024); } while (0)
; #define PG8_LDB(dst, b, h) do { _Pragma("unroll") for (int n = 0; n < 2; ++n) _Pragma("unroll") for (int k = 0; k < 2; ++k) dst[n][k] = *(const LAS bf16x8*)(lds + PG8_SB(b, h) + boff + n * 2048 + k * 1024); } while (0)
; #define PG8_MMA(ai, bj, At, Bt) do { __builtin_amdgcn_s_setprio(1); _Pragma("unroll") for (int m = 0; m < 4; ++m) _Pragma("unroll") for (int n = 0; n < 2; ++n) _Pragma("unroll") for (int k = 0; k < 2; ++k) \
;     acc[ai][bj][m][n] = __builtin_amdgcn_mfma_f32_16x16x32_bf16(Bt[n][k], At[m][k], acc[ai][bj][m][n], 0, 0, 0); __builtin_amdgcn_s_setprio(0); } while (0)
; #define PG8_WAIT_V(n) asm volatile("s_waitcnt vmcnt(" #n ")" ::: "memory")
; #define PG8_WAIT_L(n) asm volatile("s_waitcnt lgkmcnt(" #n ")" ::: "memory")
; #define PG8_BAR __builtin_amdgcn_s_barrier()
; #define PG8_SCHED __builtin_amdgcn_sched_barrier(0)
; template <class Epi, class Sched = StaticOrder>
; DI void gemm_phase(LAS unsigned char* lds, const Gemm g, const Sched& S, const Epi& E) {
;     ...
;       PG8_LDB(B0, 0, 0); PG8_SCHED; PG8_LDA(At, 0, 0); PG8_STAGE(PG8_SA(1, 1), a1 + hstep, voffA);
;       PG8_WAIT_L(8); PG8_BAR; PG8_WAIT_L(0); PG8_MMA(0, 0, At, B0); PG8_BAR; PG8_SCHED;
;       PG8_LDB(B1, 0, 1); PG8_STAGE(PG8_SB(0, 0), b2, voffB);
;       PG8_BAR; PG8_WAIT_L(0); PG8_MMA(0, 1, At, B1); PG8_BAR;
;       PG8_LDA(At, 0, 1); PG8_STAGE(PG8_SA(0, 0), a2, voffA);
;       PG8_BAR; PG8_WAIT_L(0); PG8_MMA(1, 0, At, B0); PG8_BAR; PG8_SCHED;
;       PG8_STAGE(PG8_SB(0, 1), b2 + hstep, voffB);
;       PG8_WAIT_V(6); PG8_BAR; PG8_MMA(1, 1, At, B1); PG8_BAR;
.LBB0_811:
	s_add_u32 s46, s14, 0xfff80080
	s_addc_u32 s47, s15, -1
	s_cmp_eq_u32 s52, 28
	s_cselect_b32 s49, s37, s47
	s_cselect_b32 s48, s42, s46
	s_cselect_b32 s47, s35, s45
	s_cselect_b32 s46, s43, s44
	v_lshl_add_u64 v[196:197], s[14:15], 0, v[170:171]
	s_add_i32 m0, s62, 0xc000
	ds_read_b128 v[80:83], v202
	ds_read_b128 v[84:87], v202 offset:1024
	ds_read_b128 v[92:95], v202 offset:2048
	ds_read_b128 v[96:99], v202 offset:3072
	ds_read_b128 v[180:183], v202 offset:4096
	ds_read_b128 v[184:187], v202 offset:5120
	ds_read_b128 v[188:191], v202 offset:6144
	ds_read_b128 v[192:195], v202 offset:7168
	global_load_lds_dwordx4 v[196:197], off
	v_lshl_add_u64 v[196:197], s[14:15], 0, v[172:173]
	s_add_i32 m0, s62, 0xe000
	s_nop 0
	global_load_lds_dwordx4 v[196:197], off
	s_waitcnt lgkmcnt(8)
	s_barrier
	s_waitcnt lgkmcnt(0)
	s_setprio 1
	v_mfma_f32_16x16x32_bf16 v[156:159], v[64:67], v[80:83], v[156:159]
	v_mfma_f32_16x16x32_bf16 v[144:147], v[72:75], v[80:83], v[144:147]
	v_mfma_f32_16x16x32_bf16 v[140:143], v[64:67], v[92:95], v[140:143]
	v_mfma_f32_16x16x32_bf16 v[132:135], v[72:75], v[92:95], v[132:135]
	v_mfma_f32_16x16x32_bf16 v[124:127], v[64:67], v[180:183], v[124:127]
	v_mfma_f32_16x16x32_bf16 v[116:119], v[72:75], v[180:183], v[116:119]
	v_mfma_f32_16x16x32_bf16 v[112:115], v[64:67], v[188:191], v[112:115]
	v_mfma_f32_16x16x32_bf16 v[108:111], v[72:75], v[188:191], v[108:111]
	v_mfma_f32_16x16x32_bf16 v[156:159], v[68:71], v[84:87], v[156:159]
	v_mfma_f32_16x16x32_bf16 v[144:147], v[76:79], v[84:87], v[144:147]
	v_mfma_f32_16x16x32_bf16 v[140:143], v[68:71], v[96:99], v[140:143]
	v_mfma_f32_16x16x32_bf16 v[132:135], v[76:79], v[96:99], v[132:135]
	v_mfma_f32_16x16x32_bf16 v[124:127], v[68:71], v[184:187], v[124:127]
	v_mfma_f32_16x16x32_bf16 v[116:119], v[76:79], v[184:187], v[116:119]
	v_mfma_f32_16x16x32_bf16 v[112:115], v[68:71], v[192:195], v[112:115]
	v_mfma_f32_16x16x32_bf16 v[108:111], v[76:79], v[192:195], v[108:111]
	s_barrier
	s_setprio 0
	s_add_i32 s53, s72, s60
	v_lshl_add_u64 v[196:197], s[46:47], 0, v[164:165]
	s_mov_b32 m0, s53
	ds_read_b128 v[206:209], v203
	ds_read_b128 v[212:215], v203 offset:1024
	ds_read_b128 v[216:219], v203 offset:2048
	ds_read_b128 v[220:223], v203 offset:3072
	global_load_lds_dwordx4 v[196:197], off
	v_lshl_add_u64 v[232:233], s[46:47], 0, v[160:161]
	s_add_i32 m0, s53, 0x2000
	s_nop 0
	global_load_lds_dwordx4 v[232:233], off
	s_barrier
	s_waitcnt lgkmcnt(0)
	s_setprio 1
	v_mfma_f32_16x16x32_bf16 v[152:155], v[206:209], v[80:83], v[152:155]
	v_mfma_f32_16x16x32_bf16 v[80:83], v[216:219], v[80:83], v[148:151]
	v_mfma_f32_16x16x32_bf16 v[152:155], v[212:215], v[84:87], v[152:155]
	v_mfma_f32_16x16x32_bf16 v[80:83], v[220:223], v[84:87], v[80:83]
	v_mfma_f32_16x16x32_bf16 v[84:87], v[206:209], v[92:95], v[136:139]
	v_mfma_f32_16x16x32_bf16 v[92:95], v[216:219], v[92:95], v[128:131]
	v_mfma_f32_16x16x32_bf16 v[104:107], v[216:219], v[180:183], v[104:107]
	v_mfma_f32_16x16x32_bf16 v[100:103], v[206:209], v[188:191], v[100:103]
	v_mfma_f32_16x16x32_bf16 v[88:91], v[216:219], v[188:191], v[88:91]
	v_mfma_f32_16x16x32_bf16 v[84:87], v[212:215], v[96:99], v[84:87]
	v_mfma_f32_16x16x32_bf16 v[92:95], v[220:223], v[96:99], v[92:95]
	v_mfma_f32_16x16x32_bf16 v[96:99], v[206:209], v[180:183], v[120:123]
	v_mfma_f32_16x16x32_bf16 v[104:107], v[220:223], v[184:187], v[104:107]
	v_mfma_f32_16x16x32_bf16 v[100:103], v[212:215], v[192:195], v[100:103]
	v_mfma_f32_16x16x32_bf16 v[88:91], v[220:223], v[192:195], v[88:91]
	v_mfma_f32_16x16x32_bf16 v[96:99], v[212:215], v[184:187], v[96:99]
	s_barrier
	s_setprio 0
	s_mov_b32 m0, s62
	v_lshl_add_u64 v[234:235], s[48:49], 0, v[166:167]
	ds_read_b128 v[120:123], v202 offset:16384
	ds_read_b128 v[128:131], v202 offset:17408
	ds_read_b128 v[136:139], v202 offset:18432
	ds_read_b128 v[148:151], v202 offset:19456
	ds_read_b128 v[180:183], v202 offset:20480
	ds_read_b128 v[184:187], v202 offset:21504
	ds_read_b128 v[188:191], v202 offset:22528
	ds_read_b128 v[192:195], v202 offset:23552
	global_load_lds_dwordx4 v[234:235], off
	v_lshl_add_u64 v[236:237], s[48:49], 0, v[162:163]
	s_mov_b32 m0, s63
	s_nop 0
	global_load_lds_dwordx4 v[236:237], off
	s_waitcnt vmcnt(10)
	s_barrier
	s_waitcnt lgkmcnt(0)
	s_setprio 1
	v_mfma_f32_16x16x32_bf16 v[60:63], v[64:67], v[120:123], v[60:63]
	v_mfma_f32_16x16x32_bf16 v[48:51], v[72:75], v[120:123], v[48:51]
	v_mfma_f32_16x16x32_bf16 v[44:47], v[64:67], v[136:139], v[44:47]
	v_mfma_f32_16x16x32_bf16 v[36:39], v[72:75], v[136:139], v[36:39]
	v_mfma_f32_16x16x32_bf16 v[28:31], v[64:67], v[180:183], v[28:31]
	v_mfma_f32_16x16x32_bf16 v[20:23], v[72:75], v[180:183], v[20:23]
	v_mfma_f32_16x16x32_bf16 v[16:19], v[64:67], v[188:191], v[16:19]
	v_mfma_f32_16x16x32_bf16 v[12:15], v[72:75], v[188:191], v[12:15]
	v_mfma_f32_16x16x32_bf16 v[60:63], v[68:71], v[128:131], v[60:63]
	v_mfma_f32_16x16x32_bf16 v[48:51], v[76:79], v[128:131], v[48:51]
	v_mfma_f32_16x16x32_bf16 v[44:47], v[68:71], v[148:151], v[44:47]
	v_mfma_f32_16x16x32_bf16 v[36:39], v[76:79], v[148:151], v[36:39]
	v_mfma_f32_16x16x32_bf16 v[28:31], v[68:71], v[184:187], v[28:31]
	v_mfma_f32_16x16x32_bf16 v[20:23], v[76:79], v[184:187], v[20:23]
	v_mfma_f32_16x16x32_bf16 v[16:19], v[68:71], v[192:195], v[16:19]
	v_mfma_f32_16x16x32_bf16 v[12:15], v[76:79], v[192:195], v[12:15]
	s_barrier
	s_setprio 0
	s_add_u32 s54, s46, 0x80000
	s_addc_u32 s55, s47, 0
	s_add_i32 s53, s73, s60
	v_lshl_add_u64 v[64:65], s[54:55], 0, v[164:165]
	s_mov_b32 m0, s53
	s_nop 0
	global_load_lds_dwordx4 v[64:65], off
	v_lshl_add_u64 v[64:65], s[54:55], 0, v[160:161]
	s_add_i32 m0, s53, 0x2000
	s_nop 0
	global_load_lds_dwordx4 v[64:65], off
	s_add_i32 s53, 0, 0x18000
	v_add_u32_e32 v76, s53, v198
	ds_read_b128 v[64:67], v76
	ds_read_b128 v[68:71], v76 offset:1024
	ds_read_b128 v[72:75], v76 offset:2048
	ds_read_b128 v[76:79], v76 offset:3072
	s_waitcnt vmcnt(6)
	s_barrier
; #define PG8_STAGE(bufoff, gbase, voff) do { _Pragma("unroll") for (int _i = 0; _i < 2; ++_i) \
;     __builtin_amdgcn_global_load_lds((const unsigned*)((const char*)(gbase) + (voff)[_i]), (LAS unsigned*)(lds + (bufoff) + ldsw + _i * 8192), 16, 0, 0); } while (0)
; #define PG8_LDA(dst, b, h) do { _Pragma("unroll") for (int m = 0; m < 4; ++m) _Pragma("unroll") for (int k = 0; k < 2; ++k) dst[m][k] = *(const LAS bf16x8*)(lds + PG8_SA(b, h) + aoff + m * 2048 + k * 1024); } while (0)
; #define PG8_LDB(dst, b, h) do { _Pragma("unroll") for (int n = 0; n < 2; ++n) _Pragma("unroll") for (int k = 0; k < 2; ++k) dst[n][k] = *(const LAS bf16x8*)(lds + PG8_SB(b, h) + boff + n * 2048 + k * 1024); } while (0)
; #define PG8_MMA(ai, bj, At, Bt) do { __builtin_amdgcn_s_setprio(1); _Pragma("unroll") for (int m = 0; m < 4; ++m) _Pragma("unroll") for (int n = 0; n < 2; ++n) _Pragma("unroll") for (int k = 0; k < 2; ++k) \
;     acc[ai][bj][m][n] = __builtin_amdgcn_mfma_f32_16x16x32_bf16(Bt[n][k], At[m][k], acc[ai][bj][m][n], 0, 0, 0); __builtin_amdgcn_s_setprio(0); } while (0)
; #define PG8_WAIT_V(n) asm volatile("s_waitcnt vmcnt(" #n ")" ::: "memory")
; #define PG8_WAIT_L(n) asm volatile("s_waitcnt lgkmcnt(" #n ")" ::: "memory")
; #define PG8_BAR __builtin_amdgcn_s_barrier()
; #define PG8_SCHED __builtin_amdgcn_sched_barrier(0)
; template <class Epi, class Sched = StaticOrder>
; DI void gemm_phase(LAS unsigned char* lds, const Gemm g, const Sched& S, const Epi& E) {
;     ...
;       PG8_WAIT_V(6); PG8_BAR; PG8_MMA(1, 1, At, B1); PG8_BAR;
;       PG8_LDB(B0, 1, 0); PG8_SCHED; PG8_LDA(At, 1, 0); PG8_STAGE(PG8_SA(0, 1), a2 + hstep, voffA);
;       PG8_WAIT_L(8); PG8_BAR; PG8_WAIT_L(0); PG8_MMA(0, 0, At, B0); PG8_BAR; PG8_SCHED;
;       PG8_LDB(B1, 1, 1); PG8_STAGE(PG8_SB(1, 0), b3, voffB);
;       PG8_BAR; PG8_WAIT_L(0); PG8_MMA(0, 1, At, B1); PG8_BAR;
;       PG8_LDA(At, 1, 1); PG8_STAGE(PG8_SA(1, 0), a3, voffA);
	s_setprio 1
	v_mfma_f32_16x16x32_bf16 v[56:59], v[206:209], v[120:123], v[56:59]
	v_mfma_f32_16x16x32_bf16 v[52:55], v[216:219], v[120:123], v[52:55]
	v_mfma_f32_16x16x32_bf16 v[40:43], v[206:209], v[136:139], v[40:43]
	v_mfma_f32_16x16x32_bf16 v[32:35], v[216:219], v[136:139], v[32:35]
	v_mfma_f32_16x16x32_bf16 v[24:27], v[206:209], v[180:183], v[24:27]
	v_mfma_f32_16x16x32_bf16 v[8:11], v[216:219], v[180:183], v[8:11]
	v_mfma_f32_16x16x32_bf16 v[4:7], v[206:209], v[188:191], v[4:7]
	v_mfma_f32_16x16x32_bf16 v[0:3], v[216:219], v[188:191], v[0:3]
	v_mfma_f32_16x16x32_bf16 v[56:59], v[212:215], v[128:131], v[56:59]
	v_mfma_f32_16x16x32_bf16 v[52:55], v[220:223], v[128:131], v[52:55]
	v_mfma_f32_16x16x32_bf16 v[40:43], v[212:215], v[148:151], v[40:43]
	v_mfma_f32_16x16x32_bf16 v[32:35], v[220:223], v[148:151], v[32:35]
	v_mfma_f32_16x16x32_bf16 v[24:27], v[212:215], v[184:187], v[24:27]
	v_mfma_f32_16x16x32_bf16 v[8:11], v[220:223], v[184:187], v[8:11]
	v_mfma_f32_16x16x32_bf16 v[4:7], v[212:215], v[192:195], v[4:7]
	v_mfma_f32_16x16x32_bf16 v[0:3], v[220:223], v[192:195], v[0:3]
	s_barrier
	s_setprio 0
	s_add_u32 s48, s48, 0x80000
	s_addc_u32 s49, s49, 0
	s_mov_b32 m0, s64
	v_lshl_add_u64 v[136:137], s[48:49], 0, v[166:167]
	ds_read_b128 v[120:123], v202 offset:32768
	ds_read_b128 v[128:131], v202 offset:33792
	ds_read_b128 v[180:183], v202 offset:34816
	ds_read_b128 v[184:187], v202 offset:35840
	ds_read_b128 v[188:191], v202 offset:36864
	ds_read_b128 v[192:195], v202 offset:37888
	ds_read_b128 v[206:209], v202 offset:38912
	ds_read_b128 v[212:215], v202 offset:39936
	global_load_lds_dwordx4 v[136:137], off
	v_lshl_add_u64 v[136:137], s[48:49], 0, v[162:163]
	s_mov_b32 m0, s65
	s_nop 0
	global_load_lds_dwordx4 v[136:137], off
	s_waitcnt lgkmcnt(8)
	s_barrier
	s_waitcnt lgkmcnt(0)
	s_setprio 1
	v_mfma_f32_16x16x32_bf16 v[136:139], v[64:67], v[120:123], v[156:159]
	v_mfma_f32_16x16x32_bf16 v[156:159], v[68:71], v[128:131], v[136:139]
	v_mfma_f32_16x16x32_bf16 v[136:139], v[72:75], v[120:123], v[144:147]
	v_mfma_f32_16x16x32_bf16 v[144:147], v[76:79], v[128:131], v[136:139]
	v_mfma_f32_16x16x32_bf16 v[136:139], v[64:67], v[180:183], v[140:143]
	v_mfma_f32_16x16x32_bf16 v[132:135], v[72:75], v[180:183], v[132:135]
	v_mfma_f32_16x16x32_bf16 v[124:127], v[64:67], v[188:191], v[124:127]
	v_mfma_f32_16x16x32_bf16 v[116:119], v[72:75], v[188:191], v[116:119]
	v_mfma_f32_16x16x32_bf16 v[112:115], v[64:67], v[206:209], v[112:115]
	v_mfma_f32_16x16x32_bf16 v[108:111], v[72:75], v[206:209], v[108:111]
	v_mfma_f32_16x16x32_bf16 v[140:143], v[68:71], v[184:187], v[136:139]
	v_mfma_f32_16x16x32_bf16 v[132:135], v[76:79], v[184:187], v[132:135]
	v_mfma_f32_16x16x32_bf16 v[124:127], v[68:71], v[192:195], v[124:127]
	v_mfma_f32_16x16x32_bf16 v[116:119], v[76:79], v[192:195], v[116:119]
	v_mfma_f32_16x16x32_bf16 v[112:115], v[68:71], v[212:215], v[112:115]
	v_mfma_f32_16x16x32_bf16 v[108:111], v[76:79], v[212:215], v[108:111]
	s_barrier
	s_setprio 0
	s_add_i32 s48, 0, 0x1c000
	v_add_u32_e32 v136, s48, v198
	s_add_i32 s49, s53, s60
	ds_read_b128 v[216:219], v136
	ds_read_b128 v[220:223], v136 offset:1024
	ds_read_b128 v[224:227], v136 offset:2048
	ds_read_b128 v[228:231], v136 offset:3072
	v_lshl_add_u64 v[136:137], v[196:197], 0, s[24:25]
	s_mov_b32 m0, s49
	s_nop 0
	global_load_lds_dwordx4 v[136:137], off
	v_lshl_add_u64 v[136:137], v[232:233], 0, s[24:25]
	s_add_i32 m0, s49, 0x2000
	s_nop 0
	global_load_lds_dwordx4 v[136:137], off
	s_barrier
	s_waitcnt lgkmcnt(0)
	s_setprio 1
	v_mfma_f32_16x16x32_bf16 v[80:83], v[224:227], v[120:123], v[80:83]
	v_mfma_f32_16x16x32_bf16 v[136:139], v[216:219], v[120:123], v[152:155]
	v_mfma_f32_16x16x32_bf16 v[148:151], v[228:231], v[128:131], v[80:83]
	v_mfma_f32_16x16x32_bf16 v[80:83], v[216:219], v[180:183], v[84:87]
	v_mfma_f32_16x16x32_bf16 v[152:155], v[220:223], v[128:131], v[136:139]
	v_mfma_f32_16x16x32_bf16 v[136:139], v[220:223], v[184:187], v[80:83]
	v_mfma_f32_16x16x32_bf16 v[80:83], v[224:227], v[180:183], v[92:95]
	v_mfma_f32_16x16x32_bf16 v[128:131], v[228:231], v[184:187], v[80:83]
	v_mfma_f32_16x16x32_bf16 v[80:83], v[216:219], v[188:191], v[96:99]
	v_mfma_f32_16x16x32_bf16 v[120:123], v[220:223], v[192:195], v[80:83]
	v_mfma_f32_16x16x32_bf16 v[80:83], v[224:227], v[188:191], v[104:107]
	v_mfma_f32_16x16x32_bf16 v[104:107], v[228:231], v[192:195], v[80:83]
	v_mfma_f32_16x16x32_bf16 v[80:83], v[216:219], v[206:209], v[100:103]
	v_mfma_f32_16x16x32_bf16 v[100:103], v[220:223], v[212:215], v[80:83]
	v_mfma_f32_16x16x32_bf16 v[80:83], v[224:227], v[206:209], v[88:91]
	v_mfma_f32_16x16x32_bf16 v[88:91], v[228:231], v[212:215], v[80:83]
	s_barrier
	s_setprio 0
	s_mov_b32 m0, s67
	v_lshl_add_u64 v[196:197], v[234:235], 0, s[24:25]
	s_nop 2
	ds_read_b128 v[80:83], v202 offset:49152
	ds_read_b128 v[84:87], v202 offset:50176
	ds_read_b128 v[92:95], v202 offset:51200
	ds_read_b128 v[96:99], v202 offset:52224
	ds_read_b128 v[180:183], v202 offset:53248
	ds_read_b128 v[184:187], v202 offset:54272
	ds_read_b128 v[188:191], v202 offset:55296
	ds_read_b128 v[192:195], v202 offset:56320
	global_load_lds_dwordx4 v[196:197], off
	v_lshl_add_u64 v[196:197], v[236:237], 0, s[24:25]
	s_mov_b32 m0, s68
	s_nop 0
	global_load_lds_dwordx4 v[196:197], off
	s_waitcnt vmcnt(10)
	s_barrier
; #define PG8_STAGE(bufoff, gbase, voff) do { _Pragma("unroll") for (int _i = 0; _i < 2; ++_i) \
;     __builtin_amdgcn_global_load_lds((const unsigned*)((const char*)(gbase) + (voff)[_i]), (LAS unsigned*)(lds + (bufoff) + ldsw + _i * 8192), 16, 0, 0); } while (0)
; #define PG8_LDA(dst, b, h) do { _Pragma("unroll") for (int m = 0; m < 4; ++m) _Pragma("unroll") for (int k = 0; k < 2; ++k) dst[m][k] = *(const LAS bf16x8*)(lds + PG8_SA(b, h) + aoff + m * 2048 + k * 1024); } while (0)
; #define PG8_LDB(dst, b, h) do { _Pragma("unroll") for (int n = 0; n < 2; ++n) _Pragma("unroll") for (int k = 0; k < 2; ++k) dst[n][k] = *(const LAS bf16x8*)(lds + PG8_SB(b, h) + boff + n * 2048 + k * 1024); } while (0)
; #define PG8_WAIT_V(n) asm volatile("s_waitcnt vmcnt(" #n ")" ::: "memory")
; #define PG8_WAIT_L(n) asm volatile("s_waitcnt lgkmcnt(" #n ")" ::: "memory")
; #define PG8_BAR __builtin_amdgcn_s_barrier()
; #define PG8_SCHED __builtin_amdgcn_sched_barrier(0)
;   DI void operator()(const f32x4 (&acc)[2][2][4][2], const Unit& u, int wr, int wc, int fr, int fq) const {
;     const int col = u.pn * 128 + wc * 32 + 8 * fq;
;     float w0[8], w1[8], w2[8], bb[8];
; #pragma unroll
;     for (int e = 0; e < 8; ++e) { w0[e] = cw[col + e]; w1[e] = cw[5632 + col + e]; w2[e] = cw[2 * 5632 + col + e]; bb[e] = cb[col + e]; }
; #pragma unroll
;     for (int ai = 0; ai < 2; ++ai) {
;       const int row0 = u.pm * BM + ai * HALF + wr * 64, span = row0 >> 6;
;       float rsv[4];
; #pragma unroll
;       for (int m = 0; m < 4; ++m) rsv[m] = row_rstd(ssq, row0 + 16 * m + fr, fq);
; template <class Epi, class Sched = StaticOrder>
; DI void gemm_phase(LAS unsigned char* lds, const Gemm g, const Sched& S, const Epi& E) {
;     ...
;       PG8_LDB(B0, 1, 0); PG8_SCHED; PG8_LDA(At, 1, 0); PG8_STAGE(PG8_SA(0, 1), a2 + hstep, voffA);
;       PG8_WAIT_L(8); PG8_BAR; PG8_WAIT_L(0); PG8_MMA(0, 0, At, B0); PG8_BAR; PG8_SCHED;
;       PG8_LDB(B1, 1, 1); PG8_STAGE(PG8_SB(1, 0), b3, voffB);
;       PG8_BAR; PG8_WAIT_L(0); PG8_MMA(0, 1, At, B1); PG8_BAR;
;       PG8_LDA(At, 1, 1); PG8_STAGE(PG8_SA(1, 0), a3, voffA);
;       PG8_BAR; PG8_WAIT_L(0); PG8_MMA(1, 0, At, B0); PG8_BAR; PG8_SCHED;
;       PG8_STAGE(PG8_SB(1, 1), b3 + hstep, voffB);
;       PG8_WAIT_V(6); PG8_BAR; PG8_MMA(1, 1, At, B1); PG8_BAR;
	s_waitcnt lgkmcnt(0)
	s_setprio 1
	v_mfma_f32_16x16x32_bf16 v[60:63], v[64:67], v[80:83], v[60:63]
	v_mfma_f32_16x16x32_bf16 v[48:51], v[72:75], v[80:83], v[48:51]
	v_mfma_f32_16x16x32_bf16 v[44:47], v[64:67], v[92:95], v[44:47]
	v_mfma_f32_16x16x32_bf16 v[36:39], v[72:75], v[92:95], v[36:39]
	v_mfma_f32_16x16x32_bf16 v[28:31], v[64:67], v[180:183], v[28:31]
	v_mfma_f32_16x16x32_bf16 v[20:23], v[72:75], v[180:183], v[20:23]
	v_mfma_f32_16x16x32_bf16 v[16:19], v[64:67], v[188:191], v[16:19]
	v_mfma_f32_16x16x32_bf16 v[12:15], v[72:75], v[188:191], v[12:15]
	v_mfma_f32_16x16x32_bf16 v[60:63], v[68:71], v[84:87], v[60:63]
	v_mfma_f32_16x16x32_bf16 v[48:51], v[76:79], v[84:87], v[48:51]
	v_mfma_f32_16x16x32_bf16 v[44:47], v[68:71], v[96:99], v[44:47]
	v_mfma_f32_16x16x32_bf16 v[36:39], v[76:79], v[96:99], v[36:39]
	v_mfma_f32_16x16x32_bf16 v[28:31], v[68:71], v[184:187], v[28:31]
	v_mfma_f32_16x16x32_bf16 v[20:23], v[76:79], v[184:187], v[20:23]
	v_mfma_f32_16x16x32_bf16 v[16:19], v[68:71], v[192:195], v[16:19]
	v_mfma_f32_16x16x32_bf16 v[12:15], v[76:79], v[192:195], v[12:15]
	s_barrier
	s_setprio 0
	s_add_u32 s46, s46, 0x80080
	s_addc_u32 s47, s47, 0
	s_add_i32 s48, s48, s60
	v_lshl_add_u64 v[64:65], s[46:47], 0, v[164:165]
	s_mov_b32 m0, s48
	s_nop 0
	global_load_lds_dwordx4 v[64:65], off
	v_lshl_add_u64 v[64:65], s[46:47], 0, v[160:161]
	s_add_i32 m0, s48, 0x2000
	s_nop 0
	global_load_lds_dwordx4 v[64:65], off
	ds_read_b128 v[64:67], v201
	ds_read_b128 v[68:71], v201 offset:1024
	ds_read_b128 v[72:75], v201 offset:2048
	ds_read_b128 v[76:79], v201 offset:3072
	s_waitcnt vmcnt(6)
	s_barrier
	s_setprio 1
	v_mfma_f32_16x16x32_bf16 v[56:59], v[216:219], v[80:83], v[56:59]
	v_mfma_f32_16x16x32_bf16 v[52:55], v[224:227], v[80:83], v[52:55]
	v_mfma_f32_16x16x32_bf16 v[40:43], v[216:219], v[92:95], v[40:43]
	v_mfma_f32_16x16x32_bf16 v[32:35], v[224:227], v[92:95], v[32:35]
	v_mfma_f32_16x16x32_bf16 v[24:27], v[216:219], v[180:183], v[24:27]
	v_mfma_f32_16x16x32_bf16 v[8:11], v[224:227], v[180:183], v[8:11]
	v_mfma_f32_16x16x32_bf16 v[4:7], v[216:219], v[188:191], v[4:7]
	v_mfma_f32_16x16x32_bf16 v[0:3], v[224:227], v[188:191], v[0:3]
	v_mfma_f32_16x16x32_bf16 v[56:59], v[220:223], v[84:87], v[56:59]
	v_mfma_f32_16x16x32_bf16 v[52:55], v[228:231], v[84:87], v[52:55]
	v_mfma_f32_16x16x32_bf16 v[40:43], v[220:223], v[96:99], v[40:43]
	v_mfma_f32_16x16x32_bf16 v[32:35], v[228:231], v[96:99], v[32:35]
	v_mfma_f32_16x16x32_bf16 v[24:27], v[220:223], v[184:187], v[24:27]
	v_mfma_f32_16x16x32_bf16 v[8:11], v[228:231], v[184:187], v[8:11]
	v_mfma_f32_16x16x32_bf16 v[4:7], v[220:223], v[192:195], v[4:7]
	v_mfma_f32_16x16x32_bf16 v[0:3], v[228:231], v[192:195], v[0:3]
	s_add_i32 s52, s52, 2
	s_add_u32 s14, s14, 0x100
	s_addc_u32 s15, s15, 0
	s_add_u32 s44, s44, 0x100
	s_addc_u32 s45, s45, 0
	s_cmp_gt_u32 s52, 29
	s_barrier
	s_setprio 0
	s_cbranch_scc0 .LBB0_811
	s_waitcnt lgkmcnt(0)
	s_lshl_b32 s35, s12, 8
	s_add_i32 s35, s35, s66
	v_or_b32_e32 v190, s35, v179
	v_ashrrev_i32_e32 v191, 31, v190
	v_lshlrev_b64 v[64:65], 7, v[190:191]
	v_or_b32_e32 v188, 16, v190
	v_lshl_add_u64 v[64:65], v[168:169], 0, v[64:65]
	v_ashrrev_i32_e32 v189, 31, v188
	global_load_dwordx4 v[192:195], v[64:65], off
	global_load_dwordx4 v[206:209], v[64:65], off offset:16
	v_lshlrev_b64 v[64:65], 7, v[188:189]
	v_lshl_add_u64 v[64:65], v[168:169], 0, v[64:65]
	global_load_dwordx4 v[212:215], v[64:65], off
	global_load_dwordx4 v[216:219], v[64:65], off offset:16
	v_or_b32_e32 v186, 32, v190
	v_ashrrev_i32_e32 v187, 31, v186
	v_lshlrev_b64 v[64:65], 7, v[186:187]
	v_or_b32_e32 v184, 48, v190
	v_lshl_add_u64 v[64:65], v[168:169], 0, v[64:65]
	v_ashrrev_i32_e32 v185, 31, v184
	global_load_dwordx4 v[220:223], v[64:65], off
	global_load_dwordx4 v[224:227], v[64:65], off offset:16
	v_lshlrev_b64 v[64:65], 7, v[184:185]
	v_lshl_add_u64 v[64:65], v[168:169], 0, v[64:65]
	global_load_dwordx4 v[228:231], v[64:65], off
	global_load_dwordx4 v[232:235], v[64:65], off offset:16
	v_lshl_or_b32 v180, s13, 7, v200
	v_and_b32_e32 v65, 64, v204
	v_xor_b32_e32 v64, 16, v204
	v_ashrrev_i32_e32 v181, 31, v180
	v_add_u32_e32 v65, 64, v65
	v_readlane_b32 s44, v243, 3
	v_xor_b32_e32 v66, 32, v204
	v_lshlrev_b64 v[182:183], 2, v[180:181]
	v_cmp_lt_i32_e32 vcc, v64, v65
	v_readlane_b32 s52, v243, 11
	v_readlane_b32 s53, v243, 12
	v_cndmask_b32_e32 v64, v204, v64, vcc
	v_cmp_lt_i32_e32 vcc, v66, v65
	v_lshl_add_u64 v[92:93], s[52:53], 0, v[182:183]
	v_readlane_b32 s54, v243, 13
	v_cndmask_b32_e32 v65, v204, v66, vcc
	v_add_co_u32_e32 v94, vcc, 0x5000, v92
	v_readlane_b32 s55, v243, 14
	s_nop 0
	v_addc_co_u32_e32 v95, vcc, 0, v93, vcc
	v_add_co_u32_e32 v96, vcc, 0xb000, v92
	v_lshl_add_u64 v[72:73], s[54:55], 0, v[182:183]
	v_lshl_add_u64 v[74:75], v[92:93], 0, s[26:27]
	v_lshl_add_u64 v[76:77], v[92:93], 0, s[28:29]
	v_addc_co_u32_e32 v97, vcc, 0, v93, vcc
	v_lshlrev_b32_e32 v187, 2, v64
	v_lshlrev_b32_e32 v185, 2, v65
	global_load_dwordx4 v[64:67], v[92:93], off offset:16
	global_load_dwordx4 v[80:83], v[92:93], off
	global_load_dwordx4 v[68:71], v[72:73], off offset:16
	global_load_dwordx4 v[84:87], v[72:73], off
	s_nop 0
	global_load_dwordx4 v[72:75], v[74:75], off offset:16
	s_nop 0
	global_load_dwordx4 v[76:79], v[76:77], off offset:16
	s_nop 0
	global_load_dwordx4 v[92:95], v[94:95], off offset:2048
	s_nop 0
	global_load_dwordx4 v[96:99], v[96:97], off
	v_mov_b32_e32 v211, 0
	v_mov_b32_e32 v205, 0
	v_readlane_b32 s45, v243, 4
	v_readlane_b32 s46, v243, 5
	v_readlane_b32 s47, v243, 6
	v_readlane_b32 s48, v243, 7
	v_readlane_b32 s49, v243, 8
	v_readlane_b32 s50, v243, 9
	v_readlane_b32 s51, v243, 10
	v_readlane_b32 s56, v243, 15
	v_readlane_b32 s57, v243, 16
	v_readlane_b32 s58, v243, 17
	v_readlane_b32 s59, v243, 18
	s_waitcnt vmcnt(0)
; DI float dpp_ror1(float v) { return __int_as_float(__builtin_amdgcn_update_dpp(0, __float_as_int(v), 0x121, 0xf, 0xf, false)); }
; DI float dpp_ror2(float v) { return __int_as_float(__builtin_amdgcn_update_dpp(0, __float_as_int(v), 0x122, 0xf, 0xf, false)); }
; DI float row_rstd(const float* ssq, int row, int fq) {
;   const f32x4 a = *(const f32x4*)(ssq + (size_t)row * 32 + fq * 8), b = *(const f32x4*)(ssq + (size_t)row * 32 + fq * 8 + 4);
;   float sm = ((a[0] + a[1]) + (a[2] + a[3])) + ((b[0] + b[1]) + (b[2] + b[3]));
;   sm += __shfl_xor(sm, 16); sm += __shfl_xor(sm, 32);
;   return rsqrtf(sm * (1.0f / 2048.f) + 1e-6f);
;   DI void operator()(const f32x4 (&acc)[2][2][4][2], const Unit& u, int wr, int wc, int fr, int fq) const {
;     const int col = u.pn * 128 + wc * 32 + 8 * fq;
;     float w0[8], w1[8], w2[8], bb[8];
; #pragma unroll
;     for (int e = 0; e < 8; ++e) { w0[e] = cw[col + e]; w1[e] = cw[5632 + col + e]; w2[e] = cw[2 * 5632 + col + e]; bb[e] = cb[col + e]; }
; #pragma unroll
;     for (int ai = 0; ai < 2; ++ai) {
;       const int row0 = u.pm * BM + ai * HALF + wr * 64, span = row0 >> 6;
;       float rsv[4];
; #pragma unroll
;       for (int m = 0; m < 4; ++m) rsv[m] = row_rstd(ssq, row0 + 16 * m + fr, fq);
;       float p1[8], p2[8];
; #pragma unroll
;       for (int e = 0; e < 8; ++e) { p1[e] = 0.f; p2[e] = 0.f; }
; #pragma unroll
;       for (int m = 0; m < 4; ++m) {
;         float g[8], uu[8], a[8];
;         const float rs = rsv[m];
; #pragma unroll
;         for (int e = 0; e < 4; ++e) { g[e] = acc[ai][0][m][0][e] * rs; g[4 + e] = acc[ai][0][m][1][e] * rs; uu[e] = acc[ai][1][m][0][e] * rs; uu[4 + e] = acc[ai][1][m][1][e] * rs; }
; #pragma unroll
;         for (int e = 0; e < 8; ++e) {
;           const float x1 = dpp_ror1(g[e]), x2 = dpp_ror2(g[e]);
;           const float pr1 = (fr == 0) ? p1[e] : x1, pr2 = (fr < 2) ? p2[e] : x2;
;           a[e] = w2[e] * g[e] + w1[e] * pr1 + w0[e] * pr2 + bb[e];
;           p1[e] = x1; p2[e] = x2;
;         }
	v_mov_b32_e32 v196, v192
	v_mov_b32_e32 v197, v206
	v_mov_b32_e32 v206, v193
	v_mov_b32_e32 v192, v194
	v_mov_b32_e32 v193, v208
	v_mov_b32_e32 v208, v195
	v_pk_add_f32 v[194:195], v[196:197], v[206:207]
	v_pk_add_f32 v[192:193], v[192:193], v[208:209]
	v_mov_b32_e32 v196, v212
	v_mov_b32_e32 v197, v216
	v_mov_b32_e32 v216, v213
	v_mov_b32_e32 v206, v214
	v_mov_b32_e32 v207, v218
	v_mov_b32_e32 v218, v215
	v_pk_add_f32 v[192:193], v[194:195], v[192:193]
	v_pk_add_f32 v[194:195], v[196:197], v[216:217]
	v_pk_add_f32 v[196:197], v[206:207], v[218:219]
	v_mov_b32_e32 v208, v220
	v_pk_add_f32 v[194:195], v[194:195], v[196:197]
	v_mov_b32_e32 v197, v192
	v_mov_b32_e32 v196, v194
	v_mov_b32_e32 v192, v195
	v_pk_add_f32 v[192:193], v[196:197], v[192:193]
	ds_bpermute_b32 v195, v187, v193
	ds_bpermute_b32 v194, v187, v192
	v_mov_b32_e32 v209, v224
	v_mov_b32_e32 v224, v221
	v_mov_b32_e32 v212, v222
	v_mov_b32_e32 v213, v226
	s_waitcnt lgkmcnt(0)
	v_pk_add_f32 v[192:193], v[192:193], v[194:195]
	ds_bpermute_b32 v195, v185, v193
	ds_bpermute_b32 v194, v185, v192
	v_mov_b32_e32 v226, v223
	v_mov_b32_e32 v196, v228
	v_mov_b32_e32 v197, v232
	v_mov_b32_e32 v232, v229
	s_waitcnt lgkmcnt(0)
	v_pk_add_f32 v[192:193], v[192:193], v[194:195]
	v_mov_b32_e32 v206, v230
	v_pk_fma_f32 v[192:193], v[192:193], s[30:31], v[178:179] op_sel_hi:[1,0,0]
	v_mov_b32_e32 v207, v234
	v_mul_f32_e32 v189, 0x4b800000, v193
	v_cmp_gt_f32_e64 s[12:13], s74, v193
	v_mov_b32_e32 v234, v231
	v_pk_add_f32 v[208:209], v[208:209], v[224:225]
	v_cndmask_b32_e64 v189, v193, v189, s[12:13]
	v_rsq_f32_e32 v189, v189
	v_pk_add_f32 v[212:213], v[212:213], v[226:227]
	v_pk_add_f32 v[196:197], v[196:197], v[232:233]
	v_pk_add_f32 v[194:195], v[206:207], v[234:235]
	v_mul_f32_e32 v191, 0x45800000, v189
	v_cndmask_b32_e64 v220, v189, v191, s[12:13]
	v_pk_add_f32 v[208:209], v[208:209], v[212:213]
	v_pk_add_f32 v[194:195], v[196:197], v[194:195]
	v_pk_mul_f32 v[156:157], v[156:157], v[220:221] op_sel_hi:[1,0]
	v_mov_b32_e32 v216, 0
	v_mov_b32_e32 v218, 0
	v_mov_b32_e32 v196, v194
	v_mov_b32_e32 v197, v208
	v_mov_b32_e32 v208, v195
	v_mov_b32_dpp v216, v156 row_ror:1 row_mask:0xf bank_mask:0xf
	v_mov_b32_dpp v218, v157 row_ror:1 row_mask:0xf bank_mask:0xf
	v_pk_add_f32 v[194:195], v[196:197], v[208:209]
	v_cndmask_b32_e64 v207, v218, 0, s[0:1]
	v_cndmask_b32_e64 v206, v216, 0, s[0:1]
	v_pk_mul_f32 v[158:159], v[158:159], v[220:221] op_sel_hi:[1,0]
	v_mov_b32_e32 v212, 0
	v_mov_b32_e32 v214, 0
	ds_bpermute_b32 v197, v187, v195
	ds_bpermute_b32 v196, v187, v194
	v_mov_b32_e32 v215, 0
	v_mov_b32_e32 v217, 0
	v_pk_mul_f32 v[206:207], v[92:93], v[206:207]
	v_mov_b32_dpp v212, v158 row_ror:1 row_mask:0xf bank_mask:0xf
	v_mov_b32_dpp v214, v159 row_ror:1 row_mask:0xf bank_mask:0xf
	v_mov_b32_dpp v215, v156 row_ror:2 row_mask:0xf bank_mask:0xf
	v_mov_b32_dpp v217, v157 row_ror:2 row_mask:0xf bank_mask:0xf
	v_pk_fma_f32 v[156:157], v[96:97], v[156:157], v[206:207]
	v_mov_b32_e32 v213, 0
	v_cndmask_b32_e64 v207, v214, 0, s[0:1]
	v_cndmask_b32_e64 v206, v212, 0, s[0:1]
	v_cndmask_b32_e64 v209, v217, 0, s[4:5]
	v_cndmask_b32_e64 v208, v215, 0, s[4:5]
	v_mov_b32_dpp v211, v158 row_ror:2 row_mask:0xf bank_mask:0xf
	v_mov_b32_dpp v213, v159 row_ror:2 row_mask:0xf bank_mask:0xf
	v_pk_mul_f32 v[206:207], v[94:95], v[206:207]
	v_pk_fma_f32 v[156:157], v[80:81], v[208:209], v[156:157]
	v_cndmask_b32_e64 v209, v213, 0, s[4:5]
	v_cndmask_b32_e64 v208, v211, 0, s[4:5]
	v_pk_fma_f32 v[158:159], v[98:99], v[158:159], v[206:207]
	v_pk_mul_f32 v[144:145], v[144:145], v[220:221] op_sel_hi:[1,0]
	v_pk_fma_f32 v[158:159], v[82:83], v[208:209], v[158:159]
	v_mov_b32_e32 v207, 0
	v_mov_b32_e32 v209, 0
	v_pk_mul_f32 v[146:147], v[146:147], v[220:221] op_sel_hi:[1,0]
	v_mov_b32_e32 v191, 0
	s_waitcnt lgkmcnt(0)
	v_pk_add_f32 v[194:195], v[194:195], v[196:197]
	v_mov_b32_dpp v207, v144 row_ror:1 row_mask:0xf bank_mask:0xf
	v_mov_b32_dpp v209, v145 row_ror:1 row_mask:0xf bank_mask:0xf
	v_mov_b32_dpp v191, v146 row_ror:1 row_mask:0xf bank_mask:0xf
	v_mov_b32_dpp v205, v147 row_ror:1 row_mask:0xf bank_mask:0xf
	ds_bpermute_b32 v197, v185, v195
	ds_bpermute_b32 v196, v185, v194
	v_pk_mul_f32 v[152:153], v[152:153], v[220:221] op_sel_hi:[1,0]
	v_pk_mul_f32 v[148:149], v[148:149], v[220:221] op_sel_hi:[1,0]
	v_pk_mul_f32 v[154:155], v[154:155], v[220:221] op_sel_hi:[1,0]
	v_pk_mul_f32 v[150:151], v[150:151], v[220:221] op_sel_hi:[1,0]
	v_mov_b32_e32 v206, 0
	v_mov_b32_e32 v208, 0
	v_cndmask_b32_e64 v223, v209, 0, s[0:1]
	v_cndmask_b32_e64 v222, v207, 0, s[0:1]
	v_mov_b32_e32 v189, 0
	v_mov_b32_e32 v193, 0
	v_cndmask_b32_e64 v221, v205, 0, s[0:1]
	v_cndmask_b32_e64 v220, v191, 0, s[0:1]
	v_mov_b32_dpp v206, v144 row_ror:2 row_mask:0xf bank_mask:0xf
	v_mov_b32_dpp v208, v145 row_ror:2 row_mask:0xf bank_mask:0xf
	v_pk_mul_f32 v[222:223], v[72:73], v[222:223]
	v_mov_b32_dpp v189, v146 row_ror:2 row_mask:0xf bank_mask:0xf
	v_mov_b32_dpp v193, v147 row_ror:2 row_mask:0xf bank_mask:0xf
	v_pk_mul_f32 v[220:221], v[74:75], v[220:221]
	v_cndmask_b32_e64 v225, v208, 0, s[4:5]
	v_cndmask_b32_e64 v224, v206, 0, s[4:5]
	v_pk_fma_f32 v[144:145], v[76:77], v[144:145], v[222:223]
	v_cndmask_b32_e64 v223, v193, 0, s[4:5]
	v_cndmask_b32_e64 v222, v189, 0, s[4:5]
	v_pk_fma_f32 v[146:147], v[78:79], v[146:147], v[220:221]
	v_pk_fma_f32 v[144:145], v[64:65], v[224:225], v[144:145]
	v_pk_fma_f32 v[146:147], v[66:67], v[222:223], v[146:147]
	v_cmp_gt_f32_e32 vcc, s74, v192
	v_pk_add_f32 v[156:157], v[84:85], v[156:157]
	v_pk_add_f32 v[158:159], v[86:87], v[158:159]
	v_pk_add_f32 v[144:145], v[68:69], v[144:145]
	v_pk_add_f32 v[146:147], v[70:71], v[146:147]
	s_and_saveexec_b64 s[12:13], s[10:11]
	s_xor_b64 s[12:13], exec, s[12:13]
	s_cbranch_execz .LBB0_814
; DI unsigned pack2(float lo, float hi) { f32x2 v = {lo, hi}; bf16v2 r = __builtin_convertvector(v, bf16v2); return __builtin_bit_cast(unsigned, r); }
; DI float silu_f(float x) { return x * sigmoid_f(x); }
;   DI void operator()(const f32x4 (&acc)[2][2][4][2], const Unit& u, int wr, int wc, int fr, int fq) const {
;     ...
;           u32x4 w;
;           w.x = pack2(silu_f(a[0]) * uu[0], silu_f(a[1]) * uu[1]);
;           w.y = pack2(silu_f(a[2]) * uu[2], silu_f(a[3]) * uu[3]);
;           w.z = pack2(silu_f(a[4]) * uu[4], silu_f(a[5]) * uu[5]);
;           w.w = pack2(silu_f(a[6]) * uu[6], silu_f(a[7]) * uu[7]);
;           *(u32x4*)(H + (size_t)(row0 + 16 * m + fr) * 5632 + col) = w;
	v_mul_f32_e32 v219, 0xbfb8aa3b, v156
	v_exp_f32_e32 v219, v219
	v_mul_f32_e32 v220, 0xbfb8aa3b, v157
	v_exp_f32_e32 v220, v220
	v_mul_f32_e32 v222, 0xbfb8aa3b, v159
	v_add_f32_e32 v219, 1.0, v219
	v_exp_f32_e32 v223, v222
	v_add_f32_e32 v221, 1.0, v220
	v_rcp_f32_e32 v220, v219
	v_mul_f32_e32 v219, 0xbfb8aa3b, v158
	v_exp_f32_e32 v219, v219
	v_rcp_f32_e32 v221, v221
	v_add_f32_e32 v219, 1.0, v219
	v_rcp_f32_e32 v222, v219
	v_add_f32_e32 v219, 1.0, v223
	v_rcp_f32_e32 v223, v219
	v_pk_mul_f32 v[156:157], v[156:157], v[220:221]
	s_nop 0
	v_pk_mul_f32 v[152:153], v[152:153], v[156:157]
	v_pk_mul_f32 v[156:157], v[158:159], v[222:223]
	v_cvt_pk_bf16_f32 v152, v152, v153
	v_mul_f32_e32 v153, 0xbfb8aa3b, v144
	v_pk_mul_f32 v[154:155], v[154:155], v[156:157]
	v_exp_f32_e32 v156, v153
	v_mul_f32_e32 v153, 0xbfb8aa3b, v145
	v_exp_f32_e32 v157, v153
	v_cvt_pk_bf16_f32 v153, v154, v155
	v_add_f32_e32 v154, 1.0, v156
	v_mul_f32_e32 v156, 0xbfb8aa3b, v146
	v_add_f32_e32 v155, 1.0, v157
	v_mul_f32_e32 v157, 0xbfb8aa3b, v147
	v_exp_f32_e32 v156, v156
	v_exp_f32_e32 v157, v157
	v_rcp_f32_e32 v154, v154
	v_rcp_f32_e32 v155, v155
	v_add_f32_e32 v156, 1.0, v156
	v_add_f32_e32 v157, 1.0, v157
	v_rcp_f32_e32 v156, v156
	v_rcp_f32_e32 v157, v157
	v_pk_mul_f32 v[144:145], v[144:145], v[154:155]
	s_nop 0
	v_pk_mul_f32 v[144:145], v[148:149], v[144:145]
	s_nop 0
	v_cvt_pk_bf16_f32 v154, v144, v145
	v_pk_mul_f32 v[144:145], v[146:147], v[156:157]
	s_nop 0
	v_pk_mul_f32 v[144:145], v[150:151], v[144:145]
	s_nop 0
	v_cvt_pk_bf16_f32 v155, v144, v145
	v_mov_b64_e32 v[144:145], s[16:17]
	v_mad_i64_i32 v[144:145], s[14:15], v190, s75, v[144:145]
	v_lshl_add_u64 v[144:145], v[180:181], 1, v[144:145]
	global_store_dwordx4 v[144:145], v[152:155], off

; #define PG8_STAGE(bufoff, gbase, voff) do { _Pragma("unroll") for (int _i = 0; _i < 2; ++_i) \
;     __builtin_amdgcn_global_load_lds((const unsigned*)((const char*)(gbase) + (voff)[_i]), (LAS unsigned*)(lds + (bufoff) + ldsw + _i * 8192), 16, 0, 0); } while (0)
; #define PG8_LDA(dst, b, h) do { _Pragma("unroll") for (int m = 0; m < 4; ++m) _Pragma("unroll") for (int k = 0; k < 2; ++k) dst[m][k] = *(const LAS bf16x8*)(lds + PG8_SA(b, h) + aoff + m * 2048 + k * 1024); } while (0)
; #define PG8_LDB(dst, b, h) do { _Pragma("unroll") for (int n = 0; n < 2; ++n) _Pragma("unroll") for (int k = 0; k < 2; ++k) dst[n][k] = *(const LAS bf16x8*)(lds + PG8_SB(b, h) + boff + n * 2048 + k * 1024); } while (0)
; #define PG8_MMA(ai, bj, At, Bt) do { __builtin_amdgcn_s_setprio(1); _Pragma("unroll") for (int m = 0; m < 4; ++m) _Pragma("unroll") for (int n = 0; n < 2; ++n) _Pragma("unroll") for (int k = 0; k < 2; ++k) \
;     acc[ai][bj][m][n] = __builtin_amdgcn_mfma_f32_16x16x32_bf16(Bt[n][k], At[m][k], acc[ai][bj][m][n], 0, 0, 0); __builtin_amdgcn_s_setprio(0); } while (0)
; #define PG8_WAIT_V(n) asm volatile("s_waitcnt vmcnt(" #n ")" ::: "memory")
; #define PG8_WAIT_L(n) asm volatile("s_waitcnt lgkmcnt(" #n ")" ::: "memory")
; #define PG8_BAR __builtin_amdgcn_s_barrier()
; #define PG8_SCHED __builtin_amdgcn_sched_barrier(0)
; template <class Epi, class Sched = StaticOrder>
; DI void gemm_phase(LAS unsigned char* lds, const Gemm g, const Sched& S, const Epi& E) {
;     ...
;       PG8_LDB(B0, 0, 0); PG8_SCHED; PG8_LDA(At, 0, 0); PG8_STAGE(PG8_SA(1, 1), a1 + hstep, voffA);
;       PG8_WAIT_L(8); PG8_BAR; PG8_WAIT_L(0); PG8_MMA(0, 0, At, B0); PG8_BAR; PG8_SCHED;
;       PG8_LDB(B1, 0, 1); PG8_STAGE(PG8_SB(0, 0), b2, voffB);
;       PG8_BAR; PG8_WAIT_L(0); PG8_MMA(0, 1, At, B1); PG8_BAR;
;       PG8_LDA(At, 0, 1); PG8_STAGE(PG8_SA(0, 0), a2, voffA);
;       PG8_BAR; PG8_WAIT_L(0); PG8_MMA(1, 0, At, B0); PG8_BAR; PG8_SCHED;
;       PG8_STAGE(PG8_SB(0, 1), b2 + hstep, voffB);
;       PG8_WAIT_V(6); PG8_BAR; PG8_MMA(1, 1, At, B1); PG8_BAR;
.LBB0_961:
	s_add_u32 s20, s18, 0xffea0080
	s_addc_u32 s21, s19, -1
	s_cmpk_eq_i32 s44, 0x54
	s_cselect_b32 s23, s5, s21
	s_cselect_b32 s22, s4, s20
	s_cselect_b32 s21, s7, s43
	s_cselect_b32 s20, s6, s42
	v_lshl_add_u64 v[192:193], s[18:19], 0, v[184:185]
	s_add_i32 m0, s31, 0xc000
	ds_read_b128 v[144:147], v215
	ds_read_b128 v[148:151], v215 offset:1024
	ds_read_b128 v[152:155], v215 offset:2048
	ds_read_b128 v[156:159], v215 offset:3072
	ds_read_b128 v[160:163], v215 offset:4096
	ds_read_b128 v[164:167], v215 offset:5120
	ds_read_b128 v[168:171], v215 offset:6144
	ds_read_b128 v[172:175], v215 offset:7168
	global_load_lds_dwordx4 v[192:193], off
	v_lshl_add_u64 v[192:193], s[18:19], 0, v[186:187]
	s_add_i32 m0, s31, 0xe000
	s_nop 0
	global_load_lds_dwordx4 v[192:193], off
	s_waitcnt lgkmcnt(8)
	s_barrier
	s_waitcnt lgkmcnt(0)
	s_setprio 1
	v_mfma_f32_16x16x32_bf16 v[124:127], v[128:131], v[144:147], v[124:127]
	v_mfma_f32_16x16x32_bf16 v[120:123], v[136:139], v[144:147], v[120:123]
	v_mfma_f32_16x16x32_bf16 v[108:111], v[128:131], v[152:155], v[108:111]
	v_mfma_f32_16x16x32_bf16 v[104:107], v[136:139], v[152:155], v[104:107]
	v_mfma_f32_16x16x32_bf16 v[92:95], v[128:131], v[160:163], v[92:95]
	v_mfma_f32_16x16x32_bf16 v[88:91], v[136:139], v[160:163], v[88:91]
	v_mfma_f32_16x16x32_bf16 v[76:79], v[128:131], v[168:171], v[76:79]
	v_mfma_f32_16x16x32_bf16 v[72:75], v[136:139], v[168:171], v[72:75]
	v_mfma_f32_16x16x32_bf16 v[124:127], v[132:135], v[148:151], v[124:127]
	v_mfma_f32_16x16x32_bf16 v[120:123], v[140:143], v[148:151], v[120:123]
	v_mfma_f32_16x16x32_bf16 v[108:111], v[132:135], v[156:159], v[108:111]
	v_mfma_f32_16x16x32_bf16 v[104:107], v[140:143], v[156:159], v[104:107]
	v_mfma_f32_16x16x32_bf16 v[92:95], v[132:135], v[164:167], v[92:95]
	v_mfma_f32_16x16x32_bf16 v[88:91], v[140:143], v[164:167], v[88:91]
	v_mfma_f32_16x16x32_bf16 v[76:79], v[132:135], v[172:175], v[76:79]
	v_mfma_f32_16x16x32_bf16 v[72:75], v[140:143], v[172:175], v[72:75]
	s_barrier
	s_setprio 0
	s_add_i32 s45, s46, s30
	v_lshl_add_u64 v[208:209], s[20:21], 0, v[178:179]
	s_mov_b32 m0, s45
	ds_read_b128 v[192:195], v216
	ds_read_b128 v[196:199], v216 offset:1024
	ds_read_b128 v[200:203], v216 offset:2048
	ds_read_b128 v[204:207], v216 offset:3072
	global_load_lds_dwordx4 v[208:209], off
	v_lshl_add_u64 v[218:219], s[20:21], 0, v[182:183]
	s_add_i32 m0, s45, 0x2000
	s_nop 0
	global_load_lds_dwordx4 v[218:219], off
	s_barrier
	s_waitcnt lgkmcnt(0)
	s_setprio 1
	v_mfma_f32_16x16x32_bf16 v[116:119], v[192:195], v[144:147], v[116:119]
	v_mfma_f32_16x16x32_bf16 v[112:115], v[200:203], v[144:147], v[112:115]
	v_mfma_f32_16x16x32_bf16 v[100:103], v[192:195], v[152:155], v[100:103]
	v_mfma_f32_16x16x32_bf16 v[96:99], v[200:203], v[152:155], v[96:99]
	v_mfma_f32_16x16x32_bf16 v[84:87], v[192:195], v[160:163], v[84:87]
	v_mfma_f32_16x16x32_bf16 v[80:83], v[200:203], v[160:163], v[80:83]
	v_mfma_f32_16x16x32_bf16 v[68:71], v[192:195], v[168:171], v[68:71]
	v_mfma_f32_16x16x32_bf16 v[64:67], v[200:203], v[168:171], v[64:67]
	v_mfma_f32_16x16x32_bf16 v[116:119], v[196:199], v[148:151], v[116:119]
	v_mfma_f32_16x16x32_bf16 v[112:115], v[204:207], v[148:151], v[112:115]
	v_mfma_f32_16x16x32_bf16 v[100:103], v[196:199], v[156:159], v[100:103]
	v_mfma_f32_16x16x32_bf16 v[96:99], v[204:207], v[156:159], v[96:99]
	v_mfma_f32_16x16x32_bf16 v[84:87], v[196:199], v[164:167], v[84:87]
	v_mfma_f32_16x16x32_bf16 v[80:83], v[204:207], v[164:167], v[80:83]
	v_mfma_f32_16x16x32_bf16 v[68:71], v[196:199], v[172:175], v[68:71]
	v_mfma_f32_16x16x32_bf16 v[64:67], v[204:207], v[172:175], v[64:67]
	s_barrier
	s_setprio 0
	s_mov_b32 m0, s31
	v_lshl_add_u64 v[220:221], s[22:23], 0, v[176:177]
	ds_read_b128 v[144:147], v215 offset:16384
	ds_read_b128 v[148:151], v215 offset:17408
	ds_read_b128 v[152:155], v215 offset:18432
	ds_read_b128 v[156:159], v215 offset:19456
	ds_read_b128 v[160:163], v215 offset:20480
	ds_read_b128 v[164:167], v215 offset:21504
	ds_read_b128 v[168:171], v215 offset:22528
	ds_read_b128 v[172:175], v215 offset:23552
	global_load_lds_dwordx4 v[220:221], off
	v_lshl_add_u64 v[222:223], s[22:23], 0, v[180:181]
	s_mov_b32 m0, s33
	s_nop 0
	global_load_lds_dwordx4 v[222:223], off
	s_waitcnt vmcnt(10)
	s_barrier
	s_waitcnt lgkmcnt(0)
	s_setprio 1
	v_mfma_f32_16x16x32_bf16 v[60:63], v[128:131], v[144:147], v[60:63]
	v_mfma_f32_16x16x32_bf16 v[56:59], v[136:139], v[144:147], v[56:59]
	v_mfma_f32_16x16x32_bf16 v[44:47], v[128:131], v[152:155], v[44:47]
	v_mfma_f32_16x16x32_bf16 v[40:43], v[136:139], v[152:155], v[40:43]
	v_mfma_f32_16x16x32_bf16 v[28:31], v[128:131], v[160:163], v[28:31]
	v_mfma_f32_16x16x32_bf16 v[24:27], v[136:139], v[160:163], v[24:27]
	v_mfma_f32_16x16x32_bf16 v[12:15], v[128:131], v[168:171], v[12:15]
	v_mfma_f32_16x16x32_bf16 v[8:11], v[136:139], v[168:171], v[8:11]
	v_mfma_f32_16x16x32_bf16 v[60:63], v[132:135], v[148:151], v[60:63]
	v_mfma_f32_16x16x32_bf16 v[56:59], v[140:143], v[148:151], v[56:59]
	v_mfma_f32_16x16x32_bf16 v[44:47], v[132:135], v[156:159], v[44:47]
	v_mfma_f32_16x16x32_bf16 v[40:43], v[140:143], v[156:159], v[40:43]
	v_mfma_f32_16x16x32_bf16 v[28:31], v[132:135], v[164:167], v[28:31]
	v_mfma_f32_16x16x32_bf16 v[24:27], v[140:143], v[164:167], v[24:27]
	v_mfma_f32_16x16x32_bf16 v[12:15], v[132:135], v[172:175], v[12:15]
	v_mfma_f32_16x16x32_bf16 v[8:11], v[140:143], v[172:175], v[8:11]
	s_barrier
; #define PG8_STAGE(bufoff, gbase, voff) do { _Pragma("unroll") for (int _i = 0; _i < 2; ++_i) \
;     __builtin_amdgcn_global_load_lds((const unsigned*)((const char*)(gbase) + (voff)[_i]), (LAS unsigned*)(lds + (bufoff) + ldsw + _i * 8192), 16, 0, 0); } while (0)
; #define PG8_LDA(dst, b, h) do { _Pragma("unroll") for (int m = 0; m < 4; ++m) _Pragma("unroll") for (int k = 0; k < 2; ++k) dst[m][k] = *(const LAS bf16x8*)(lds + PG8_SA(b, h) + aoff + m * 2048 + k * 1024); } while (0)
; #define PG8_LDB(dst, b, h) do { _Pragma("unroll") for (int n = 0; n < 2; ++n) _Pragma("unroll") for (int k = 0; k < 2; ++k) dst[n][k] = *(const LAS bf16x8*)(lds + PG8_SB(b, h) + boff + n * 2048 + k * 1024); } while (0)
; #define PG8_MMA(ai, bj, At, Bt) do { __builtin_amdgcn_s_setprio(1); _Pragma("unroll") for (int m = 0; m < 4; ++m) _Pragma("unroll") for (int n = 0; n < 2; ++n) _Pragma("unroll") for (int k = 0; k < 2; ++k) \
;     acc[ai][bj][m][n] = __builtin_amdgcn_mfma_f32_16x16x32_bf16(Bt[n][k], At[m][k], acc[ai][bj][m][n], 0, 0, 0); __builtin_amdgcn_s_setprio(0); } while (0)
; #define PG8_WAIT_V(n) asm volatile("s_waitcnt vmcnt(" #n ")" ::: "memory")
; #define PG8_WAIT_L(n) asm volatile("s_waitcnt lgkmcnt(" #n ")" ::: "memory")
; #define PG8_BAR __builtin_amdgcn_s_barrier()
; #define PG8_SCHED __builtin_amdgcn_sched_barrier(0)
; template <class Epi, class Sched = StaticOrder>
; DI void gemm_phase(LAS unsigned char* lds, const Gemm g, const Sched& S, const Epi& E) {
;     ...
;       PG8_WAIT_V(6); PG8_BAR; PG8_MMA(1, 1, At, B1); PG8_BAR;
;       PG8_LDB(B0, 1, 0); PG8_SCHED; PG8_LDA(At, 1, 0); PG8_STAGE(PG8_SA(0, 1), a2 + hstep, voffA);
;       PG8_WAIT_L(8); PG8_BAR; PG8_WAIT_L(0); PG8_MMA(0, 0, At, B0); PG8_BAR; PG8_SCHED;
;       PG8_LDB(B1, 1, 1); PG8_STAGE(PG8_SB(1, 0), b3, voffB);
;       PG8_BAR; PG8_WAIT_L(0); PG8_MMA(0, 1, At, B1); PG8_BAR;
;       PG8_LDA(At, 1, 1); PG8_STAGE(PG8_SA(1, 0), a3, voffA);
	s_setprio 0
	s_add_u32 s52, s20, 0x160000
	s_addc_u32 s53, s21, 0
	s_add_i32 s45, s47, s30
	v_lshl_add_u64 v[128:129], s[52:53], 0, v[178:179]
	s_mov_b32 m0, s45
	s_nop 0
	global_load_lds_dwordx4 v[128:129], off
	v_lshl_add_u64 v[128:129], s[52:53], 0, v[182:183]
	s_add_i32 m0, s45, 0x2000
	s_nop 0
	global_load_lds_dwordx4 v[128:129], off
	s_add_i32 s45, 0, 0x18000
	v_add_u32_e32 v140, s45, v212
	ds_read_b128 v[128:131], v140
	ds_read_b128 v[132:135], v140 offset:1024
	ds_read_b128 v[136:139], v140 offset:2048
	ds_read_b128 v[140:143], v140 offset:3072
	s_waitcnt vmcnt(6)
	s_barrier
	s_setprio 1
	v_mfma_f32_16x16x32_bf16 v[52:55], v[192:195], v[144:147], v[52:55]
	v_mfma_f32_16x16x32_bf16 v[48:51], v[200:203], v[144:147], v[48:51]
	v_mfma_f32_16x16x32_bf16 v[36:39], v[192:195], v[152:155], v[36:39]
	v_mfma_f32_16x16x32_bf16 v[32:35], v[200:203], v[152:155], v[32:35]
	v_mfma_f32_16x16x32_bf16 v[20:23], v[192:195], v[160:163], v[20:23]
	v_mfma_f32_16x16x32_bf16 v[16:19], v[200:203], v[160:163], v[16:19]
	v_mfma_f32_16x16x32_bf16 v[4:7], v[192:195], v[168:171], v[4:7]
	v_mfma_f32_16x16x32_bf16 v[0:3], v[200:203], v[168:171], v[0:3]
	v_mfma_f32_16x16x32_bf16 v[52:55], v[196:199], v[148:151], v[52:55]
	v_mfma_f32_16x16x32_bf16 v[48:51], v[204:207], v[148:151], v[48:51]
	v_mfma_f32_16x16x32_bf16 v[36:39], v[196:199], v[156:159], v[36:39]
	v_mfma_f32_16x16x32_bf16 v[32:35], v[204:207], v[156:159], v[32:35]
	v_mfma_f32_16x16x32_bf16 v[20:23], v[196:199], v[164:167], v[20:23]
	v_mfma_f32_16x16x32_bf16 v[16:19], v[204:207], v[164:167], v[16:19]
	v_mfma_f32_16x16x32_bf16 v[4:7], v[196:199], v[172:175], v[4:7]
	v_mfma_f32_16x16x32_bf16 v[0:3], v[204:207], v[172:175], v[0:3]
	s_barrier
	s_setprio 0
	s_add_u32 s22, s22, 0x160000
	s_addc_u32 s23, s23, 0
	s_mov_b32 m0, s34
	v_lshl_add_u64 v[192:193], s[22:23], 0, v[176:177]
	ds_read_b128 v[144:147], v215 offset:32768
	ds_read_b128 v[148:151], v215 offset:33792
	ds_read_b128 v[152:155], v215 offset:34816
	ds_read_b128 v[156:159], v215 offset:35840
	ds_read_b128 v[160:163], v215 offset:36864
	ds_read_b128 v[164:167], v215 offset:37888
	ds_read_b128 v[168:171], v215 offset:38912
	ds_read_b128 v[172:175], v215 offset:39936
	global_load_lds_dwordx4 v[192:193], off
	v_lshl_add_u64 v[192:193], s[22:23], 0, v[180:181]
	s_mov_b32 m0, s35
	s_nop 0
	global_load_lds_dwordx4 v[192:193], off
	s_waitcnt lgkmcnt(8)
	s_barrier
	s_waitcnt lgkmcnt(0)
	s_setprio 1
	v_mfma_f32_16x16x32_bf16 v[124:127], v[128:131], v[144:147], v[124:127]
	v_mfma_f32_16x16x32_bf16 v[120:123], v[136:139], v[144:147], v[120:123]
	v_mfma_f32_16x16x32_bf16 v[108:111], v[128:131], v[152:155], v[108:111]
	v_mfma_f32_16x16x32_bf16 v[104:107], v[136:139], v[152:155], v[104:107]
	v_mfma_f32_16x16x32_bf16 v[92:95], v[128:131], v[160:163], v[92:95]
	v_mfma_f32_16x16x32_bf16 v[88:91], v[136:139], v[160:163], v[88:91]
	v_mfma_f32_16x16x32_bf16 v[76:79], v[128:131], v[168:171], v[76:79]
	v_mfma_f32_16x16x32_bf16 v[72:75], v[136:139], v[168:171], v[72:75]
	v_mfma_f32_16x16x32_bf16 v[124:127], v[132:135], v[148:151], v[124:127]
	v_mfma_f32_16x16x32_bf16 v[120:123], v[140:143], v[148:151], v[120:123]
	v_mfma_f32_16x16x32_bf16 v[108:111], v[132:135], v[156:159], v[108:111]
	v_mfma_f32_16x16x32_bf16 v[104:107], v[140:143], v[156:159], v[104:107]
	v_mfma_f32_16x16x32_bf16 v[92:95], v[132:135], v[164:167], v[92:95]
	v_mfma_f32_16x16x32_bf16 v[88:91], v[140:143], v[164:167], v[88:91]
	v_mfma_f32_16x16x32_bf16 v[76:79], v[132:135], v[172:175], v[76:79]
	v_mfma_f32_16x16x32_bf16 v[72:75], v[140:143], v[172:175], v[72:75]
	s_barrier
	s_setprio 0
	s_add_i32 s22, 0, 0x1c000
	s_add_i32 s23, s45, s30
	v_add_u32_e32 v204, s22, v212
	v_lshl_add_u64 v[208:209], v[208:209], 0, s[16:17]
	s_mov_b32 m0, s23
	ds_read_b128 v[192:195], v204
	ds_read_b128 v[196:199], v204 offset:1024
	ds_read_b128 v[200:203], v204 offset:2048
	ds_read_b128 v[204:207], v204 offset:3072
	global_load_lds_dwordx4 v[208:209], off
	v_lshl_add_u64 v[208:209], v[218:219], 0, s[16:17]
	s_add_i32 m0, s23, 0x2000
	s_nop 0
	global_load_lds_dwordx4 v[208:209], off
	s_barrier
	s_waitcnt lgkmcnt(0)
	s_setprio 1
	v_mfma_f32_16x16x32_bf16 v[116:119], v[192:195], v[144:147], v[116:119]
	v_mfma_f32_16x16x32_bf16 v[112:115], v[200:203], v[144:147], v[112:115]
	v_mfma_f32_16x16x32_bf16 v[100:103], v[192:195], v[152:155], v[100:103]
	v_mfma_f32_16x16x32_bf16 v[96:99], v[200:203], v[152:155], v[96:99]
	v_mfma_f32_16x16x32_bf16 v[84:87], v[192:195], v[160:163], v[84:87]
	v_mfma_f32_16x16x32_bf16 v[80:83], v[200:203], v[160:163], v[80:83]
	v_mfma_f32_16x16x32_bf16 v[68:71], v[192:195], v[168:171], v[68:71]
	v_mfma_f32_16x16x32_bf16 v[64:67], v[200:203], v[168:171], v[64:67]
	v_mfma_f32_16x16x32_bf16 v[116:119], v[196:199], v[148:151], v[116:119]
	v_mfma_f32_16x16x32_bf16 v[112:115], v[204:207], v[148:151], v[112:115]
	v_mfma_f32_16x16x32_bf16 v[100:103], v[196:199], v[156:159], v[100:103]
	v_mfma_f32_16x16x32_bf16 v[96:99], v[204:207], v[156:159], v[96:99]
	v_mfma_f32_16x16x32_bf16 v[84:87], v[196:199], v[164:167], v[84:87]
	v_mfma_f32_16x16x32_bf16 v[80:83], v[204:207], v[164:167], v[80:83]
	v_mfma_f32_16x16x32_bf16 v[68:71], v[196:199], v[172:175], v[68:71]
	v_mfma_f32_16x16x32_bf16 v[64:67], v[204:207], v[172:175], v[64:67]
	s_barrier
	s_setprio 0
	s_mov_b32 m0, s37
	v_lshl_add_u64 v[208:209], v[220:221], 0, s[16:17]
	ds_read_b128 v[144:147], v215 offset:49152
	ds_read_b128 v[148:151], v215 offset:50176
	ds_read_b128 v[152:155], v215 offset:51200
	ds_read_b128 v[156:159], v215 offset:52224
	ds_read_b128 v[160:163], v215 offset:53248
	ds_read_b128 v[164:167], v215 offset:54272
	ds_read_b128 v[168:171], v215 offset:55296
	ds_read_b128 v[172:175], v215 offset:56320
	global_load_lds_dwordx4 v[208:209], off
	v_lshl_add_u64 v[208:209], v[222:223], 0, s[16:17]
	s_mov_b32 m0, s38
	s_nop 0
	global_load_lds_dwordx4 v[208:209], off
	s_waitcnt vmcnt(10)
	s_barrier
; #define PG8_STAGE(bufoff, gbase, voff) do { _Pragma("unroll") for (int _i = 0; _i < 2; ++_i) \
;     __builtin_amdgcn_global_load_lds((const unsigned*)((const char*)(gbase) + (voff)[_i]), (LAS unsigned*)(lds + (bufoff) + ldsw + _i * 8192), 16, 0, 0); } while (0)
; #define PG8_LDA(dst, b, h) do { _Pragma("unroll") for (int m = 0; m < 4; ++m) _Pragma("unroll") for (int k = 0; k < 2; ++k) dst[m][k] = *(const LAS bf16x8*)(lds + PG8_SA(b, h) + aoff + m * 2048 + k * 1024); } while (0)
; #define PG8_MMA(ai, bj, At, Bt) do { __builtin_amdgcn_s_setprio(1); _Pragma("unroll") for (int m = 0; m < 4; ++m) _Pragma("unroll") for (int n = 0; n < 2; ++n) _Pragma("unroll") for (int k = 0; k < 2; ++k) \
;     acc[ai][bj][m][n] = __builtin_amdgcn_mfma_f32_16x16x32_bf16(Bt[n][k], At[m][k], acc[ai][bj][m][n], 0, 0, 0); __builtin_amdgcn_s_setprio(0); } while (0)
; #define PG8_WAIT_V(n) asm volatile("s_waitcnt vmcnt(" #n ")" ::: "memory")
; #define PG8_WAIT_L(n) asm volatile("s_waitcnt lgkmcnt(" #n ")" ::: "memory")
; #define PG8_BAR __builtin_amdgcn_s_barrier()
; #define PG8_SCHED __builtin_amdgcn_sched_barrier(0)
; template <class Epi, class Sched = StaticOrder>
; DI void gemm_phase(LAS unsigned char* lds, const Gemm g, const Sched& S, const Epi& E) {
;     ...
;       PG8_LDA(At, 1, 1); PG8_STAGE(PG8_SA(1, 0), a3, voffA);
;       PG8_BAR; PG8_WAIT_L(0); PG8_MMA(1, 0, At, B0); PG8_BAR; PG8_SCHED;
;       PG8_STAGE(PG8_SB(1, 1), b3 + hstep, voffB);
;       PG8_WAIT_V(6); PG8_BAR; PG8_MMA(1, 1, At, B1); PG8_BAR;
	s_waitcnt lgkmcnt(0)
	s_setprio 1
	v_mfma_f32_16x16x32_bf16 v[60:63], v[128:131], v[144:147], v[60:63]
	v_mfma_f32_16x16x32_bf16 v[56:59], v[136:139], v[144:147], v[56:59]
	v_mfma_f32_16x16x32_bf16 v[44:47], v[128:131], v[152:155], v[44:47]
	v_mfma_f32_16x16x32_bf16 v[40:43], v[136:139], v[152:155], v[40:43]
	v_mfma_f32_16x16x32_bf16 v[28:31], v[128:131], v[160:163], v[28:31]
	v_mfma_f32_16x16x32_bf16 v[24:27], v[136:139], v[160:163], v[24:27]
	v_mfma_f32_16x16x32_bf16 v[12:15], v[128:131], v[168:171], v[12:15]
	v_mfma_f32_16x16x32_bf16 v[8:11], v[136:139], v[168:171], v[8:11]
	v_mfma_f32_16x16x32_bf16 v[60:63], v[132:135], v[148:151], v[60:63]
	v_mfma_f32_16x16x32_bf16 v[56:59], v[140:143], v[148:151], v[56:59]
	v_mfma_f32_16x16x32_bf16 v[44:47], v[132:135], v[156:159], v[44:47]
	v_mfma_f32_16x16x32_bf16 v[40:43], v[140:143], v[156:159], v[40:43]
	v_mfma_f32_16x16x32_bf16 v[28:31], v[132:135], v[164:167], v[28:31]
	v_mfma_f32_16x16x32_bf16 v[24:27], v[140:143], v[164:167], v[24:27]
	v_mfma_f32_16x16x32_bf16 v[12:15], v[132:135], v[172:175], v[12:15]
	v_mfma_f32_16x16x32_bf16 v[8:11], v[140:143], v[172:175], v[8:11]
	s_barrier
	s_setprio 0
	s_add_u32 s20, s20, 0x160080
	s_addc_u32 s21, s21, 0
	s_add_i32 s22, s22, s30
	v_lshl_add_u64 v[128:129], s[20:21], 0, v[178:179]
	s_mov_b32 m0, s22
	s_nop 0
	global_load_lds_dwordx4 v[128:129], off
	v_lshl_add_u64 v[128:129], s[20:21], 0, v[182:183]
	s_add_i32 m0, s22, 0x2000
	s_nop 0
	global_load_lds_dwordx4 v[128:129], off
	ds_read_b128 v[128:131], v214
	ds_read_b128 v[132:135], v214 offset:1024
	ds_read_b128 v[136:139], v214 offset:2048
	ds_read_b128 v[140:143], v214 offset:3072
	s_waitcnt vmcnt(6)
	s_barrier
	s_setprio 1
	v_mfma_f32_16x16x32_bf16 v[52:55], v[192:195], v[144:147], v[52:55]
	v_mfma_f32_16x16x32_bf16 v[48:51], v[200:203], v[144:147], v[48:51]
	v_mfma_f32_16x16x32_bf16 v[36:39], v[192:195], v[152:155], v[36:39]
	v_mfma_f32_16x16x32_bf16 v[32:35], v[200:203], v[152:155], v[32:35]
	v_mfma_f32_16x16x32_bf16 v[20:23], v[192:195], v[160:163], v[20:23]
	v_mfma_f32_16x16x32_bf16 v[16:19], v[200:203], v[160:163], v[16:19]
	v_mfma_f32_16x16x32_bf16 v[4:7], v[192:195], v[168:171], v[4:7]
	v_mfma_f32_16x16x32_bf16 v[0:3], v[200:203], v[168:171], v[0:3]
	v_mfma_f32_16x16x32_bf16 v[52:55], v[196:199], v[148:151], v[52:55]
	v_mfma_f32_16x16x32_bf16 v[48:51], v[204:207], v[148:151], v[48:51]
	v_mfma_f32_16x16x32_bf16 v[36:39], v[196:199], v[156:159], v[36:39]
	v_mfma_f32_16x16x32_bf16 v[32:35], v[204:207], v[156:159], v[32:35]
	v_mfma_f32_16x16x32_bf16 v[20:23], v[196:199], v[164:167], v[20:23]
	v_mfma_f32_16x16x32_bf16 v[16:19], v[204:207], v[164:167], v[16:19]
	v_mfma_f32_16x16x32_bf16 v[4:7], v[196:199], v[172:175], v[4:7]
	v_mfma_f32_16x16x32_bf16 v[0:3], v[204:207], v[172:175], v[0:3]
	s_add_i32 s44, s44, 2
	s_add_u32 s18, s18, 0x100
	s_addc_u32 s19, s19, 0
	s_add_u32 s42, s42, 0x100
	s_addc_u32 s43, s43, 0
	s_cmpk_gt_u32 s44, 0x55
	s_barrier
	s_setprio 0
	s_cbranch_scc0 .LBB0_961
; DI unsigned pack2(float lo, float hi) { f32x2 v = {lo, hi}; bf16v2 r = __builtin_convertvector(v, bf16v2); return __builtin_bit_cast(unsigned, r); }
;   DI void operator()(const f32x4 (&acc)[2][2][4][2], const Unit& u, int wr, int wc, int fr, int fq) const {
;     const int row0 = u.pm * BM + wr * 64 + fr, col0 = u.pn * BM + wc * 32 + 8 * fq;
; #pragma unroll
;     for (int ai = 0; ai < 2; ++ai) {
;       f32x4 bv[4][2][2];
; #pragma unroll
;       for (int m = 0; m < 4; ++m)
; #pragma unroll
;         for (int bj = 0; bj < 2; ++bj) {
;           const float* bp = base + (size_t)(row0 + ai * HALF + m * 16) * 2048 + col0 + bj * HALF;
;           bv[m][bj][0] = *(const f32x4*)bp; bv[m][bj][1] = *(const f32x4*)(bp + 4);
;         }
; #pragma unroll
;       for (int m = 0; m < 4; ++m) {
;         const int row = row0 + ai * HALF + m * 16;
;         const size_t off = (size_t)row * 2048 + col0;
;         float ss = 0.f;
; #pragma unroll
;         for (int bj = 0; bj < 2; ++bj) {
;           const f32x4 v0 = acc[ai][bj][m][0] + bv[m][bj][0], v1 = acc[ai][bj][m][1] + bv[m][bj][1];
;           *(f32x4*)(C + off + bj * HALF) = v0; *(f32x4*)(C + off + bj * HALF + 4) = v1;
;           if (xb) {
;             u32x4 w; w.x = pack2(v0[0], v0[1]); w.y = pack2(v0[2], v0[3]); w.z = pack2(v1[0], v1[1]); w.w = pack2(v1[2], v1[3]);
;             *(u32x4*)(xb + off + bj * HALF) = w;
;             ss += v0[0] * v0[0] + v0[1] * v0[1] + v0[2] * v0[2] + v0[3] * v0[3] + v1[0] * v1[0] + v1[1] * v1[1] + v1[2] * v1[2] + v1[3] * v1[3];
;           }
;         }
;         if (xb) {
;           ss += __shfl_xor(ss, 16); ss += __shfl_xor(ss, 32);
;           if (fq == 0) ssq[(size_t)row * 32 + u.pn * 4 + wc] = ss;
;         }
	s_waitcnt lgkmcnt(0)
	v_lshl_add_u32 v194, s51, 8, v211
	v_lshl_or_b32 v192, s2, 8, v213
	v_readlane_b32 s52, v243, 3
	v_ashrrev_i32_e32 v193, 31, v192
	v_readlane_b32 s66, v243, 17
	v_readlane_b32 s67, v243, 18
	v_ashrrev_i32_e32 v195, 31, v194
	v_lshlrev_b64 v[128:129], 13, v[194:195]
	v_lshl_add_u64 v[196:197], v[192:193], 2, s[66:67]
	v_lshl_add_u64 v[236:237], v[196:197], 0, v[128:129]
	global_load_dwordx4 v[220:223], v[236:237], off
	global_load_dwordx4 v[224:227], v[236:237], off offset:16
	global_load_dwordx4 v[228:231], v[236:237], off offset:512
	global_load_dwordx4 v[232:235], v[236:237], off offset:528
	v_or_b32_e32 v206, 16, v194
	v_or_b32_e32 v202, 32, v194
	v_or_b32_e32 v198, 48, v194
	v_ashrrev_i32_e32 v207, 31, v206
	v_ashrrev_i32_e32 v203, 31, v202
	v_ashrrev_i32_e32 v199, 31, v198
	v_lshlrev_b64 v[128:129], 13, v[206:207]
	v_lshlrev_b64 v[130:131], 13, v[202:203]
	v_lshlrev_b64 v[132:133], 13, v[198:199]
	v_lshl_add_u64 v[208:209], v[196:197], 0, v[128:129]
	v_lshl_add_u64 v[204:205], v[196:197], 0, v[130:131]
	v_lshl_add_u64 v[200:201], v[196:197], 0, v[132:133]
	global_load_dwordx4 v[168:171], v[208:209], off offset:16
	global_load_dwordx4 v[172:175], v[208:209], off
	global_load_dwordx4 v[160:163], v[208:209], off offset:528
	global_load_dwordx4 v[164:167], v[208:209], off offset:512
	global_load_dwordx4 v[152:155], v[204:205], off offset:16
	global_load_dwordx4 v[156:159], v[204:205], off
	global_load_dwordx4 v[144:147], v[204:205], off offset:528
	global_load_dwordx4 v[148:151], v[204:205], off offset:512
	global_load_dwordx4 v[136:139], v[200:201], off offset:16
	global_load_dwordx4 v[140:143], v[200:201], off
	global_load_dwordx4 v[128:131], v[200:201], off offset:528
	global_load_dwordx4 v[132:135], v[200:201], off offset:512
	v_and_b32_e32 v218, 64, v217
	v_xor_b32_e32 v238, 16, v217
	v_add_u32_e32 v240, 64, v218
	v_xor_b32_e32 v239, 32, v217
	v_cmp_lt_i32_e32 vcc, v238, v240
	v_lshlrev_b64 v[218:219], 11, v[194:195]
	s_lshl_b32 s18, s2, 2
	v_cndmask_b32_e32 v241, v217, v238, vcc
	v_cmp_lt_i32_e32 vcc, v239, v240
	s_ashr_i32 s19, s18, 31
	v_readlane_b32 s53, v243, 4
	v_cndmask_b32_e32 v240, v217, v239, vcc
	v_lshl_add_u64 v[238:239], v[218:219], 0, v[192:193]
	v_lshlrev_b32_e32 v218, 2, v241
	v_lshl_add_u64 v[238:239], v[238:239], 1, s[12:13]
	v_readlane_b32 s54, v243, 5
	v_readlane_b32 s55, v243, 6
	v_readlane_b32 s56, v243, 7
	v_readlane_b32 s57, v243, 8
	v_readlane_b32 s58, v243, 9
	v_readlane_b32 s59, v243, 10
	v_readlane_b32 s60, v243, 11
	v_readlane_b32 s61, v243, 12
	v_readlane_b32 s62, v243, 13
	v_readlane_b32 s63, v243, 14
	v_readlane_b32 s64, v243, 15
	v_readlane_b32 s65, v243, 16
	s_waitcnt vmcnt(0)
	v_pk_add_f32 v[126:127], v[126:127], v[222:223]
	v_pk_add_f32 v[124:125], v[124:125], v[220:221]
	v_pk_add_f32 v[116:117], v[116:117], v[228:229]
	v_pk_add_f32 v[122:123], v[122:123], v[226:227]
	v_pk_add_f32 v[120:121], v[120:121], v[224:225]
	v_pk_add_f32 v[220:221], v[112:113], v[232:233]
	global_store_dwordx4 v[236:237], v[124:127], off
	global_store_dwordx4 v[236:237], v[120:123], off offset:16
	v_cvt_pk_bf16_f32 v112, v124, v125
	v_mul_f32_e32 v125, v125, v125
	v_mul_f32_e32 v219, v117, v117
	v_pk_add_f32 v[118:119], v[118:119], v[230:231]
	v_fmac_f32_e32 v125, v124, v124
	v_fmac_f32_e32 v219, v116, v116
	v_fmac_f32_e32 v125, v126, v126
	v_fmac_f32_e32 v219, v118, v118
	v_fmac_f32_e32 v125, v127, v127
	v_fmac_f32_e32 v219, v119, v119
	v_fmac_f32_e32 v125, v120, v120
	v_fmac_f32_e32 v219, v220, v220
	v_pk_add_f32 v[222:223], v[114:115], v[234:235]
	v_fmac_f32_e32 v125, v121, v121
	v_fmac_f32_e32 v219, v221, v221
	v_fmac_f32_e32 v125, v122, v122
	v_fmac_f32_e32 v219, v222, v222
	v_fmac_f32_e32 v125, v123, v123
	v_fmac_f32_e32 v219, v223, v223
	v_cvt_pk_bf16_f32 v114, v120, v121
	v_add_f32_e32 v121, v125, v219
	v_cvt_pk_bf16_f32 v115, v122, v123
	ds_bpermute_b32 v122, v218, v121
	v_cvt_pk_bf16_f32 v113, v126, v127
	global_store_dwordx4 v[238:239], v[112:115], off
	global_store_dwordx4 v[236:237], v[116:119], off offset:512
	global_store_dwordx4 v[236:237], v[220:223], off offset:528
	v_lshlrev_b32_e32 v126, 2, v240
	v_cvt_pk_bf16_f32 v120, v116, v117
	s_waitcnt lgkmcnt(0)
	v_add_f32_e32 v112, v121, v122
	ds_bpermute_b32 v113, v126, v112
	v_cvt_pk_bf16_f32 v121, v118, v119
	v_cvt_pk_bf16_f32 v122, v220, v221
	v_cvt_pk_bf16_f32 v123, v222, v223
	global_store_dwordx4 v[238:239], v[120:123], off offset:256
	s_and_saveexec_b64 s[20:21], s[0:1]
	s_cbranch_execz .LBB0_964
	s_waitcnt lgkmcnt(0)
	v_add_f32_e32 v114, v112, v113
	v_lshlrev_b64 v[112:113], 7, v[194:195]
	v_lshl_add_u64 v[112:113], s[14:15], 0, v[112:113]
	v_lshl_add_u64 v[112:113], s[18:19], 2, v[112:113]
	s_lshl_b32 s2, s36, 2
	v_lshl_add_u64 v[112:113], v[112:113], 0, s[2:3]
	global_store_dword v[112:113], v114, off

; #define PG8_STAGE(bufoff, gbase, voff) do { _Pragma("unroll") for (int _i = 0; _i < 2; ++_i) \
;     __builtin_amdgcn_global_load_lds((const unsigned*)((const char*)(gbase) + (voff)[_i]), (LAS unsigned*)(lds + (bufoff) + ldsw + _i * 8192), 16, 0, 0); } while (0)
; #define PG8_LDA(dst, b, h) do { _Pragma("unroll") for (int m = 0; m < 4; ++m) _Pragma("unroll") for (int k = 0; k < 2; ++k) dst[m][k] = *(const LAS bf16x8*)(lds + PG8_SA(b, h) + aoff + m * 2048 + k * 1024); } while (0)
; #define PG8_LDB(dst, b, h) do { _Pragma("unroll") for (int n = 0; n < 2; ++n) _Pragma("unroll") for (int k = 0; k < 2; ++k) dst[n][k] = *(const LAS bf16x8*)(lds + PG8_SB(b, h) + boff + n * 2048 + k * 1024); } while (0)
; #define PG8_MMA(ai, bj, At, Bt) do { __builtin_amdgcn_s_setprio(1); _Pragma("unroll") for (int m = 0; m < 4; ++m) _Pragma("unroll") for (int n = 0; n < 2; ++n) _Pragma("unroll") for (int k = 0; k < 2; ++k) \
;     acc[ai][bj][m][n] = __builtin_amdgcn_mfma_f32_16x16x32_bf16(Bt[n][k], At[m][k], acc[ai][bj][m][n], 0, 0, 0); __builtin_amdgcn_s_setprio(0); } while (0)
; #define PG8_WAIT_V(n) asm volatile("s_waitcnt vmcnt(" #n ")" ::: "memory")
; #define PG8_WAIT_L(n) asm volatile("s_waitcnt lgkmcnt(" #n ")" ::: "memory")
; #define PG8_BAR __builtin_amdgcn_s_barrier()
; #define PG8_SCHED __builtin_amdgcn_sched_barrier(0)
; template <class Epi, class Sched = StaticOrder>
; DI void gemm_phase(LAS unsigned char* lds, const Gemm g, const Sched& S, const Epi& E) {
;     ...
;       PG8_LDB(B0, 0, 0); PG8_SCHED; PG8_LDA(At, 0, 0); PG8_STAGE(PG8_SA(1, 1), a1 + hstep, voffA);
;       PG8_WAIT_L(8); PG8_BAR; PG8_WAIT_L(0); PG8_MMA(0, 0, At, B0); PG8_BAR; PG8_SCHED;
;       PG8_LDB(B1, 0, 1); PG8_STAGE(PG8_SB(0, 0), b2, voffB);
;       PG8_BAR; PG8_WAIT_L(0); PG8_MMA(0, 1, At, B1); PG8_BAR;
;       PG8_LDA(At, 0, 1); PG8_STAGE(PG8_SA(0, 0), a2, voffA);
;       PG8_BAR; PG8_WAIT_L(0); PG8_MMA(1, 0, At, B0); PG8_BAR; PG8_SCHED;
;       PG8_STAGE(PG8_SB(0, 1), b2 + hstep, voffB);
;       PG8_WAIT_V(6); PG8_BAR; PG8_MMA(1, 1, At, B1); PG8_BAR;
.LBB0_1052:
	s_add_u32 s12, s10, 0xfff80080
	s_addc_u32 s13, s11, -1
	s_cmp_eq_u32 s52, 28
	s_cselect_b32 s65, s41, s13
	s_cselect_b32 s64, s42, s12
	s_cselect_b32 s13, s43, s49
	s_cselect_b32 s12, s44, s45
	v_lshl_add_u64 v[194:195], s[10:11], 0, v[172:173]
	s_add_i32 m0, s61, 0xc000
	ds_read_b128 v[144:147], v204
	ds_read_b128 v[148:151], v204 offset:1024
	ds_read_b128 v[152:155], v204 offset:2048
	ds_read_b128 v[156:159], v204 offset:3072
	ds_read_b128 v[178:181], v204 offset:4096
	ds_read_b128 v[182:185], v204 offset:5120
	ds_read_b128 v[186:189], v204 offset:6144
	ds_read_b128 v[190:193], v204 offset:7168
	global_load_lds_dwordx4 v[194:195], off
	v_lshl_add_u64 v[194:195], s[10:11], 0, v[174:175]
	s_add_i32 m0, s61, 0xe000
	s_nop 0
	global_load_lds_dwordx4 v[194:195], off
	s_waitcnt lgkmcnt(8)
	s_barrier
	s_waitcnt lgkmcnt(0)
	s_setprio 1
	v_mfma_f32_16x16x32_bf16 v[124:127], v[128:131], v[144:147], v[124:127]
	v_mfma_f32_16x16x32_bf16 v[120:123], v[136:139], v[144:147], v[120:123]
	v_mfma_f32_16x16x32_bf16 v[116:119], v[128:131], v[152:155], v[116:119]
	v_mfma_f32_16x16x32_bf16 v[104:107], v[136:139], v[152:155], v[104:107]
	v_mfma_f32_16x16x32_bf16 v[92:95], v[128:131], v[178:181], v[92:95]
	v_mfma_f32_16x16x32_bf16 v[88:91], v[136:139], v[178:181], v[88:91]
	v_mfma_f32_16x16x32_bf16 v[84:87], v[128:131], v[186:189], v[84:87]
	v_mfma_f32_16x16x32_bf16 v[72:75], v[136:139], v[186:189], v[72:75]
	v_mfma_f32_16x16x32_bf16 v[124:127], v[132:135], v[148:151], v[124:127]
	v_mfma_f32_16x16x32_bf16 v[120:123], v[140:143], v[148:151], v[120:123]
	v_mfma_f32_16x16x32_bf16 v[116:119], v[132:135], v[156:159], v[116:119]
	v_mfma_f32_16x16x32_bf16 v[104:107], v[140:143], v[156:159], v[104:107]
	v_mfma_f32_16x16x32_bf16 v[92:95], v[132:135], v[182:185], v[92:95]
	v_mfma_f32_16x16x32_bf16 v[88:91], v[140:143], v[182:185], v[88:91]
	v_mfma_f32_16x16x32_bf16 v[84:87], v[132:135], v[190:193], v[84:87]
	v_mfma_f32_16x16x32_bf16 v[72:75], v[140:143], v[190:193], v[72:75]
	s_barrier
	s_setprio 0
	s_add_i32 s53, s80, s70
	v_lshl_add_u64 v[208:209], s[12:13], 0, v[162:163]
	s_mov_b32 m0, s53
	ds_read_b128 v[194:197], v205
	ds_read_b128 v[212:215], v205 offset:1024
	ds_read_b128 v[216:219], v205 offset:2048
	ds_read_b128 v[220:223], v205 offset:3072
	global_load_lds_dwordx4 v[208:209], off
	v_lshl_add_u64 v[224:225], s[12:13], 0, v[166:167]
	s_add_i32 m0, s53, 0x2000
	s_nop 0
	global_load_lds_dwordx4 v[224:225], off
	s_barrier
	s_waitcnt lgkmcnt(0)
	s_setprio 1
	v_mfma_f32_16x16x32_bf16 v[112:115], v[194:197], v[144:147], v[112:115]
	v_mfma_f32_16x16x32_bf16 v[108:111], v[216:219], v[144:147], v[108:111]
	v_mfma_f32_16x16x32_bf16 v[100:103], v[194:197], v[152:155], v[100:103]
	v_mfma_f32_16x16x32_bf16 v[96:99], v[216:219], v[152:155], v[96:99]
	v_mfma_f32_16x16x32_bf16 v[80:83], v[194:197], v[178:181], v[80:83]
	v_mfma_f32_16x16x32_bf16 v[76:79], v[216:219], v[178:181], v[76:79]
	v_mfma_f32_16x16x32_bf16 v[68:71], v[194:197], v[186:189], v[68:71]
	v_mfma_f32_16x16x32_bf16 v[64:67], v[216:219], v[186:189], v[64:67]
	v_mfma_f32_16x16x32_bf16 v[112:115], v[212:215], v[148:151], v[112:115]
	v_mfma_f32_16x16x32_bf16 v[108:111], v[220:223], v[148:151], v[108:111]
	v_mfma_f32_16x16x32_bf16 v[100:103], v[212:215], v[156:159], v[100:103]
	v_mfma_f32_16x16x32_bf16 v[96:99], v[220:223], v[156:159], v[96:99]
	v_mfma_f32_16x16x32_bf16 v[80:83], v[212:215], v[182:185], v[80:83]
	v_mfma_f32_16x16x32_bf16 v[76:79], v[220:223], v[182:185], v[76:79]
	v_mfma_f32_16x16x32_bf16 v[68:71], v[212:215], v[190:193], v[68:71]
	v_mfma_f32_16x16x32_bf16 v[64:67], v[220:223], v[190:193], v[64:67]
	s_barrier
	s_setprio 0
	s_mov_b32 m0, s61
	v_lshl_add_u64 v[226:227], s[64:65], 0, v[160:161]
	ds_read_b128 v[144:147], v204 offset:16384
	ds_read_b128 v[148:151], v204 offset:17408
	ds_read_b128 v[152:155], v204 offset:18432
	ds_read_b128 v[156:159], v204 offset:19456
	ds_read_b128 v[178:181], v204 offset:20480
	ds_read_b128 v[182:185], v204 offset:21504
	ds_read_b128 v[186:189], v204 offset:22528
	ds_read_b128 v[190:193], v204 offset:23552
	global_load_lds_dwordx4 v[226:227], off
	v_lshl_add_u64 v[228:229], s[64:65], 0, v[164:165]
	s_mov_b32 m0, s63
	s_nop 0
	global_load_lds_dwordx4 v[228:229], off
	s_waitcnt vmcnt(10)
	s_barrier
	s_waitcnt lgkmcnt(0)
	s_setprio 1
	v_mfma_f32_16x16x32_bf16 v[60:63], v[128:131], v[144:147], v[60:63]
	v_mfma_f32_16x16x32_bf16 v[56:59], v[136:139], v[144:147], v[56:59]
	v_mfma_f32_16x16x32_bf16 v[48:51], v[128:131], v[152:155], v[48:51]
	v_mfma_f32_16x16x32_bf16 v[40:43], v[136:139], v[152:155], v[40:43]
	v_mfma_f32_16x16x32_bf16 v[28:31], v[128:131], v[178:181], v[28:31]
	v_mfma_f32_16x16x32_bf16 v[24:27], v[136:139], v[178:181], v[24:27]
	v_mfma_f32_16x16x32_bf16 v[12:15], v[128:131], v[186:189], v[12:15]
	v_mfma_f32_16x16x32_bf16 v[8:11], v[136:139], v[186:189], v[8:11]
	v_mfma_f32_16x16x32_bf16 v[60:63], v[132:135], v[148:151], v[60:63]
	v_mfma_f32_16x16x32_bf16 v[56:59], v[140:143], v[148:151], v[56:59]
	v_mfma_f32_16x16x32_bf16 v[48:51], v[132:135], v[156:159], v[48:51]
	v_mfma_f32_16x16x32_bf16 v[40:43], v[140:143], v[156:159], v[40:43]
	v_mfma_f32_16x16x32_bf16 v[28:31], v[132:135], v[182:185], v[28:31]
	v_mfma_f32_16x16x32_bf16 v[24:27], v[140:143], v[182:185], v[24:27]
	v_mfma_f32_16x16x32_bf16 v[12:15], v[132:135], v[190:193], v[12:15]
	v_mfma_f32_16x16x32_bf16 v[8:11], v[140:143], v[190:193], v[8:11]
	s_barrier
; #define PG8_STAGE(bufoff, gbase, voff) do { _Pragma("unroll") for (int _i = 0; _i < 2; ++_i) \
;     __builtin_amdgcn_global_load_lds((const unsigned*)((const char*)(gbase) + (voff)[_i]), (LAS unsigned*)(lds + (bufoff) + ldsw + _i * 8192), 16, 0, 0); } while (0)
; #define PG8_LDA(dst, b, h) do { _Pragma("unroll") for (int m = 0; m < 4; ++m) _Pragma("unroll") for (int k = 0; k < 2; ++k) dst[m][k] = *(const LAS bf16x8*)(lds + PG8_SA(b, h) + aoff + m * 2048 + k * 1024); } while (0)
; #define PG8_LDB(dst, b, h) do { _Pragma("unroll") for (int n = 0; n < 2; ++n) _Pragma("unroll") for (int k = 0; k < 2; ++k) dst[n][k] = *(const LAS bf16x8*)(lds + PG8_SB(b, h) + boff + n * 2048 + k * 1024); } while (0)
; #define PG8_MMA(ai, bj, At, Bt) do { __builtin_amdgcn_s_setprio(1); _Pragma("unroll") for (int m = 0; m < 4; ++m) _Pragma("unroll") for (int n = 0; n < 2; ++n) _Pragma("unroll") for (int k = 0; k < 2; ++k) \
;     acc[ai][bj][m][n] = __builtin_amdgcn_mfma_f32_16x16x32_bf16(Bt[n][k], At[m][k], acc[ai][bj][m][n], 0, 0, 0); __builtin_amdgcn_s_setprio(0); } while (0)
; #define PG8_WAIT_V(n) asm volatile("s_waitcnt vmcnt(" #n ")" ::: "memory")
; #define PG8_WAIT_L(n) asm volatile("s_waitcnt lgkmcnt(" #n ")" ::: "memory")
; #define PG8_BAR __builtin_amdgcn_s_barrier()
; #define PG8_SCHED __builtin_amdgcn_sched_barrier(0)
; template <class Epi, class Sched = StaticOrder>
; DI void gemm_phase(LAS unsigned char* lds, const Gemm g, const Sched& S, const Epi& E) {
;     ...
;       PG8_WAIT_V(6); PG8_BAR; PG8_MMA(1, 1, At, B1); PG8_BAR;
;       PG8_LDB(B0, 1, 0); PG8_SCHED; PG8_LDA(At, 1, 0); PG8_STAGE(PG8_SA(0, 1), a2 + hstep, voffA);
;       PG8_WAIT_L(8); PG8_BAR; PG8_WAIT_L(0); PG8_MMA(0, 0, At, B0); PG8_BAR; PG8_SCHED;
;       PG8_LDB(B1, 1, 1); PG8_STAGE(PG8_SB(1, 0), b3, voffB);
;       PG8_BAR; PG8_WAIT_L(0); PG8_MMA(0, 1, At, B1); PG8_BAR;
;       PG8_LDA(At, 1, 1); PG8_STAGE(PG8_SA(1, 0), a3, voffA);
	s_setprio 0
	s_add_u32 s54, s12, 0x80000
	s_addc_u32 s55, s13, 0
	s_add_i32 s53, s81, s70
	v_lshl_add_u64 v[128:129], s[54:55], 0, v[162:163]
	s_mov_b32 m0, s53
	s_nop 0
	global_load_lds_dwordx4 v[128:129], off
	v_lshl_add_u64 v[128:129], s[54:55], 0, v[166:167]
	s_add_i32 m0, s53, 0x2000
	s_nop 0
	global_load_lds_dwordx4 v[128:129], off
	s_add_i32 s53, 0, 0x18000
	v_add_u32_e32 v140, s53, v199
	ds_read_b128 v[128:131], v140
	ds_read_b128 v[132:135], v140 offset:1024
	ds_read_b128 v[136:139], v140 offset:2048
	ds_read_b128 v[140:143], v140 offset:3072
	s_waitcnt vmcnt(6)
	s_barrier
	s_setprio 1
	v_mfma_f32_16x16x32_bf16 v[52:55], v[194:197], v[144:147], v[52:55]
	v_mfma_f32_16x16x32_bf16 v[44:47], v[216:219], v[144:147], v[44:47]
	v_mfma_f32_16x16x32_bf16 v[36:39], v[194:197], v[152:155], v[36:39]
	v_mfma_f32_16x16x32_bf16 v[32:35], v[216:219], v[152:155], v[32:35]
	v_mfma_f32_16x16x32_bf16 v[20:23], v[194:197], v[178:181], v[20:23]
	v_mfma_f32_16x16x32_bf16 v[16:19], v[216:219], v[178:181], v[16:19]
	v_mfma_f32_16x16x32_bf16 v[4:7], v[194:197], v[186:189], v[4:7]
	v_mfma_f32_16x16x32_bf16 v[0:3], v[216:219], v[186:189], v[0:3]
	v_mfma_f32_16x16x32_bf16 v[52:55], v[212:215], v[148:151], v[52:55]
	v_mfma_f32_16x16x32_bf16 v[44:47], v[220:223], v[148:151], v[44:47]
	v_mfma_f32_16x16x32_bf16 v[36:39], v[212:215], v[156:159], v[36:39]
	v_mfma_f32_16x16x32_bf16 v[32:35], v[220:223], v[156:159], v[32:35]
	v_mfma_f32_16x16x32_bf16 v[20:23], v[212:215], v[182:185], v[20:23]
	v_mfma_f32_16x16x32_bf16 v[16:19], v[220:223], v[182:185], v[16:19]
	v_mfma_f32_16x16x32_bf16 v[4:7], v[212:215], v[190:193], v[4:7]
	v_mfma_f32_16x16x32_bf16 v[0:3], v[220:223], v[190:193], v[0:3]
	s_barrier
	s_setprio 0
	s_add_u32 s54, s64, 0x80000
	s_addc_u32 s55, s65, 0
	s_mov_b32 m0, s71
	v_lshl_add_u64 v[194:195], s[54:55], 0, v[160:161]
	ds_read_b128 v[144:147], v204 offset:32768
	ds_read_b128 v[148:151], v204 offset:33792
	ds_read_b128 v[152:155], v204 offset:34816
	ds_read_b128 v[156:159], v204 offset:35840
	ds_read_b128 v[178:181], v204 offset:36864
	ds_read_b128 v[182:185], v204 offset:37888
	ds_read_b128 v[186:189], v204 offset:38912
	ds_read_b128 v[190:193], v204 offset:39936
	global_load_lds_dwordx4 v[194:195], off
	v_lshl_add_u64 v[194:195], s[54:55], 0, v[164:165]
	s_mov_b32 m0, s72
	s_nop 0
	global_load_lds_dwordx4 v[194:195], off
	s_waitcnt lgkmcnt(8)
	s_barrier
	s_waitcnt lgkmcnt(0)
	s_setprio 1
	v_mfma_f32_16x16x32_bf16 v[124:127], v[128:131], v[144:147], v[124:127]
	v_mfma_f32_16x16x32_bf16 v[120:123], v[136:139], v[144:147], v[120:123]
	v_mfma_f32_16x16x32_bf16 v[116:119], v[128:131], v[152:155], v[116:119]
	v_mfma_f32_16x16x32_bf16 v[104:107], v[136:139], v[152:155], v[104:107]
	v_mfma_f32_16x16x32_bf16 v[92:95], v[128:131], v[178:181], v[92:95]
	v_mfma_f32_16x16x32_bf16 v[88:91], v[136:139], v[178:181], v[88:91]
	v_mfma_f32_16x16x32_bf16 v[84:87], v[128:131], v[186:189], v[84:87]
	v_mfma_f32_16x16x32_bf16 v[72:75], v[136:139], v[186:189], v[72:75]
	v_mfma_f32_16x16x32_bf16 v[124:127], v[132:135], v[148:151], v[124:127]
	v_mfma_f32_16x16x32_bf16 v[120:123], v[140:143], v[148:151], v[120:123]
	v_mfma_f32_16x16x32_bf16 v[116:119], v[132:135], v[156:159], v[116:119]
	v_mfma_f32_16x16x32_bf16 v[104:107], v[140:143], v[156:159], v[104:107]
	v_mfma_f32_16x16x32_bf16 v[92:95], v[132:135], v[182:185], v[92:95]
	v_mfma_f32_16x16x32_bf16 v[88:91], v[140:143], v[182:185], v[88:91]
	v_mfma_f32_16x16x32_bf16 v[84:87], v[132:135], v[190:193], v[84:87]
	v_mfma_f32_16x16x32_bf16 v[72:75], v[140:143], v[190:193], v[72:75]
	s_barrier
	s_setprio 0
	s_add_i32 s54, 0, 0x1c000
	s_add_i32 s53, s53, s70
	v_add_u32_e32 v168, s54, v199
	v_lshl_add_u64 v[208:209], v[208:209], 0, s[24:25]
	s_mov_b32 m0, s53
	ds_read_b128 v[194:197], v168
	ds_read_b128 v[212:215], v168 offset:1024
	ds_read_b128 v[216:219], v168 offset:2048
	ds_read_b128 v[220:223], v168 offset:3072
	global_load_lds_dwordx4 v[208:209], off
	v_lshl_add_u64 v[208:209], v[224:225], 0, s[24:25]
	s_add_i32 m0, s53, 0x2000
	s_nop 0
	global_load_lds_dwordx4 v[208:209], off
	s_barrier
	s_waitcnt lgkmcnt(0)
	s_setprio 1
	v_mfma_f32_16x16x32_bf16 v[112:115], v[194:197], v[144:147], v[112:115]
	v_mfma_f32_16x16x32_bf16 v[108:111], v[216:219], v[144:147], v[108:111]
	v_mfma_f32_16x16x32_bf16 v[100:103], v[194:197], v[152:155], v[100:103]
	v_mfma_f32_16x16x32_bf16 v[96:99], v[216:219], v[152:155], v[96:99]
	v_mfma_f32_16x16x32_bf16 v[80:83], v[194:197], v[178:181], v[80:83]
	v_mfma_f32_16x16x32_bf16 v[76:79], v[216:219], v[178:181], v[76:79]
	v_mfma_f32_16x16x32_bf16 v[68:71], v[194:197], v[186:189], v[68:71]
	v_mfma_f32_16x16x32_bf16 v[64:67], v[216:219], v[186:189], v[64:67]
	v_mfma_f32_16x16x32_bf16 v[112:115], v[212:215], v[148:151], v[112:115]
	v_mfma_f32_16x16x32_bf16 v[108:111], v[220:223], v[148:151], v[108:111]
	v_mfma_f32_16x16x32_bf16 v[100:103], v[212:215], v[156:159], v[100:103]
	v_mfma_f32_16x16x32_bf16 v[96:99], v[220:223], v[156:159], v[96:99]
	v_mfma_f32_16x16x32_bf16 v[80:83], v[212:215], v[182:185], v[80:83]
	v_mfma_f32_16x16x32_bf16 v[76:79], v[220:223], v[182:185], v[76:79]
	v_mfma_f32_16x16x32_bf16 v[68:71], v[212:215], v[190:193], v[68:71]
	v_mfma_f32_16x16x32_bf16 v[64:67], v[220:223], v[190:193], v[64:67]
	s_barrier
	s_setprio 0
	s_mov_b32 m0, s76
	v_lshl_add_u64 v[208:209], v[226:227], 0, s[24:25]
	ds_read_b128 v[144:147], v204 offset:49152
	ds_read_b128 v[148:151], v204 offset:50176
	ds_read_b128 v[152:155], v204 offset:51200
	ds_read_b128 v[156:159], v204 offset:52224
	ds_read_b128 v[178:181], v204 offset:53248
	ds_read_b128 v[182:185], v204 offset:54272
	ds_read_b128 v[186:189], v204 offset:55296
	ds_read_b128 v[190:193], v204 offset:56320
	global_load_lds_dwordx4 v[208:209], off
	v_lshl_add_u64 v[208:209], v[228:229], 0, s[24:25]
	s_mov_b32 m0, s77
	s_nop 0
	global_load_lds_dwordx4 v[208:209], off
	s_waitcnt vmcnt(10)
	s_barrier
; #define PG8_STAGE(bufoff, gbase, voff) do { _Pragma("unroll") for (int _i = 0; _i < 2; ++_i) \
;     __builtin_amdgcn_global_load_lds((const unsigned*)((const char*)(gbase) + (voff)[_i]), (LAS unsigned*)(lds + (bufoff) + ldsw + _i * 8192), 16, 0, 0); } while (0)
; #define PG8_LDA(dst, b, h) do { _Pragma("unroll") for (int m = 0; m < 4; ++m) _Pragma("unroll") for (int k = 0; k < 2; ++k) dst[m][k] = *(const LAS bf16x8*)(lds + PG8_SA(b, h) + aoff + m * 2048 + k * 1024); } while (0)
; #define PG8_MMA(ai, bj, At, Bt) do { __builtin_amdgcn_s_setprio(1); _Pragma("unroll") for (int m = 0; m < 4; ++m) _Pragma("unroll") for (int n = 0; n < 2; ++n) _Pragma("unroll") for (int k = 0; k < 2; ++k) \
;     acc[ai][bj][m][n] = __builtin_amdgcn_mfma_f32_16x16x32_bf16(Bt[n][k], At[m][k], acc[ai][bj][m][n], 0, 0, 0); __builtin_amdgcn_s_setprio(0); } while (0)
; #define PG8_WAIT_V(n) asm volatile("s_waitcnt vmcnt(" #n ")" ::: "memory")
; #define PG8_WAIT_L(n) asm volatile("s_waitcnt lgkmcnt(" #n ")" ::: "memory")
; #define PG8_BAR __builtin_amdgcn_s_barrier()
; #define PG8_SCHED __builtin_amdgcn_sched_barrier(0)
;   DI void operator()(const f32x4 (&acc)[2][2][4][2], const Unit& u, int wr, int wc, int fr, int fq) const {
;     ...
;     const int col = u.pn * 128 + wc * 32 + 8 * fq;
;     float w0[8], w1[8], w2[8];
; #pragma unroll
;     for (int e = 0; e < 8; ++e) { w0[e] = cw[col + e]; w1[e] = cw[2048 + col + e]; w2[e] = cw[4096 + col + e]; }
; #pragma unroll
;     for (int ai = 0; ai < 2; ++ai) {
;       const int row0 = u.pm * BM + ai * HALF + wr * 64, span = row0 >> 6;
;       float rsv[4];
; #pragma unroll
;       for (int m = 0; m < 4; ++m) rsv[m] = row_rstd(ssq, row0 + 16 * m + fr, fq);
; template <class Epi, class Sched = StaticOrder>
; DI void gemm_phase(LAS unsigned char* lds, const Gemm g, const Sched& S, const Epi& E) {
;     ...
;       PG8_LDA(At, 1, 1); PG8_STAGE(PG8_SA(1, 0), a3, voffA);
;       PG8_BAR; PG8_WAIT_L(0); PG8_MMA(1, 0, At, B0); PG8_BAR; PG8_SCHED;
;       PG8_STAGE(PG8_SB(1, 1), b3 + hstep, voffB);
;       PG8_WAIT_V(6); PG8_BAR; PG8_MMA(1, 1, At, B1); PG8_BAR;
	s_waitcnt lgkmcnt(0)
	s_setprio 1
	v_mfma_f32_16x16x32_bf16 v[60:63], v[128:131], v[144:147], v[60:63]
	v_mfma_f32_16x16x32_bf16 v[56:59], v[136:139], v[144:147], v[56:59]
	v_mfma_f32_16x16x32_bf16 v[48:51], v[128:131], v[152:155], v[48:51]
	v_mfma_f32_16x16x32_bf16 v[40:43], v[136:139], v[152:155], v[40:43]
	v_mfma_f32_16x16x32_bf16 v[28:31], v[128:131], v[178:181], v[28:31]
	v_mfma_f32_16x16x32_bf16 v[24:27], v[136:139], v[178:181], v[24:27]
	v_mfma_f32_16x16x32_bf16 v[12:15], v[128:131], v[186:189], v[12:15]
	v_mfma_f32_16x16x32_bf16 v[8:11], v[136:139], v[186:189], v[8:11]
	v_mfma_f32_16x16x32_bf16 v[60:63], v[132:135], v[148:151], v[60:63]
	v_mfma_f32_16x16x32_bf16 v[56:59], v[140:143], v[148:151], v[56:59]
	v_mfma_f32_16x16x32_bf16 v[48:51], v[132:135], v[156:159], v[48:51]
	v_mfma_f32_16x16x32_bf16 v[40:43], v[140:143], v[156:159], v[40:43]
	v_mfma_f32_16x16x32_bf16 v[28:31], v[132:135], v[182:185], v[28:31]
	v_mfma_f32_16x16x32_bf16 v[24:27], v[140:143], v[182:185], v[24:27]
	v_mfma_f32_16x16x32_bf16 v[12:15], v[132:135], v[190:193], v[12:15]
	v_mfma_f32_16x16x32_bf16 v[8:11], v[140:143], v[190:193], v[8:11]
	s_barrier
	s_setprio 0
	s_add_u32 s12, s12, 0x80080
	s_addc_u32 s13, s13, 0
	s_add_i32 s53, s54, s70
	v_lshl_add_u64 v[128:129], s[12:13], 0, v[162:163]
	s_mov_b32 m0, s53
	s_nop 0
	global_load_lds_dwordx4 v[128:129], off
	v_lshl_add_u64 v[128:129], s[12:13], 0, v[166:167]
	s_add_i32 m0, s53, 0x2000
	s_nop 0
	global_load_lds_dwordx4 v[128:129], off
	ds_read_b128 v[128:131], v203
	ds_read_b128 v[132:135], v203 offset:1024
	ds_read_b128 v[136:139], v203 offset:2048
	ds_read_b128 v[140:143], v203 offset:3072
	s_waitcnt vmcnt(6)
	s_barrier
	s_setprio 1
	v_mfma_f32_16x16x32_bf16 v[52:55], v[194:197], v[144:147], v[52:55]
	v_mfma_f32_16x16x32_bf16 v[44:47], v[216:219], v[144:147], v[44:47]
	v_mfma_f32_16x16x32_bf16 v[36:39], v[194:197], v[152:155], v[36:39]
	v_mfma_f32_16x16x32_bf16 v[32:35], v[216:219], v[152:155], v[32:35]
	v_mfma_f32_16x16x32_bf16 v[20:23], v[194:197], v[178:181], v[20:23]
	v_mfma_f32_16x16x32_bf16 v[16:19], v[216:219], v[178:181], v[16:19]
	v_mfma_f32_16x16x32_bf16 v[4:7], v[194:197], v[186:189], v[4:7]
	v_mfma_f32_16x16x32_bf16 v[0:3], v[216:219], v[186:189], v[0:3]
	v_mfma_f32_16x16x32_bf16 v[52:55], v[212:215], v[148:151], v[52:55]
	v_mfma_f32_16x16x32_bf16 v[44:47], v[220:223], v[148:151], v[44:47]
	v_mfma_f32_16x16x32_bf16 v[36:39], v[212:215], v[156:159], v[36:39]
	v_mfma_f32_16x16x32_bf16 v[32:35], v[220:223], v[156:159], v[32:35]
	v_mfma_f32_16x16x32_bf16 v[20:23], v[212:215], v[182:185], v[20:23]
	v_mfma_f32_16x16x32_bf16 v[16:19], v[220:223], v[182:185], v[16:19]
	v_mfma_f32_16x16x32_bf16 v[4:7], v[212:215], v[190:193], v[4:7]
	v_mfma_f32_16x16x32_bf16 v[0:3], v[220:223], v[190:193], v[0:3]
	s_add_i32 s52, s52, 2
	s_add_u32 s10, s10, 0x100
	s_addc_u32 s11, s11, 0
	s_add_u32 s45, s45, 0x100
	s_addc_u32 s49, s49, 0
	s_cmp_gt_u32 s52, 29
	s_barrier
	s_setprio 0
	s_cbranch_scc0 .LBB0_1052
	s_waitcnt lgkmcnt(0)
	s_cmp_lt_i32 s62, 16
	s_mov_b64 s[10:11], -1
	s_cbranch_scc0 .LBB0_1067
	s_lshl_b32 s41, s60, 8
	s_add_i32 s41, s41, s75
	v_or_b32_e32 v186, s41, v177
	v_ashrrev_i32_e32 v187, 31, v186
	v_lshlrev_b64 v[128:129], 7, v[186:187]
	v_or_b32_e32 v180, 16, v186
	v_lshl_add_u64 v[128:129], v[170:171], 0, v[128:129]
	v_ashrrev_i32_e32 v181, 31, v180
	global_load_dwordx4 v[152:155], v[128:129], off
	global_load_dwordx4 v[156:159], v[128:129], off offset:16
	v_lshlrev_b64 v[128:129], 7, v[180:181]
	v_lshl_add_u64 v[128:129], v[170:171], 0, v[128:129]
	global_load_dwordx4 v[188:191], v[128:129], off
	global_load_dwordx4 v[192:195], v[128:129], off offset:16
	v_or_b32_e32 v184, 32, v186
	v_ashrrev_i32_e32 v185, 31, v184
	v_lshlrev_b64 v[128:129], 7, v[184:185]
	v_or_b32_e32 v182, 48, v186
	v_lshl_add_u64 v[128:129], v[170:171], 0, v[128:129]
	v_ashrrev_i32_e32 v183, 31, v182
	global_load_dwordx4 v[212:215], v[128:129], off
	global_load_dwordx4 v[216:219], v[128:129], off offset:16
	v_lshlrev_b64 v[128:129], 7, v[182:183]
	v_lshl_add_u64 v[128:129], v[170:171], 0, v[128:129]
	global_load_dwordx4 v[220:223], v[128:129], off
	global_load_dwordx4 v[224:227], v[128:129], off offset:16
	v_and_b32_e32 v129, 64, v206
	v_lshl_or_b32 v178, s62, 7, v200
	v_xor_b32_e32 v128, 16, v206
	v_add_u32_e32 v129, 64, v129
	v_readlane_b32 s44, v243, 3
	v_xor_b32_e32 v130, 32, v206
	v_ashrrev_i32_e32 v179, 31, v178
	v_readlane_b32 s45, v243, 4
	v_cmp_lt_i32_e32 vcc, v128, v129
	s_movk_i32 s10, 0x2000
	v_lshl_add_u64 v[144:145], v[178:179], 2, s[44:45]
	v_cndmask_b32_e32 v134, v206, v128, vcc
	v_cmp_lt_i32_e32 vcc, v130, v129
	v_lshl_add_u64 v[132:133], v[144:145], 0, s[26:27]
	v_lshl_add_u64 v[136:137], v[144:145], 0, s[28:29]
	v_cndmask_b32_e32 v135, v206, v130, vcc
	v_add_co_u32_e32 v146, vcc, s10, v144
	global_load_dwordx4 v[128:131], v[144:145], off offset:16
	global_load_dwordx4 v[140:143], v[144:145], off
	v_addc_co_u32_e32 v147, vcc, 0, v145, vcc
	v_add_co_u32_e32 v148, vcc, s74, v144
	v_lshlrev_b32_e32 v196, 2, v134
	s_nop 0
	v_addc_co_u32_e32 v149, vcc, 0, v145, vcc
	v_lshlrev_b32_e32 v207, 2, v135
	global_load_dwordx4 v[132:135], v[132:133], off offset:16
	s_nop 0
	global_load_dwordx4 v[136:139], v[136:137], off offset:16
	s_nop 0
	global_load_dwordx4 v[144:147], v[146:147], off
	s_nop 0
	global_load_dwordx4 v[148:151], v[148:149], off
	v_mov_b32_e32 v197, 0
	v_mov_b32_e32 v211, 0
	v_readlane_b32 s46, v243, 5
	v_readlane_b32 s47, v243, 6
	v_readlane_b32 s48, v243, 7
	v_readlane_b32 s49, v243, 8
	v_readlane_b32 s50, v243, 9
	v_readlane_b32 s51, v243, 10
	v_readlane_b32 s52, v243, 11
	v_readlane_b32 s53, v243, 12
	v_readlane_b32 s54, v243, 13
	v_readlane_b32 s55, v243, 14
	v_readlane_b32 s56, v243, 15
	v_readlane_b32 s57, v243, 16
	v_readlane_b32 s58, v243, 17
	v_readlane_b32 s59, v243, 18
	s_waitcnt vmcnt(0)
; DI unsigned pack2(float lo, float hi) { f32x2 v = {lo, hi}; bf16v2 r = __builtin_convertvector(v, bf16v2); return __builtin_bit_cast(unsigned, r); }
; DI float dpp_ror1(float v) { return __int_as_float(__builtin_amdgcn_update_dpp(0, __float_as_int(v), 0x121, 0xf, 0xf, false)); }
; DI float dpp_ror2(float v) { return __int_as_float(__builtin_amdgcn_update_dpp(0, __float_as_int(v), 0x122, 0xf, 0xf, false)); }
; DI float row_rstd(const float* ssq, int row, int fq) {
;   const f32x4 a = *(const f32x4*)(ssq + (size_t)row * 32 + fq * 8), b = *(const f32x4*)(ssq + (size_t)row * 32 + fq * 8 + 4);
;   float sm = ((a[0] + a[1]) + (a[2] + a[3])) + ((b[0] + b[1]) + (b[2] + b[3]));
;   sm += __shfl_xor(sm, 16); sm += __shfl_xor(sm, 32);
;   return rsqrtf(sm * (1.0f / 2048.f) + 1e-6f);
;   DI void operator()(const f32x4 (&acc)[2][2][4][2], const Unit& u, int wr, int wc, int fr, int fq) const {
;     ...
;       for (int m = 0; m < 4; ++m) {
;         float g[8], a[8];
;         const float rs1 = rsv[m], rs2 = rs1 * rs1;
; #pragma unroll
;         for (int e = 0; e < 4; ++e) { g[e] = acc[ai][0][m][0][e] * acc[ai][1][m][0][e] * rs2; g[4 + e] = acc[ai][0][m][1][e] * acc[ai][1][m][1][e] * rs2; }
; #pragma unroll
;         for (int e = 0; e < 8; ++e) {
;           const float x1 = dpp_ror1(g[e]), x2 = dpp_ror2(g[e]);
;           const float pr1 = (fr == 0) ? p1[e] : x1, pr2 = (fr < 2) ? p2[e] : x2;
;           a[e] = w2[e] * g[e] + w1[e] * pr1 + w0[e] * pr2;
;           p1[e] = x1; p2[e] = x2;
;         }
;         if (m == 0 && fr < 2) {
;           float* hc = headC + (size_t)(span * 2 + fr) * 2048 + col;
;           *(f32x4*)hc = (f32x4){a[0], a[1], a[2], a[3]}; *(f32x4*)(hc + 4) = (f32x4){a[4], a[5], a[6], a[7]};
;         } else {
;           u32x4 w; w.x = pack2(a[0] * rs1, a[1] * rs1); w.y = pack2(a[2] * rs1, a[3] * rs1); w.z = pack2(a[4] * rs1, a[5] * rs1); w.w = pack2(a[6] * rs1, a[7] * rs1);
;           *(u32x4*)(C + (size_t)(row0 + 16 * m + fr) * 2048 + col) = w;
	v_mov_b32_e32 v208, v152
	v_mov_b32_e32 v209, v156
	v_mov_b32_e32 v156, v153
	v_mov_b32_e32 v152, v154
	v_mov_b32_e32 v153, v158
	v_mov_b32_e32 v158, v155
	v_pk_add_f32 v[154:155], v[208:209], v[156:157]
	v_pk_add_f32 v[152:153], v[152:153], v[158:159]
	v_mov_b32_e32 v156, v188
	v_mov_b32_e32 v157, v192
	v_mov_b32_e32 v192, v189
	v_mov_b32_e32 v158, v190
	v_mov_b32_e32 v159, v194
	v_mov_b32_e32 v194, v191
	v_pk_add_f32 v[152:153], v[154:155], v[152:153]
	v_pk_add_f32 v[154:155], v[156:157], v[192:193]
	v_pk_add_f32 v[156:157], v[158:159], v[194:195]
	v_mov_b32_e32 v188, v212
	v_pk_add_f32 v[154:155], v[154:155], v[156:157]
	v_mov_b32_e32 v157, v152
	v_mov_b32_e32 v156, v154
	v_mov_b32_e32 v152, v155
	v_pk_add_f32 v[152:153], v[156:157], v[152:153]
	ds_bpermute_b32 v155, v196, v153
	ds_bpermute_b32 v154, v196, v152
	v_mov_b32_e32 v189, v216
	v_mov_b32_e32 v216, v213
	v_mov_b32_e32 v190, v214
	v_mov_b32_e32 v191, v218
	s_waitcnt lgkmcnt(0)
	v_pk_add_f32 v[152:153], v[152:153], v[154:155]
	ds_bpermute_b32 v155, v207, v153
	ds_bpermute_b32 v154, v207, v152
	v_mov_b32_e32 v218, v215
	v_mov_b32_e32 v208, v220
	v_mov_b32_e32 v209, v224
	v_mov_b32_e32 v224, v221
	v_mov_b32_e32 v212, v222
	v_mov_b32_e32 v213, v226
	v_mov_b32_e32 v226, v223
	v_pk_add_f32 v[156:157], v[188:189], v[216:217]
	v_pk_add_f32 v[158:159], v[190:191], v[218:219]
	v_pk_add_f32 v[188:189], v[208:209], v[224:225]
	v_pk_add_f32 v[190:191], v[212:213], v[226:227]
	s_waitcnt lgkmcnt(0)
	v_pk_add_f32 v[152:153], v[152:153], v[154:155]
	v_pk_add_f32 v[156:157], v[156:157], v[158:159]
	v_pk_add_f32 v[158:159], v[188:189], v[190:191]
	v_pk_fma_f32 v[188:189], v[152:153], s[30:31], v[176:177] op_sel_hi:[1,0,0]
	v_mov_b32_e32 v153, v156
	v_mul_f32_e32 v152, 0x4b800000, v189
	v_cmp_gt_f32_e64 s[10:11], s84, v189
	v_mov_b32_e32 v156, v159
	v_mov_b32_e32 v194, v123
	v_cndmask_b32_e64 v152, v189, v152, s[10:11]
	v_rsq_f32_e32 v168, v152
	v_mov_b32_e32 v152, v158
	v_pk_add_f32 v[152:153], v[152:153], v[156:157]
	ds_bpermute_b32 v155, v196, v153
	ds_bpermute_b32 v154, v196, v152
	v_mul_f32_e32 v156, 0x45800000, v168
	v_cndmask_b32_e64 v195, v168, v156, s[10:11]
	v_mov_b32_e32 v217, 0
	v_mul_f32_e32 v156, v125, v113
	s_waitcnt lgkmcnt(0)
	v_pk_add_f32 v[190:191], v[152:153], v[154:155]
	v_mov_b32_e32 v152, v111
	v_mov_b32_e32 v153, v195
	v_mul_f32_e32 v154, v124, v112
	v_pk_mul_f32 v[152:153], v[194:195], v[152:153]
	v_mul_f32_e32 v155, v120, v108
	v_mul_f32_e32 v154, v154, v153
	v_pk_mul_f32 v[222:223], v[152:153], v[152:153] op_sel:[0,1] op_sel_hi:[1,0]
	v_mov_b32_e32 v213, 0
	v_mov_b32_dpp v217, v154 row_ror:1 row_mask:0xf bank_mask:0xf
	v_cndmask_b32_e64 v152, v217, 0, s[0:1]
	v_mul_f32_e32 v157, v121, v109
	v_mul_f32_e32 v158, v126, v114
	v_mul_f32_e32 v159, v122, v110
	v_mul_f32_e32 v168, v127, v115
	v_mul_f32_e32 v194, v155, v153
	v_mul_f32_e32 v155, v156, v153
	v_mov_b32_dpp v213, v154 row_ror:2 row_mask:0xf bank_mask:0xf
	v_mov_b32_e32 v221, 0
	v_mul_f32_e32 v152, v144, v152
	v_mul_f32_e32 v208, v157, v153
	v_mul_f32_e32 v156, v158, v153
	v_mul_f32_e32 v159, v159, v153
	v_mul_f32_e32 v157, v168, v153
	v_mov_b32_dpp v221, v155 row_ror:1 row_mask:0xf bank_mask:0xf
	v_cndmask_b32_e64 v153, v213, 0, s[8:9]
	v_fmac_f32_e32 v152, v148, v154
	v_mov_b32_e32 v219, 0
	v_fmac_f32_e32 v152, v140, v153
	v_cndmask_b32_e64 v153, v221, 0, s[0:1]
	v_mov_b32_dpp v219, v155 row_ror:2 row_mask:0xf bank_mask:0xf
	v_mul_f32_e32 v153, v145, v153
	v_mov_b32_e32 v216, 0
	v_cndmask_b32_e64 v154, v219, 0, s[8:9]
	v_fmac_f32_e32 v153, v149, v155
	v_mov_b32_dpp v216, v156 row_ror:1 row_mask:0xf bank_mask:0xf
	v_fmac_f32_e32 v153, v141, v154
	v_mov_b32_e32 v212, 0
	v_cndmask_b32_e64 v154, v216, 0, s[0:1]
	v_mov_b32_e32 v220, 0
	v_mov_b32_dpp v212, v156 row_ror:2 row_mask:0xf bank_mask:0xf
	v_mul_f32_e32 v154, v146, v154
	v_mov_b32_dpp v220, v157 row_ror:1 row_mask:0xf bank_mask:0xf
	v_cndmask_b32_e64 v155, v212, 0, s[8:9]
	v_fmac_f32_e32 v154, v150, v156
	v_mov_b32_e32 v218, 0
	v_fmac_f32_e32 v154, v142, v155
	v_cndmask_b32_e64 v155, v220, 0, s[0:1]
	v_mov_b32_dpp v218, v157 row_ror:2 row_mask:0xf bank_mask:0xf
	v_mul_f32_e32 v155, v147, v155
	v_cndmask_b32_e64 v156, v218, 0, s[8:9]
	v_fmac_f32_e32 v155, v151, v157
	v_mov_b32_dpp v197, v194 row_ror:1 row_mask:0xf bank_mask:0xf
	v_fmac_f32_e32 v155, v143, v156
	v_mov_b32_e32 v189, 0
	v_cndmask_b32_e64 v156, v197, 0, s[0:1]
	v_mov_b32_e32 v214, 0
	v_mov_b32_dpp v189, v194 row_ror:2 row_mask:0xf bank_mask:0xf
	v_mul_f32_e32 v156, v132, v156
	v_mov_b32_dpp v214, v208 row_ror:1 row_mask:0xf bank_mask:0xf
	v_cndmask_b32_e64 v157, v189, 0, s[8:9]
	v_fmac_f32_e32 v156, v136, v194
	v_fmac_f32_e32 v156, v128, v157
	v_cndmask_b32_e64 v157, v214, 0, s[0:1]
	v_mov_b32_e32 v209, 0
	v_mul_f32_e32 v157, v133, v157
	v_fmac_f32_e32 v157, v137, v208
	v_mov_b32_dpp v209, v208 row_ror:2 row_mask:0xf bank_mask:0xf
	v_mov_b32_e32 v208, 0
	v_cndmask_b32_e64 v158, v209, 0, s[8:9]
	v_fmac_f32_e32 v157, v129, v158
	v_mov_b32_dpp v208, v159 row_ror:1 row_mask:0xf bank_mask:0xf
	v_mov_b32_e32 v194, 0
	v_cndmask_b32_e64 v158, v208, 0, s[0:1]
	ds_bpermute_b32 v193, v207, v191
	ds_bpermute_b32 v192, v207, v190
	v_mov_b32_dpp v194, v159 row_ror:2 row_mask:0xf bank_mask:0xf
	v_mov_b32_e32 v215, 0
	v_mul_f32_e32 v158, v134, v158
	v_cndmask_b32_e64 v168, v194, 0, s[8:9]
	v_mov_b32_dpp v215, v222 row_ror:1 row_mask:0xf bank_mask:0xf
	v_fmac_f32_e32 v158, v138, v159
	v_mov_b32_dpp v211, v222 row_ror:2 row_mask:0xf bank_mask:0xf
	v_fmac_f32_e32 v158, v130, v168
	v_cndmask_b32_e64 v168, v215, 0, s[0:1]
	v_mul_f32_e32 v159, v139, v222
	v_cndmask_b32_e64 v223, v211, 0, s[8:9]
	v_fmac_f32_e32 v159, v135, v168
	v_cmp_gt_f32_e32 vcc, s84, v188
	v_fmac_f32_e32 v159, v131, v223
	s_and_saveexec_b64 s[10:11], s[4:5]
	s_xor_b64 s[10:11], exec, s[10:11]
	s_cbranch_execz .LBB0_1056
	v_mul_f32_e32 v152, v195, v152
	v_mul_f32_e32 v153, v195, v153
	v_cvt_pk_bf16_f32 v152, v152, v153
	v_mul_f32_e32 v153, v195, v154
	v_mul_f32_e32 v154, v195, v155
	v_cvt_pk_bf16_f32 v153, v153, v154
	v_mul_f32_e32 v154, v195, v156
	v_mul_f32_e32 v155, v195, v157
	v_cvt_pk_bf16_f32 v154, v154, v155
	v_mul_f32_e32 v155, v195, v158
	v_mul_f32_e32 v156, v195, v159
	v_cvt_pk_bf16_f32 v155, v155, v156
	v_lshlrev_b64 v[156:157], 12, v[186:187]
	v_lshl_add_u64 v[156:157], s[18:19], 0, v[156:157]
	v_lshl_add_u64 v[156:157], v[178:179], 1, v[156:157]
	global_store_dwordx4 v[156:157], v[152:155], off

; #define PG8_STAGE(bufoff, gbase, voff) do { _Pragma("unroll") for (int _i = 0; _i < 2; ++_i) \
;     __builtin_amdgcn_global_load_lds((const unsigned*)((const char*)(gbase) + (voff)[_i]), (LAS unsigned*)(lds + (bufoff) + ldsw + _i * 8192), 16, 0, 0); } while (0)
; #define PG8_LDA(dst, b, h) do { _Pragma("unroll") for (int m = 0; m < 4; ++m) _Pragma("unroll") for (int k = 0; k < 2; ++k) dst[m][k] = *(const LAS bf16x8*)(lds + PG8_SA(b, h) + aoff + m * 2048 + k * 1024); } while (0)
; #define PG8_LDB(dst, b, h) do { _Pragma("unroll") for (int n = 0; n < 2; ++n) _Pragma("unroll") for (int k = 0; k < 2; ++k) dst[n][k] = *(const LAS bf16x8*)(lds + PG8_SB(b, h) + boff + n * 2048 + k * 1024); } while (0)
; #define PG8_MMA(ai, bj, At, Bt) do { __builtin_amdgcn_s_setprio(1); _Pragma("unroll") for (int m = 0; m < 4; ++m) _Pragma("unroll") for (int n = 0; n < 2; ++n) _Pragma("unroll") for (int k = 0; k < 2; ++k) \
;     acc[ai][bj][m][n] = __builtin_amdgcn_mfma_f32_16x16x32_bf16(Bt[n][k], At[m][k], acc[ai][bj][m][n], 0, 0, 0); __builtin_amdgcn_s_setprio(0); } while (0)
; #define PG8_WAIT_V(n) asm volatile("s_waitcnt vmcnt(" #n ")" ::: "memory")
; #define PG8_WAIT_L(n) asm volatile("s_waitcnt lgkmcnt(" #n ")" ::: "memory")
; #define PG8_BAR __builtin_amdgcn_s_barrier()
; #define PG8_SCHED __builtin_amdgcn_sched_barrier(0)
; template <class Epi, class Sched = StaticOrder>
; DI void gemm_phase(LAS unsigned char* lds, const Gemm g, const Sched& S, const Epi& E) {
;     ...
;       PG8_LDB(B0, 0, 0); PG8_SCHED; PG8_LDA(At, 0, 0); PG8_STAGE(PG8_SA(1, 1), a1 + hstep, voffA);
;       PG8_WAIT_L(8); PG8_BAR; PG8_WAIT_L(0); PG8_MMA(0, 0, At, B0); PG8_BAR; PG8_SCHED;
;       PG8_LDB(B1, 0, 1); PG8_STAGE(PG8_SB(0, 0), b2, voffB);
;       PG8_BAR; PG8_WAIT_L(0); PG8_MMA(0, 1, At, B1); PG8_BAR;
;       PG8_LDA(At, 0, 1); PG8_STAGE(PG8_SA(0, 0), a2, voffA);
;       PG8_BAR; PG8_WAIT_L(0); PG8_MMA(1, 0, At, B0); PG8_BAR; PG8_SCHED;
;       PG8_STAGE(PG8_SB(0, 1), b2 + hstep, voffB);
;       PG8_WAIT_V(6); PG8_BAR; PG8_MMA(1, 1, At, B1); PG8_BAR;
.LBB0_1194:
	s_add_u32 s24, s22, 0xfff80080
	s_addc_u32 s25, s23, -1
	s_cmp_eq_u32 s54, 28
	s_cselect_b32 s27, s17, s25
	s_cselect_b32 s26, s43, s24
	s_cselect_b32 s25, s15, s53
	s_cselect_b32 s24, s51, s52
	v_lshl_add_u64 v[192:193], s[22:23], 0, v[184:185]
	s_add_i32 m0, s37, 0xc000
	ds_read_b128 v[144:147], v215
	ds_read_b128 v[148:151], v215 offset:1024
	ds_read_b128 v[152:155], v215 offset:2048
	ds_read_b128 v[156:159], v215 offset:3072
	ds_read_b128 v[160:163], v215 offset:4096
	ds_read_b128 v[164:167], v215 offset:5120
	ds_read_b128 v[168:171], v215 offset:6144
	ds_read_b128 v[172:175], v215 offset:7168
	global_load_lds_dwordx4 v[192:193], off
	v_lshl_add_u64 v[192:193], s[22:23], 0, v[186:187]
	s_add_i32 m0, s37, 0xe000
	s_nop 0
	global_load_lds_dwordx4 v[192:193], off
	s_waitcnt lgkmcnt(8)
	s_barrier
	s_waitcnt lgkmcnt(0)
	s_setprio 1
	v_mfma_f32_16x16x32_bf16 v[124:127], v[128:131], v[144:147], v[124:127]
	v_mfma_f32_16x16x32_bf16 v[120:123], v[136:139], v[144:147], v[120:123]
	v_mfma_f32_16x16x32_bf16 v[108:111], v[128:131], v[152:155], v[108:111]
	v_mfma_f32_16x16x32_bf16 v[104:107], v[136:139], v[152:155], v[104:107]
	v_mfma_f32_16x16x32_bf16 v[92:95], v[128:131], v[160:163], v[92:95]
	v_mfma_f32_16x16x32_bf16 v[88:91], v[136:139], v[160:163], v[88:91]
	v_mfma_f32_16x16x32_bf16 v[76:79], v[128:131], v[168:171], v[76:79]
	v_mfma_f32_16x16x32_bf16 v[72:75], v[136:139], v[168:171], v[72:75]
	v_mfma_f32_16x16x32_bf16 v[124:127], v[132:135], v[148:151], v[124:127]
	v_mfma_f32_16x16x32_bf16 v[120:123], v[140:143], v[148:151], v[120:123]
	v_mfma_f32_16x16x32_bf16 v[108:111], v[132:135], v[156:159], v[108:111]
	v_mfma_f32_16x16x32_bf16 v[104:107], v[140:143], v[156:159], v[104:107]
	v_mfma_f32_16x16x32_bf16 v[92:95], v[132:135], v[164:167], v[92:95]
	v_mfma_f32_16x16x32_bf16 v[88:91], v[140:143], v[164:167], v[88:91]
	v_mfma_f32_16x16x32_bf16 v[76:79], v[132:135], v[172:175], v[76:79]
	v_mfma_f32_16x16x32_bf16 v[72:75], v[140:143], v[172:175], v[72:75]
	s_barrier
	s_setprio 0
	s_add_i32 s55, s48, s35
	v_lshl_add_u64 v[208:209], s[24:25], 0, v[180:181]
	s_mov_b32 m0, s55
	ds_read_b128 v[192:195], v216
	ds_read_b128 v[196:199], v216 offset:1024
	ds_read_b128 v[200:203], v216 offset:2048
	ds_read_b128 v[204:207], v216 offset:3072
	global_load_lds_dwordx4 v[208:209], off
	v_lshl_add_u64 v[218:219], s[24:25], 0, v[176:177]
	s_add_i32 m0, s55, 0x2000
	s_nop 0
	global_load_lds_dwordx4 v[218:219], off
	s_barrier
	s_waitcnt lgkmcnt(0)
	s_setprio 1
	v_mfma_f32_16x16x32_bf16 v[116:119], v[192:195], v[144:147], v[116:119]
	v_mfma_f32_16x16x32_bf16 v[112:115], v[200:203], v[144:147], v[112:115]
	v_mfma_f32_16x16x32_bf16 v[100:103], v[192:195], v[152:155], v[100:103]
	v_mfma_f32_16x16x32_bf16 v[96:99], v[200:203], v[152:155], v[96:99]
	v_mfma_f32_16x16x32_bf16 v[84:87], v[192:195], v[160:163], v[84:87]
	v_mfma_f32_16x16x32_bf16 v[80:83], v[200:203], v[160:163], v[80:83]
	v_mfma_f32_16x16x32_bf16 v[68:71], v[192:195], v[168:171], v[68:71]
	v_mfma_f32_16x16x32_bf16 v[64:67], v[200:203], v[168:171], v[64:67]
	v_mfma_f32_16x16x32_bf16 v[116:119], v[196:199], v[148:151], v[116:119]
	v_mfma_f32_16x16x32_bf16 v[112:115], v[204:207], v[148:151], v[112:115]
	v_mfma_f32_16x16x32_bf16 v[100:103], v[196:199], v[156:159], v[100:103]
	v_mfma_f32_16x16x32_bf16 v[96:99], v[204:207], v[156:159], v[96:99]
	v_mfma_f32_16x16x32_bf16 v[84:87], v[196:199], v[164:167], v[84:87]
	v_mfma_f32_16x16x32_bf16 v[80:83], v[204:207], v[164:167], v[80:83]
	v_mfma_f32_16x16x32_bf16 v[68:71], v[196:199], v[172:175], v[68:71]
	v_mfma_f32_16x16x32_bf16 v[64:67], v[204:207], v[172:175], v[64:67]
	s_barrier
	s_setprio 0
	s_mov_b32 m0, s37
	v_lshl_add_u64 v[220:221], s[26:27], 0, v[182:183]
	ds_read_b128 v[144:147], v215 offset:16384
	ds_read_b128 v[148:151], v215 offset:17408
	ds_read_b128 v[152:155], v215 offset:18432
	ds_read_b128 v[156:159], v215 offset:19456
	ds_read_b128 v[160:163], v215 offset:20480
	ds_read_b128 v[164:167], v215 offset:21504
	ds_read_b128 v[168:171], v215 offset:22528
	ds_read_b128 v[172:175], v215 offset:23552
	global_load_lds_dwordx4 v[220:221], off
	v_lshl_add_u64 v[222:223], s[26:27], 0, v[178:179]
	s_mov_b32 m0, s38
	s_nop 0
	global_load_lds_dwordx4 v[222:223], off
	s_waitcnt vmcnt(10)
	s_barrier
	s_waitcnt lgkmcnt(0)
	s_setprio 1
	v_mfma_f32_16x16x32_bf16 v[60:63], v[128:131], v[144:147], v[60:63]
	v_mfma_f32_16x16x32_bf16 v[56:59], v[136:139], v[144:147], v[56:59]
	v_mfma_f32_16x16x32_bf16 v[44:47], v[128:131], v[152:155], v[44:47]
	v_mfma_f32_16x16x32_bf16 v[40:43], v[136:139], v[152:155], v[40:43]
	v_mfma_f32_16x16x32_bf16 v[28:31], v[128:131], v[160:163], v[28:31]
	v_mfma_f32_16x16x32_bf16 v[24:27], v[136:139], v[160:163], v[24:27]
	v_mfma_f32_16x16x32_bf16 v[12:15], v[128:131], v[168:171], v[12:15]
	v_mfma_f32_16x16x32_bf16 v[8:11], v[136:139], v[168:171], v[8:11]
	v_mfma_f32_16x16x32_bf16 v[60:63], v[132:135], v[148:151], v[60:63]
	v_mfma_f32_16x16x32_bf16 v[56:59], v[140:143], v[148:151], v[56:59]
	v_mfma_f32_16x16x32_bf16 v[44:47], v[132:135], v[156:159], v[44:47]
	v_mfma_f32_16x16x32_bf16 v[40:43], v[140:143], v[156:159], v[40:43]
	v_mfma_f32_16x16x32_bf16 v[28:31], v[132:135], v[164:167], v[28:31]
	v_mfma_f32_16x16x32_bf16 v[24:27], v[140:143], v[164:167], v[24:27]
	v_mfma_f32_16x16x32_bf16 v[12:15], v[132:135], v[172:175], v[12:15]
	v_mfma_f32_16x16x32_bf16 v[8:11], v[140:143], v[172:175], v[8:11]
	s_barrier
; #define PG8_STAGE(bufoff, gbase, voff) do { _Pragma("unroll") for (int _i = 0; _i < 2; ++_i) \
;     __builtin_amdgcn_global_load_lds((const unsigned*)((const char*)(gbase) + (voff)[_i]), (LAS unsigned*)(lds + (bufoff) + ldsw + _i * 8192), 16, 0, 0); } while (0)
; #define PG8_LDA(dst, b, h) do { _Pragma("unroll") for (int m = 0; m < 4; ++m) _Pragma("unroll") for (int k = 0; k < 2; ++k) dst[m][k] = *(const LAS bf16x8*)(lds + PG8_SA(b, h) + aoff + m * 2048 + k * 1024); } while (0)
; #define PG8_LDB(dst, b, h) do { _Pragma("unroll") for (int n = 0; n < 2; ++n) _Pragma("unroll") for (int k = 0; k < 2; ++k) dst[n][k] = *(const LAS bf16x8*)(lds + PG8_SB(b, h) + boff + n * 2048 + k * 1024); } while (0)
; #define PG8_MMA(ai, bj, At, Bt) do { __builtin_amdgcn_s_setprio(1); _Pragma("unroll") for (int m = 0; m < 4; ++m) _Pragma("unroll") for (int n = 0; n < 2; ++n) _Pragma("unroll") for (int k = 0; k < 2; ++k) \
;     acc[ai][bj][m][n] = __builtin_amdgcn_mfma_f32_16x16x32_bf16(Bt[n][k], At[m][k], acc[ai][bj][m][n], 0, 0, 0); __builtin_amdgcn_s_setprio(0); } while (0)
; #define PG8_WAIT_V(n) asm volatile("s_waitcnt vmcnt(" #n ")" ::: "memory")
; #define PG8_WAIT_L(n) asm volatile("s_waitcnt lgkmcnt(" #n ")" ::: "memory")
; #define PG8_BAR __builtin_amdgcn_s_barrier()
; #define PG8_SCHED __builtin_amdgcn_sched_barrier(0)
; template <class Epi, class Sched = StaticOrder>
; DI void gemm_phase(LAS unsigned char* lds, const Gemm g, const Sched& S, const Epi& E) {
;     ...
;       PG8_WAIT_V(6); PG8_BAR; PG8_MMA(1, 1, At, B1); PG8_BAR;
;       PG8_LDB(B0, 1, 0); PG8_SCHED; PG8_LDA(At, 1, 0); PG8_STAGE(PG8_SA(0, 1), a2 + hstep, voffA);
;       PG8_WAIT_L(8); PG8_BAR; PG8_WAIT_L(0); PG8_MMA(0, 0, At, B0); PG8_BAR; PG8_SCHED;
;       PG8_LDB(B1, 1, 1); PG8_STAGE(PG8_SB(1, 0), b3, voffB);
;       PG8_BAR; PG8_WAIT_L(0); PG8_MMA(0, 1, At, B1); PG8_BAR;
;       PG8_LDA(At, 1, 1); PG8_STAGE(PG8_SA(1, 0), a3, voffA);
	s_setprio 0
	s_add_u32 s56, s24, 0x80000
	s_addc_u32 s57, s25, 0
	s_add_i32 s55, s49, s35
	v_lshl_add_u64 v[128:129], s[56:57], 0, v[180:181]
	s_mov_b32 m0, s55
	s_nop 0
	global_load_lds_dwordx4 v[128:129], off
	v_lshl_add_u64 v[128:129], s[56:57], 0, v[176:177]
	s_add_i32 m0, s55, 0x2000
	s_nop 0
	global_load_lds_dwordx4 v[128:129], off
	s_add_i32 s55, 0, 0x18000
	v_add_u32_e32 v140, s55, v212
	ds_read_b128 v[128:131], v140
	ds_read_b128 v[132:135], v140 offset:1024
	ds_read_b128 v[136:139], v140 offset:2048
	ds_read_b128 v[140:143], v140 offset:3072
	s_waitcnt vmcnt(6)
	s_barrier
	s_setprio 1
	v_mfma_f32_16x16x32_bf16 v[52:55], v[192:195], v[144:147], v[52:55]
	v_mfma_f32_16x16x32_bf16 v[48:51], v[200:203], v[144:147], v[48:51]
	v_mfma_f32_16x16x32_bf16 v[36:39], v[192:195], v[152:155], v[36:39]
	v_mfma_f32_16x16x32_bf16 v[32:35], v[200:203], v[152:155], v[32:35]
	v_mfma_f32_16x16x32_bf16 v[20:23], v[192:195], v[160:163], v[20:23]
	v_mfma_f32_16x16x32_bf16 v[16:19], v[200:203], v[160:163], v[16:19]
	v_mfma_f32_16x16x32_bf16 v[4:7], v[192:195], v[168:171], v[4:7]
	v_mfma_f32_16x16x32_bf16 v[0:3], v[200:203], v[168:171], v[0:3]
	v_mfma_f32_16x16x32_bf16 v[52:55], v[196:199], v[148:151], v[52:55]
	v_mfma_f32_16x16x32_bf16 v[48:51], v[204:207], v[148:151], v[48:51]
	v_mfma_f32_16x16x32_bf16 v[36:39], v[196:199], v[156:159], v[36:39]
	v_mfma_f32_16x16x32_bf16 v[32:35], v[204:207], v[156:159], v[32:35]
	v_mfma_f32_16x16x32_bf16 v[20:23], v[196:199], v[164:167], v[20:23]
	v_mfma_f32_16x16x32_bf16 v[16:19], v[204:207], v[164:167], v[16:19]
	v_mfma_f32_16x16x32_bf16 v[4:7], v[196:199], v[172:175], v[4:7]
	v_mfma_f32_16x16x32_bf16 v[0:3], v[204:207], v[172:175], v[0:3]
	s_barrier
	s_setprio 0
	s_add_u32 s26, s26, 0x80000
	s_addc_u32 s27, s27, 0
	s_mov_b32 m0, s39
	v_lshl_add_u64 v[192:193], s[26:27], 0, v[182:183]
	ds_read_b128 v[144:147], v215 offset:32768
	ds_read_b128 v[148:151], v215 offset:33792
	ds_read_b128 v[152:155], v215 offset:34816
	ds_read_b128 v[156:159], v215 offset:35840
	ds_read_b128 v[160:163], v215 offset:36864
	ds_read_b128 v[164:167], v215 offset:37888
	ds_read_b128 v[168:171], v215 offset:38912
	ds_read_b128 v[172:175], v215 offset:39936
	global_load_lds_dwordx4 v[192:193], off
	v_lshl_add_u64 v[192:193], s[26:27], 0, v[178:179]
	s_mov_b32 m0, s40
	s_nop 0
	global_load_lds_dwordx4 v[192:193], off
	s_waitcnt lgkmcnt(8)
	s_barrier
	s_waitcnt lgkmcnt(0)
	s_setprio 1
	v_mfma_f32_16x16x32_bf16 v[124:127], v[128:131], v[144:147], v[124:127]
	v_mfma_f32_16x16x32_bf16 v[120:123], v[136:139], v[144:147], v[120:123]
	v_mfma_f32_16x16x32_bf16 v[108:111], v[128:131], v[152:155], v[108:111]
	v_mfma_f32_16x16x32_bf16 v[104:107], v[136:139], v[152:155], v[104:107]
	v_mfma_f32_16x16x32_bf16 v[92:95], v[128:131], v[160:163], v[92:95]
	v_mfma_f32_16x16x32_bf16 v[88:91], v[136:139], v[160:163], v[88:91]
	v_mfma_f32_16x16x32_bf16 v[76:79], v[128:131], v[168:171], v[76:79]
	v_mfma_f32_16x16x32_bf16 v[72:75], v[136:139], v[168:171], v[72:75]
	v_mfma_f32_16x16x32_bf16 v[124:127], v[132:135], v[148:151], v[124:127]
	v_mfma_f32_16x16x32_bf16 v[120:123], v[140:143], v[148:151], v[120:123]
	v_mfma_f32_16x16x32_bf16 v[108:111], v[132:135], v[156:159], v[108:111]
	v_mfma_f32_16x16x32_bf16 v[104:107], v[140:143], v[156:159], v[104:107]
	v_mfma_f32_16x16x32_bf16 v[92:95], v[132:135], v[164:167], v[92:95]
	v_mfma_f32_16x16x32_bf16 v[88:91], v[140:143], v[164:167], v[88:91]
	v_mfma_f32_16x16x32_bf16 v[76:79], v[132:135], v[172:175], v[76:79]
	v_mfma_f32_16x16x32_bf16 v[72:75], v[140:143], v[172:175], v[72:75]
	s_barrier
	s_setprio 0
	s_add_i32 s26, 0, 0x1c000
	s_add_i32 s27, s55, s35
	v_add_u32_e32 v204, s26, v212
	v_lshl_add_u64 v[208:209], v[208:209], 0, s[10:11]
	s_mov_b32 m0, s27
	ds_read_b128 v[192:195], v204
	ds_read_b128 v[196:199], v204 offset:1024
	ds_read_b128 v[200:203], v204 offset:2048
	ds_read_b128 v[204:207], v204 offset:3072
	global_load_lds_dwordx4 v[208:209], off
	v_lshl_add_u64 v[208:209], v[218:219], 0, s[10:11]
	s_add_i32 m0, s27, 0x2000
	s_nop 0
	global_load_lds_dwordx4 v[208:209], off
	s_barrier
	s_waitcnt lgkmcnt(0)
	s_setprio 1
	v_mfma_f32_16x16x32_bf16 v[116:119], v[192:195], v[144:147], v[116:119]
	v_mfma_f32_16x16x32_bf16 v[112:115], v[200:203], v[144:147], v[112:115]
	v_mfma_f32_16x16x32_bf16 v[100:103], v[192:195], v[152:155], v[100:103]
	v_mfma_f32_16x16x32_bf16 v[96:99], v[200:203], v[152:155], v[96:99]
	v_mfma_f32_16x16x32_bf16 v[84:87], v[192:195], v[160:163], v[84:87]
	v_mfma_f32_16x16x32_bf16 v[80:83], v[200:203], v[160:163], v[80:83]
	v_mfma_f32_16x16x32_bf16 v[68:71], v[192:195], v[168:171], v[68:71]
	v_mfma_f32_16x16x32_bf16 v[64:67], v[200:203], v[168:171], v[64:67]
	v_mfma_f32_16x16x32_bf16 v[116:119], v[196:199], v[148:151], v[116:119]
	v_mfma_f32_16x16x32_bf16 v[112:115], v[204:207], v[148:151], v[112:115]
	v_mfma_f32_16x16x32_bf16 v[100:103], v[196:199], v[156:159], v[100:103]
	v_mfma_f32_16x16x32_bf16 v[96:99], v[204:207], v[156:159], v[96:99]
	v_mfma_f32_16x16x32_bf16 v[84:87], v[196:199], v[164:167], v[84:87]
	v_mfma_f32_16x16x32_bf16 v[80:83], v[204:207], v[164:167], v[80:83]
	v_mfma_f32_16x16x32_bf16 v[68:71], v[196:199], v[172:175], v[68:71]
	v_mfma_f32_16x16x32_bf16 v[64:67], v[204:207], v[172:175], v[64:67]
	s_barrier
	s_setprio 0
	s_mov_b32 m0, s44
	v_lshl_add_u64 v[208:209], v[220:221], 0, s[10:11]
	ds_read_b128 v[144:147], v215 offset:49152
	ds_read_b128 v[148:151], v215 offset:50176
	ds_read_b128 v[152:155], v215 offset:51200
	ds_read_b128 v[156:159], v215 offset:52224
	ds_read_b128 v[160:163], v215 offset:53248
	ds_read_b128 v[164:167], v215 offset:54272
	ds_read_b128 v[168:171], v215 offset:55296
	ds_read_b128 v[172:175], v215 offset:56320
	global_load_lds_dwordx4 v[208:209], off
	v_lshl_add_u64 v[208:209], v[222:223], 0, s[10:11]
	s_mov_b32 m0, s45
	s_nop 0
	global_load_lds_dwordx4 v[208:209], off
	s_waitcnt vmcnt(10)
	s_barrier
; #define PG8_STAGE(bufoff, gbase, voff) do { _Pragma("unroll") for (int _i = 0; _i < 2; ++_i) \
;     __builtin_amdgcn_global_load_lds((const unsigned*)((const char*)(gbase) + (voff)[_i]), (LAS unsigned*)(lds + (bufoff) + ldsw + _i * 8192), 16, 0, 0); } while (0)
; #define PG8_LDA(dst, b, h) do { _Pragma("unroll") for (int m = 0; m < 4; ++m) _Pragma("unroll") for (int k = 0; k < 2; ++k) dst[m][k] = *(const LAS bf16x8*)(lds + PG8_SA(b, h) + aoff + m * 2048 + k * 1024); } while (0)
; #define PG8_MMA(ai, bj, At, Bt) do { __builtin_amdgcn_s_setprio(1); _Pragma("unroll") for (int m = 0; m < 4; ++m) _Pragma("unroll") for (int n = 0; n < 2; ++n) _Pragma("unroll") for (int k = 0; k < 2; ++k) \
;     acc[ai][bj][m][n] = __builtin_amdgcn_mfma_f32_16x16x32_bf16(Bt[n][k], At[m][k], acc[ai][bj][m][n], 0, 0, 0); __builtin_amdgcn_s_setprio(0); } while (0)
; #define PG8_WAIT_V(n) asm volatile("s_waitcnt vmcnt(" #n ")" ::: "memory")
; #define PG8_WAIT_L(n) asm volatile("s_waitcnt lgkmcnt(" #n ")" ::: "memory")
; #define PG8_BAR __builtin_amdgcn_s_barrier()
; #define PG8_SCHED __builtin_amdgcn_sched_barrier(0)
; template <class Epi, class Sched = StaticOrder>
; DI void gemm_phase(LAS unsigned char* lds, const Gemm g, const Sched& S, const Epi& E) {
;     ...
;       PG8_LDA(At, 1, 1); PG8_STAGE(PG8_SA(1, 0), a3, voffA);
;       PG8_BAR; PG8_WAIT_L(0); PG8_MMA(1, 0, At, B0); PG8_BAR; PG8_SCHED;
;       PG8_STAGE(PG8_SB(1, 1), b3 + hstep, voffB);
;       PG8_WAIT_V(6); PG8_BAR; PG8_MMA(1, 1, At, B1); PG8_BAR;
	s_waitcnt lgkmcnt(0)
	s_setprio 1
	v_mfma_f32_16x16x32_bf16 v[60:63], v[128:131], v[144:147], v[60:63]
	v_mfma_f32_16x16x32_bf16 v[56:59], v[136:139], v[144:147], v[56:59]
	v_mfma_f32_16x16x32_bf16 v[44:47], v[128:131], v[152:155], v[44:47]
	v_mfma_f32_16x16x32_bf16 v[40:43], v[136:139], v[152:155], v[40:43]
	v_mfma_f32_16x16x32_bf16 v[28:31], v[128:131], v[160:163], v[28:31]
	v_mfma_f32_16x16x32_bf16 v[24:27], v[136:139], v[160:163], v[24:27]
	v_mfma_f32_16x16x32_bf16 v[12:15], v[128:131], v[168:171], v[12:15]
	v_mfma_f32_16x16x32_bf16 v[8:11], v[136:139], v[168:171], v[8:11]
	v_mfma_f32_16x16x32_bf16 v[60:63], v[132:135], v[148:151], v[60:63]
	v_mfma_f32_16x16x32_bf16 v[56:59], v[140:143], v[148:151], v[56:59]
	v_mfma_f32_16x16x32_bf16 v[44:47], v[132:135], v[156:159], v[44:47]
	v_mfma_f32_16x16x32_bf16 v[40:43], v[140:143], v[156:159], v[40:43]
	v_mfma_f32_16x16x32_bf16 v[28:31], v[132:135], v[164:167], v[28:31]
	v_mfma_f32_16x16x32_bf16 v[24:27], v[140:143], v[164:167], v[24:27]
	v_mfma_f32_16x16x32_bf16 v[12:15], v[132:135], v[172:175], v[12:15]
	v_mfma_f32_16x16x32_bf16 v[8:11], v[140:143], v[172:175], v[8:11]
	s_barrier
	s_setprio 0
	s_add_u32 s24, s24, 0x80080
	s_addc_u32 s25, s25, 0
	s_add_i32 s26, s26, s35
	v_lshl_add_u64 v[128:129], s[24:25], 0, v[180:181]
	s_mov_b32 m0, s26
	s_nop 0
	global_load_lds_dwordx4 v[128:129], off
	v_lshl_add_u64 v[128:129], s[24:25], 0, v[176:177]
	s_add_i32 m0, s26, 0x2000
	s_nop 0
	global_load_lds_dwordx4 v[128:129], off
	ds_read_b128 v[128:131], v214
	ds_read_b128 v[132:135], v214 offset:1024
	ds_read_b128 v[136:139], v214 offset:2048
	ds_read_b128 v[140:143], v214 offset:3072
	s_waitcnt vmcnt(6)
	s_barrier
	s_setprio 1
	v_mfma_f32_16x16x32_bf16 v[52:55], v[192:195], v[144:147], v[52:55]
	v_mfma_f32_16x16x32_bf16 v[48:51], v[200:203], v[144:147], v[48:51]
	v_mfma_f32_16x16x32_bf16 v[36:39], v[192:195], v[152:155], v[36:39]
	v_mfma_f32_16x16x32_bf16 v[32:35], v[200:203], v[152:155], v[32:35]
	v_mfma_f32_16x16x32_bf16 v[20:23], v[192:195], v[160:163], v[20:23]
	v_mfma_f32_16x16x32_bf16 v[16:19], v[200:203], v[160:163], v[16:19]
	v_mfma_f32_16x16x32_bf16 v[4:7], v[192:195], v[168:171], v[4:7]
	v_mfma_f32_16x16x32_bf16 v[0:3], v[200:203], v[168:171], v[0:3]
	v_mfma_f32_16x16x32_bf16 v[52:55], v[196:199], v[148:151], v[52:55]
	v_mfma_f32_16x16x32_bf16 v[48:51], v[204:207], v[148:151], v[48:51]
	v_mfma_f32_16x16x32_bf16 v[36:39], v[196:199], v[156:159], v[36:39]
	v_mfma_f32_16x16x32_bf16 v[32:35], v[204:207], v[156:159], v[32:35]
	v_mfma_f32_16x16x32_bf16 v[20:23], v[196:199], v[164:167], v[20:23]
	v_mfma_f32_16x16x32_bf16 v[16:19], v[204:207], v[164:167], v[16:19]
	v_mfma_f32_16x16x32_bf16 v[4:7], v[196:199], v[172:175], v[4:7]
	v_mfma_f32_16x16x32_bf16 v[0:3], v[204:207], v[172:175], v[0:3]
	s_add_i32 s54, s54, 2
	s_add_u32 s22, s22, 0x100
	s_addc_u32 s23, s23, 0
	s_add_u32 s52, s52, 0x100
	s_addc_u32 s53, s53, 0
	s_cmp_gt_u32 s54, 29
	s_barrier
	s_setprio 0
	s_cbranch_scc0 .LBB0_1194
; DI unsigned pack2(float lo, float hi) { f32x2 v = {lo, hi}; bf16v2 r = __builtin_convertvector(v, bf16v2); return __builtin_bit_cast(unsigned, r); }
;   DI void operator()(const f32x4 (&acc)[2][2][4][2], const Unit& u, int wr, int wc, int fr, int fq) const {
;     const int row0 = u.pm * BM + wr * 64 + fr, col0 = u.pn * BM + wc * 32 + 8 * fq;
; #pragma unroll
;     for (int ai = 0; ai < 2; ++ai) {
;       f32x4 bv[4][2][2];
; #pragma unroll
;       for (int m = 0; m < 4; ++m)
; #pragma unroll
;         for (int bj = 0; bj < 2; ++bj) {
;           const float* bp = base + (size_t)(row0 + ai * HALF + m * 16) * 2048 + col0 + bj * HALF;
;           bv[m][bj][0] = *(const f32x4*)bp; bv[m][bj][1] = *(const f32x4*)(bp + 4);
;         }
; #pragma unroll
;       for (int m = 0; m < 4; ++m) {
;         const int row = row0 + ai * HALF + m * 16;
;         const size_t off = (size_t)row * 2048 + col0;
;         float ss = 0.f;
; #pragma unroll
;         for (int bj = 0; bj < 2; ++bj) {
;           const f32x4 v0 = acc[ai][bj][m][0] + bv[m][bj][0], v1 = acc[ai][bj][m][1] + bv[m][bj][1];
;           *(f32x4*)(C + off + bj * HALF) = v0; *(f32x4*)(C + off + bj * HALF + 4) = v1;
;           if (xb) {
;             u32x4 w; w.x = pack2(v0[0], v0[1]); w.y = pack2(v0[2], v0[3]); w.z = pack2(v1[0], v1[1]); w.w = pack2(v1[2], v1[3]);
;             *(u32x4*)(xb + off + bj * HALF) = w;
;             ss += v0[0] * v0[0] + v0[1] * v0[1] + v0[2] * v0[2] + v0[3] * v0[3] + v1[0] * v1[0] + v1[1] * v1[1] + v1[2] * v1[2] + v1[3] * v1[3];
;           }
;         }
;         if (xb) {
;           ss += __shfl_xor(ss, 16); ss += __shfl_xor(ss, 32);
;           if (fq == 0) ssq[(size_t)row * 32 + u.pn * 4 + wc] = ss;
;         }
	s_waitcnt lgkmcnt(0)
	v_lshl_add_u32 v194, s12, 8, v211
	v_lshl_or_b32 v192, s42, 8, v213
	v_readlane_b32 s52, v243, 3
	v_ashrrev_i32_e32 v193, 31, v192
	v_readlane_b32 s66, v243, 17
	v_readlane_b32 s67, v243, 18
	v_ashrrev_i32_e32 v195, 31, v194
	v_lshlrev_b64 v[128:129], 13, v[194:195]
	v_lshl_add_u64 v[196:197], v[192:193], 2, s[66:67]
	v_lshl_add_u64 v[236:237], v[196:197], 0, v[128:129]
	global_load_dwordx4 v[220:223], v[236:237], off
	global_load_dwordx4 v[224:227], v[236:237], off offset:16
	global_load_dwordx4 v[228:231], v[236:237], off offset:512
	global_load_dwordx4 v[232:235], v[236:237], off offset:528
	v_or_b32_e32 v206, 16, v194
	v_or_b32_e32 v202, 32, v194
	v_or_b32_e32 v198, 48, v194
	v_ashrrev_i32_e32 v207, 31, v206
	v_ashrrev_i32_e32 v203, 31, v202
	v_ashrrev_i32_e32 v199, 31, v198
	v_lshlrev_b64 v[128:129], 13, v[206:207]
	v_lshlrev_b64 v[130:131], 13, v[202:203]
	v_lshlrev_b64 v[132:133], 13, v[198:199]
	v_lshl_add_u64 v[208:209], v[196:197], 0, v[128:129]
	v_lshl_add_u64 v[204:205], v[196:197], 0, v[130:131]
	v_lshl_add_u64 v[200:201], v[196:197], 0, v[132:133]
	global_load_dwordx4 v[168:171], v[208:209], off offset:16
	global_load_dwordx4 v[172:175], v[208:209], off
	global_load_dwordx4 v[160:163], v[208:209], off offset:528
	global_load_dwordx4 v[164:167], v[208:209], off offset:512
	global_load_dwordx4 v[152:155], v[204:205], off offset:16
	global_load_dwordx4 v[156:159], v[204:205], off
	global_load_dwordx4 v[144:147], v[204:205], off offset:528
	global_load_dwordx4 v[148:151], v[204:205], off offset:512
	global_load_dwordx4 v[136:139], v[200:201], off offset:16
	global_load_dwordx4 v[140:143], v[200:201], off
	global_load_dwordx4 v[128:131], v[200:201], off offset:528
	global_load_dwordx4 v[132:135], v[200:201], off offset:512
	v_and_b32_e32 v218, 64, v217
	v_xor_b32_e32 v238, 16, v217
	v_add_u32_e32 v240, 64, v218
	v_xor_b32_e32 v239, 32, v217
	v_cmp_lt_i32_e32 vcc, v238, v240
	v_lshlrev_b64 v[218:219], 11, v[194:195]
	s_lshl_b32 s22, s42, 2
	v_cndmask_b32_e32 v241, v217, v238, vcc
	v_cmp_lt_i32_e32 vcc, v239, v240
	s_ashr_i32 s23, s22, 31
	v_readlane_b32 s53, v243, 4
	v_cndmask_b32_e32 v240, v217, v239, vcc
	v_lshl_add_u64 v[238:239], v[218:219], 0, v[192:193]
	v_lshlrev_b32_e32 v218, 2, v241
	v_lshl_add_u64 v[238:239], v[238:239], 1, s[2:3]
	v_readlane_b32 s54, v243, 5
	v_readlane_b32 s55, v243, 6
	v_readlane_b32 s56, v243, 7
	v_readlane_b32 s57, v243, 8
	v_readlane_b32 s58, v243, 9
	v_readlane_b32 s59, v243, 10
	v_readlane_b32 s60, v243, 11
	v_readlane_b32 s61, v243, 12
	v_readlane_b32 s62, v243, 13
	v_readlane_b32 s63, v243, 14
	v_readlane_b32 s64, v243, 15
	v_readlane_b32 s65, v243, 16
	s_waitcnt vmcnt(0)
	v_pk_add_f32 v[126:127], v[126:127], v[222:223]
	v_pk_add_f32 v[124:125], v[124:125], v[220:221]
	v_pk_add_f32 v[116:117], v[116:117], v[228:229]
	v_pk_add_f32 v[122:123], v[122:123], v[226:227]
	v_pk_add_f32 v[120:121], v[120:121], v[224:225]
	v_pk_add_f32 v[220:221], v[112:113], v[232:233]
	global_store_dwordx4 v[236:237], v[124:127], off
	global_store_dwordx4 v[236:237], v[120:123], off offset:16
	v_cvt_pk_bf16_f32 v112, v124, v125
	v_mul_f32_e32 v125, v125, v125
	v_mul_f32_e32 v219, v117, v117
	v_pk_add_f32 v[118:119], v[118:119], v[230:231]
	v_fmac_f32_e32 v125, v124, v124
	v_fmac_f32_e32 v219, v116, v116
	v_fmac_f32_e32 v125, v126, v126
	v_fmac_f32_e32 v219, v118, v118
	v_fmac_f32_e32 v125, v127, v127
	v_fmac_f32_e32 v219, v119, v119
	v_fmac_f32_e32 v125, v120, v120
	v_fmac_f32_e32 v219, v220, v220
	v_pk_add_f32 v[222:223], v[114:115], v[234:235]
	v_fmac_f32_e32 v125, v121, v121
	v_fmac_f32_e32 v219, v221, v221
	v_fmac_f32_e32 v125, v122, v122
	v_fmac_f32_e32 v219, v222, v222
	v_fmac_f32_e32 v125, v123, v123
	v_fmac_f32_e32 v219, v223, v223
	v_cvt_pk_bf16_f32 v114, v120, v121
	v_add_f32_e32 v121, v125, v219
	v_cvt_pk_bf16_f32 v115, v122, v123
	ds_bpermute_b32 v122, v218, v121
	v_cvt_pk_bf16_f32 v113, v126, v127
	global_store_dwordx4 v[238:239], v[112:115], off
	global_store_dwordx4 v[236:237], v[116:119], off offset:512
	global_store_dwordx4 v[236:237], v[220:223], off offset:528
	v_lshlrev_b32_e32 v126, 2, v240
	v_cvt_pk_bf16_f32 v120, v116, v117
	s_waitcnt lgkmcnt(0)
	v_add_f32_e32 v112, v121, v122
	ds_bpermute_b32 v113, v126, v112
	v_cvt_pk_bf16_f32 v121, v118, v119
	v_cvt_pk_bf16_f32 v122, v220, v221
	v_cvt_pk_bf16_f32 v123, v222, v223
	global_store_dwordx4 v[238:239], v[120:123], off offset:256
	s_and_saveexec_b64 s[24:25], s[0:1]
	s_cbranch_execz .LBB0_1197
	s_waitcnt lgkmcnt(0)
	v_add_f32_e32 v114, v112, v113
	v_lshlrev_b64 v[112:113], 7, v[194:195]
	v_lshl_add_u64 v[112:113], s[8:9], 0, v[112:113]
	v_lshl_add_u64 v[112:113], s[22:23], 2, v[112:113]
	s_lshl_b32 s12, s41, 2
	v_lshl_add_u64 v[112:113], v[112:113], 0, s[12:13]
	global_store_dword v[112:113], v114, off

; #define PG8_STAGE(bufoff, gbase, voff) do { _Pragma("unroll") for (int _i = 0; _i < 2; ++_i) \
;     __builtin_amdgcn_global_load_lds((const unsigned*)((const char*)(gbase) + (voff)[_i]), (LAS unsigned*)(lds + (bufoff) + ldsw + _i * 8192), 16, 0, 0); } while (0)
; #define PG8_LDA(dst, b, h) do { _Pragma("unroll") for (int m = 0; m < 4; ++m) _Pragma("unroll") for (int k = 0; k < 2; ++k) dst[m][k] = *(const LAS bf16x8*)(lds + PG8_SA(b, h) + aoff + m * 2048 + k * 1024); } while (0)
; #define PG8_LDB(dst, b, h) do { _Pragma("unroll") for (int n = 0; n < 2; ++n) _Pragma("unroll") for (int k = 0; k < 2; ++k) dst[n][k] = *(const LAS bf16x8*)(lds + PG8_SB(b, h) + boff + n * 2048 + k * 1024); } while (0)
; #define PG8_MMA(ai, bj, At, Bt) do { __builtin_amdgcn_s_setprio(1); _Pragma("unroll") for (int m = 0; m < 4; ++m) _Pragma("unroll") for (int n = 0; n < 2; ++n) _Pragma("unroll") for (int k = 0; k < 2; ++k) \
;     acc[ai][bj][m][n] = __builtin_amdgcn_mfma_f32_16x16x32_bf16(Bt[n][k], At[m][k], acc[ai][bj][m][n], 0, 0, 0); __builtin_amdgcn_s_setprio(0); } while (0)
; #define PG8_WAIT_V(n) asm volatile("s_waitcnt vmcnt(" #n ")" ::: "memory")
; #define PG8_WAIT_L(n) asm volatile("s_waitcnt lgkmcnt(" #n ")" ::: "memory")
; #define PG8_BAR __builtin_amdgcn_s_barrier()
; #define PG8_SCHED __builtin_amdgcn_sched_barrier(0)
; template <class Epi, class Sched = StaticOrder>
; DI void gemm_phase(LAS unsigned char* lds, const Gemm g, const Sched& S, const Epi& E) {
;     ...
;       PG8_LDB(B0, 0, 0); PG8_SCHED; PG8_LDA(At, 0, 0); PG8_STAGE(PG8_SA(1, 1), a1 + hstep, voffA);
;       PG8_WAIT_L(8); PG8_BAR; PG8_WAIT_L(0); PG8_MMA(0, 0, At, B0); PG8_BAR; PG8_SCHED;
;       PG8_LDB(B1, 0, 1); PG8_STAGE(PG8_SB(0, 0), b2, voffB);
;       PG8_BAR; PG8_WAIT_L(0); PG8_MMA(0, 1, At, B1); PG8_BAR;
;       PG8_LDA(At, 0, 1); PG8_STAGE(PG8_SA(0, 0), a2, voffA);
;       PG8_BAR; PG8_WAIT_L(0); PG8_MMA(1, 0, At, B0); PG8_BAR; PG8_SCHED;
;       PG8_STAGE(PG8_SB(0, 1), b2 + hstep, voffB);
;       PG8_WAIT_V(6); PG8_BAR; PG8_MMA(1, 1, At, B1); PG8_BAR;
.LBB0_1277:
	s_add_u32 s48, s14, 0xfff80080
	s_addc_u32 s49, s15, -1
	s_cmp_eq_u32 s58, 28
	s_cselect_b32 s51, s41, s49
	s_cselect_b32 s50, s42, s48
	s_cselect_b32 s49, s39, s53
	s_cselect_b32 s48, s43, s52
	v_lshl_add_u64 v[196:197], s[14:15], 0, v[170:171]
	s_add_i32 m0, s64, 0xc000
	ds_read_b128 v[80:83], v202
	ds_read_b128 v[84:87], v202 offset:1024
	ds_read_b128 v[88:91], v202 offset:2048
	ds_read_b128 v[92:95], v202 offset:3072
	ds_read_b128 v[180:183], v202 offset:4096
	ds_read_b128 v[184:187], v202 offset:5120
	ds_read_b128 v[188:191], v202 offset:6144
	ds_read_b128 v[192:195], v202 offset:7168
	global_load_lds_dwordx4 v[196:197], off
	v_lshl_add_u64 v[196:197], s[14:15], 0, v[172:173]
	s_add_i32 m0, s64, 0xe000
	s_nop 0
	global_load_lds_dwordx4 v[196:197], off
	s_waitcnt lgkmcnt(8)
	s_barrier
	s_waitcnt lgkmcnt(0)
	s_setprio 1
	v_mfma_f32_16x16x32_bf16 v[156:159], v[64:67], v[80:83], v[156:159]
	v_mfma_f32_16x16x32_bf16 v[144:147], v[72:75], v[80:83], v[144:147]
	v_mfma_f32_16x16x32_bf16 v[140:143], v[64:67], v[88:91], v[140:143]
	v_mfma_f32_16x16x32_bf16 v[132:135], v[72:75], v[88:91], v[132:135]
	v_mfma_f32_16x16x32_bf16 v[124:127], v[64:67], v[180:183], v[124:127]
	v_mfma_f32_16x16x32_bf16 v[116:119], v[72:75], v[180:183], v[116:119]
	v_mfma_f32_16x16x32_bf16 v[112:115], v[64:67], v[188:191], v[112:115]
	v_mfma_f32_16x16x32_bf16 v[108:111], v[72:75], v[188:191], v[108:111]
	v_mfma_f32_16x16x32_bf16 v[156:159], v[68:71], v[84:87], v[156:159]
	v_mfma_f32_16x16x32_bf16 v[144:147], v[76:79], v[84:87], v[144:147]
	v_mfma_f32_16x16x32_bf16 v[140:143], v[68:71], v[92:95], v[140:143]
	v_mfma_f32_16x16x32_bf16 v[132:135], v[76:79], v[92:95], v[132:135]
	v_mfma_f32_16x16x32_bf16 v[124:127], v[68:71], v[184:187], v[124:127]
	v_mfma_f32_16x16x32_bf16 v[116:119], v[76:79], v[184:187], v[116:119]
	v_mfma_f32_16x16x32_bf16 v[112:115], v[68:71], v[192:195], v[112:115]
	v_mfma_f32_16x16x32_bf16 v[108:111], v[76:79], v[192:195], v[108:111]
	s_barrier
	s_setprio 0
	s_add_i32 s59, s72, s62
	v_lshl_add_u64 v[196:197], s[48:49], 0, v[164:165]
	s_mov_b32 m0, s59
	ds_read_b128 v[206:209], v203
	ds_read_b128 v[212:215], v203 offset:1024
	ds_read_b128 v[216:219], v203 offset:2048
	ds_read_b128 v[220:223], v203 offset:3072
	global_load_lds_dwordx4 v[196:197], off
	v_lshl_add_u64 v[232:233], s[48:49], 0, v[160:161]
	s_add_i32 m0, s59, 0x2000
	s_nop 0
	global_load_lds_dwordx4 v[232:233], off
	s_barrier
	s_waitcnt lgkmcnt(0)
	s_setprio 1
	v_mfma_f32_16x16x32_bf16 v[152:155], v[206:209], v[80:83], v[152:155]
	v_mfma_f32_16x16x32_bf16 v[80:83], v[216:219], v[80:83], v[148:151]
	v_mfma_f32_16x16x32_bf16 v[152:155], v[212:215], v[84:87], v[152:155]
	v_mfma_f32_16x16x32_bf16 v[80:83], v[220:223], v[84:87], v[80:83]
	v_mfma_f32_16x16x32_bf16 v[84:87], v[206:209], v[88:91], v[136:139]
	v_mfma_f32_16x16x32_bf16 v[88:91], v[216:219], v[88:91], v[128:131]
	v_mfma_f32_16x16x32_bf16 v[104:107], v[216:219], v[180:183], v[104:107]
	v_mfma_f32_16x16x32_bf16 v[100:103], v[206:209], v[188:191], v[100:103]
	v_mfma_f32_16x16x32_bf16 v[96:99], v[216:219], v[188:191], v[96:99]
	v_mfma_f32_16x16x32_bf16 v[84:87], v[212:215], v[92:95], v[84:87]
	v_mfma_f32_16x16x32_bf16 v[88:91], v[220:223], v[92:95], v[88:91]
	v_mfma_f32_16x16x32_bf16 v[92:95], v[206:209], v[180:183], v[120:123]
	v_mfma_f32_16x16x32_bf16 v[104:107], v[220:223], v[184:187], v[104:107]
	v_mfma_f32_16x16x32_bf16 v[100:103], v[212:215], v[192:195], v[100:103]
	v_mfma_f32_16x16x32_bf16 v[96:99], v[220:223], v[192:195], v[96:99]
	v_mfma_f32_16x16x32_bf16 v[92:95], v[212:215], v[184:187], v[92:95]
	s_barrier
	s_setprio 0
	s_mov_b32 m0, s64
	v_lshl_add_u64 v[234:235], s[50:51], 0, v[166:167]
	ds_read_b128 v[120:123], v202 offset:16384
	ds_read_b128 v[128:131], v202 offset:17408
	ds_read_b128 v[136:139], v202 offset:18432
	ds_read_b128 v[148:151], v202 offset:19456
	ds_read_b128 v[180:183], v202 offset:20480
	ds_read_b128 v[184:187], v202 offset:21504
	ds_read_b128 v[188:191], v202 offset:22528
	ds_read_b128 v[192:195], v202 offset:23552
	global_load_lds_dwordx4 v[234:235], off
	v_lshl_add_u64 v[236:237], s[50:51], 0, v[162:163]
	s_mov_b32 m0, s65
	s_nop 0
	global_load_lds_dwordx4 v[236:237], off
	s_waitcnt vmcnt(10)
	s_barrier
	s_waitcnt lgkmcnt(0)
	s_setprio 1
	v_mfma_f32_16x16x32_bf16 v[60:63], v[64:67], v[120:123], v[60:63]
	v_mfma_f32_16x16x32_bf16 v[48:51], v[72:75], v[120:123], v[48:51]
	v_mfma_f32_16x16x32_bf16 v[44:47], v[64:67], v[136:139], v[44:47]
	v_mfma_f32_16x16x32_bf16 v[36:39], v[72:75], v[136:139], v[36:39]
	v_mfma_f32_16x16x32_bf16 v[28:31], v[64:67], v[180:183], v[28:31]
	v_mfma_f32_16x16x32_bf16 v[20:23], v[72:75], v[180:183], v[20:23]
	v_mfma_f32_16x16x32_bf16 v[16:19], v[64:67], v[188:191], v[16:19]
	v_mfma_f32_16x16x32_bf16 v[12:15], v[72:75], v[188:191], v[12:15]
	v_mfma_f32_16x16x32_bf16 v[60:63], v[68:71], v[128:131], v[60:63]
	v_mfma_f32_16x16x32_bf16 v[48:51], v[76:79], v[128:131], v[48:51]
	v_mfma_f32_16x16x32_bf16 v[44:47], v[68:71], v[148:151], v[44:47]
	v_mfma_f32_16x16x32_bf16 v[36:39], v[76:79], v[148:151], v[36:39]
	v_mfma_f32_16x16x32_bf16 v[28:31], v[68:71], v[184:187], v[28:31]
	v_mfma_f32_16x16x32_bf16 v[20:23], v[76:79], v[184:187], v[20:23]
	v_mfma_f32_16x16x32_bf16 v[16:19], v[68:71], v[192:195], v[16:19]
	v_mfma_f32_16x16x32_bf16 v[12:15], v[76:79], v[192:195], v[12:15]
	s_barrier
	s_setprio 0
	s_add_u32 s78, s48, 0x80000
	s_addc_u32 s79, s49, 0
	s_add_i32 s59, s73, s62
	v_lshl_add_u64 v[64:65], s[78:79], 0, v[164:165]
	s_mov_b32 m0, s59
	s_nop 0
	global_load_lds_dwordx4 v[64:65], off
	v_lshl_add_u64 v[64:65], s[78:79], 0, v[160:161]
	s_add_i32 m0, s59, 0x2000
	s_nop 0
	global_load_lds_dwordx4 v[64:65], off
	s_add_i32 s59, 0, 0x18000
	v_add_u32_e32 v76, s59, v198
	ds_read_b128 v[64:67], v76
	ds_read_b128 v[68:71], v76 offset:1024
	ds_read_b128 v[72:75], v76 offset:2048
	ds_read_b128 v[76:79], v76 offset:3072
	s_waitcnt vmcnt(6)
	s_barrier
; #define PG8_STAGE(bufoff, gbase, voff) do { _Pragma("unroll") for (int _i = 0; _i < 2; ++_i) \
;     __builtin_amdgcn_global_load_lds((const unsigned*)((const char*)(gbase) + (voff)[_i]), (LAS unsigned*)(lds + (bufoff) + ldsw + _i * 8192), 16, 0, 0); } while (0)
; #define PG8_LDA(dst, b, h) do { _Pragma("unroll") for (int m = 0; m < 4; ++m) _Pragma("unroll") for (int k = 0; k < 2; ++k) dst[m][k] = *(const LAS bf16x8*)(lds + PG8_SA(b, h) + aoff + m * 2048 + k * 1024); } while (0)
; #define PG8_LDB(dst, b, h) do { _Pragma("unroll") for (int n = 0; n < 2; ++n) _Pragma("unroll") for (int k = 0; k < 2; ++k) dst[n][k] = *(const LAS bf16x8*)(lds + PG8_SB(b, h) + boff + n * 2048 + k * 1024); } while (0)
; #define PG8_MMA(ai, bj, At, Bt) do { __builtin_amdgcn_s_setprio(1); _Pragma("unroll") for (int m = 0; m < 4; ++m) _Pragma("unroll") for (int n = 0; n < 2; ++n) _Pragma("unroll") for (int k = 0; k < 2; ++k) \
;     acc[ai][bj][m][n] = __builtin_amdgcn_mfma_f32_16x16x32_bf16(Bt[n][k], At[m][k], acc[ai][bj][m][n], 0, 0, 0); __builtin_amdgcn_s_setprio(0); } while (0)
; #define PG8_WAIT_V(n) asm volatile("s_waitcnt vmcnt(" #n ")" ::: "memory")
; #define PG8_WAIT_L(n) asm volatile("s_waitcnt lgkmcnt(" #n ")" ::: "memory")
; #define PG8_BAR __builtin_amdgcn_s_barrier()
; #define PG8_SCHED __builtin_amdgcn_sched_barrier(0)
; template <class Epi, class Sched = StaticOrder>
; DI void gemm_phase(LAS unsigned char* lds, const Gemm g, const Sched& S, const Epi& E) {
;     ...
;       PG8_WAIT_V(6); PG8_BAR; PG8_MMA(1, 1, At, B1); PG8_BAR;
;       PG8_LDB(B0, 1, 0); PG8_SCHED; PG8_LDA(At, 1, 0); PG8_STAGE(PG8_SA(0, 1), a2 + hstep, voffA);
;       PG8_WAIT_L(8); PG8_BAR; PG8_WAIT_L(0); PG8_MMA(0, 0, At, B0); PG8_BAR; PG8_SCHED;
;       PG8_LDB(B1, 1, 1); PG8_STAGE(PG8_SB(1, 0), b3, voffB);
;       PG8_BAR; PG8_WAIT_L(0); PG8_MMA(0, 1, At, B1); PG8_BAR;
;       PG8_LDA(At, 1, 1); PG8_STAGE(PG8_SA(1, 0), a3, voffA);
	s_setprio 1
	v_mfma_f32_16x16x32_bf16 v[56:59], v[206:209], v[120:123], v[56:59]
	v_mfma_f32_16x16x32_bf16 v[52:55], v[216:219], v[120:123], v[52:55]
	v_mfma_f32_16x16x32_bf16 v[40:43], v[206:209], v[136:139], v[40:43]
	v_mfma_f32_16x16x32_bf16 v[32:35], v[216:219], v[136:139], v[32:35]
	v_mfma_f32_16x16x32_bf16 v[24:27], v[206:209], v[180:183], v[24:27]
	v_mfma_f32_16x16x32_bf16 v[8:11], v[216:219], v[180:183], v[8:11]
	v_mfma_f32_16x16x32_bf16 v[4:7], v[206:209], v[188:191], v[4:7]
	v_mfma_f32_16x16x32_bf16 v[0:3], v[216:219], v[188:191], v[0:3]
	v_mfma_f32_16x16x32_bf16 v[56:59], v[212:215], v[128:131], v[56:59]
	v_mfma_f32_16x16x32_bf16 v[52:55], v[220:223], v[128:131], v[52:55]
	v_mfma_f32_16x16x32_bf16 v[40:43], v[212:215], v[148:151], v[40:43]
	v_mfma_f32_16x16x32_bf16 v[32:35], v[220:223], v[148:151], v[32:35]
	v_mfma_f32_16x16x32_bf16 v[24:27], v[212:215], v[184:187], v[24:27]
	v_mfma_f32_16x16x32_bf16 v[8:11], v[220:223], v[184:187], v[8:11]
	v_mfma_f32_16x16x32_bf16 v[4:7], v[212:215], v[192:195], v[4:7]
	v_mfma_f32_16x16x32_bf16 v[0:3], v[220:223], v[192:195], v[0:3]
	s_barrier
	s_setprio 0
	s_add_u32 s50, s50, 0x80000
	s_addc_u32 s51, s51, 0
	s_mov_b32 m0, s66
	v_lshl_add_u64 v[136:137], s[50:51], 0, v[166:167]
	ds_read_b128 v[120:123], v202 offset:32768
	ds_read_b128 v[128:131], v202 offset:33792
	ds_read_b128 v[180:183], v202 offset:34816
	ds_read_b128 v[184:187], v202 offset:35840
	ds_read_b128 v[188:191], v202 offset:36864
	ds_read_b128 v[192:195], v202 offset:37888
	ds_read_b128 v[206:209], v202 offset:38912
	ds_read_b128 v[212:215], v202 offset:39936
	global_load_lds_dwordx4 v[136:137], off
	v_lshl_add_u64 v[136:137], s[50:51], 0, v[162:163]
	s_mov_b32 m0, s67
	s_nop 0
	global_load_lds_dwordx4 v[136:137], off
	s_waitcnt lgkmcnt(8)
	s_barrier
	s_waitcnt lgkmcnt(0)
	s_setprio 1
	v_mfma_f32_16x16x32_bf16 v[136:139], v[64:67], v[120:123], v[156:159]
	v_mfma_f32_16x16x32_bf16 v[156:159], v[68:71], v[128:131], v[136:139]
	v_mfma_f32_16x16x32_bf16 v[136:139], v[72:75], v[120:123], v[144:147]
	v_mfma_f32_16x16x32_bf16 v[144:147], v[76:79], v[128:131], v[136:139]
	v_mfma_f32_16x16x32_bf16 v[136:139], v[64:67], v[180:183], v[140:143]
	v_mfma_f32_16x16x32_bf16 v[132:135], v[72:75], v[180:183], v[132:135]
	v_mfma_f32_16x16x32_bf16 v[124:127], v[64:67], v[188:191], v[124:127]
	v_mfma_f32_16x16x32_bf16 v[116:119], v[72:75], v[188:191], v[116:119]
	v_mfma_f32_16x16x32_bf16 v[112:115], v[64:67], v[206:209], v[112:115]
	v_mfma_f32_16x16x32_bf16 v[108:111], v[72:75], v[206:209], v[108:111]
	v_mfma_f32_16x16x32_bf16 v[140:143], v[68:71], v[184:187], v[136:139]
	v_mfma_f32_16x16x32_bf16 v[132:135], v[76:79], v[184:187], v[132:135]
	v_mfma_f32_16x16x32_bf16 v[124:127], v[68:71], v[192:195], v[124:127]
	v_mfma_f32_16x16x32_bf16 v[116:119], v[76:79], v[192:195], v[116:119]
	v_mfma_f32_16x16x32_bf16 v[112:115], v[68:71], v[212:215], v[112:115]
	v_mfma_f32_16x16x32_bf16 v[108:111], v[76:79], v[212:215], v[108:111]
	s_barrier
	s_setprio 0
	s_add_i32 s50, 0, 0x1c000
	v_add_u32_e32 v136, s50, v198
	s_add_i32 s51, s59, s62
	ds_read_b128 v[216:219], v136
	ds_read_b128 v[220:223], v136 offset:1024
	ds_read_b128 v[224:227], v136 offset:2048
	ds_read_b128 v[228:231], v136 offset:3072
	v_lshl_add_u64 v[136:137], v[196:197], 0, s[28:29]
	s_mov_b32 m0, s51
	s_nop 0
	global_load_lds_dwordx4 v[136:137], off
	v_lshl_add_u64 v[136:137], v[232:233], 0, s[28:29]
	s_add_i32 m0, s51, 0x2000
	s_nop 0
	global_load_lds_dwordx4 v[136:137], off
	s_barrier
	s_waitcnt lgkmcnt(0)
	s_setprio 1
	v_mfma_f32_16x16x32_bf16 v[80:83], v[224:227], v[120:123], v[80:83]
	v_mfma_f32_16x16x32_bf16 v[136:139], v[216:219], v[120:123], v[152:155]
	v_mfma_f32_16x16x32_bf16 v[148:151], v[228:231], v[128:131], v[80:83]
	v_mfma_f32_16x16x32_bf16 v[80:83], v[216:219], v[180:183], v[84:87]
	v_mfma_f32_16x16x32_bf16 v[152:155], v[220:223], v[128:131], v[136:139]
	v_mfma_f32_16x16x32_bf16 v[136:139], v[220:223], v[184:187], v[80:83]
	v_mfma_f32_16x16x32_bf16 v[80:83], v[224:227], v[180:183], v[88:91]
	v_mfma_f32_16x16x32_bf16 v[128:131], v[228:231], v[184:187], v[80:83]
	v_mfma_f32_16x16x32_bf16 v[80:83], v[216:219], v[188:191], v[92:95]
	v_mfma_f32_16x16x32_bf16 v[120:123], v[220:223], v[192:195], v[80:83]
	v_mfma_f32_16x16x32_bf16 v[80:83], v[224:227], v[188:191], v[104:107]
	v_mfma_f32_16x16x32_bf16 v[104:107], v[228:231], v[192:195], v[80:83]
	v_mfma_f32_16x16x32_bf16 v[80:83], v[216:219], v[206:209], v[100:103]
	v_mfma_f32_16x16x32_bf16 v[100:103], v[220:223], v[212:215], v[80:83]
	v_mfma_f32_16x16x32_bf16 v[80:83], v[224:227], v[206:209], v[96:99]
	v_mfma_f32_16x16x32_bf16 v[96:99], v[228:231], v[212:215], v[80:83]
	s_barrier
	s_setprio 0
	s_mov_b32 m0, s55
	v_lshl_add_u64 v[196:197], v[234:235], 0, s[28:29]
	s_nop 2
	ds_read_b128 v[80:83], v202 offset:49152
	ds_read_b128 v[84:87], v202 offset:50176
	ds_read_b128 v[88:91], v202 offset:51200
	ds_read_b128 v[92:95], v202 offset:52224
	ds_read_b128 v[180:183], v202 offset:53248
	ds_read_b128 v[184:187], v202 offset:54272
	ds_read_b128 v[188:191], v202 offset:55296
	ds_read_b128 v[192:195], v202 offset:56320
	global_load_lds_dwordx4 v[196:197], off
	v_lshl_add_u64 v[196:197], v[236:237], 0, s[28:29]
	s_mov_b32 m0, s68
	s_nop 0
	global_load_lds_dwordx4 v[196:197], off
	s_waitcnt vmcnt(10)
	s_barrier
; #define PG8_STAGE(bufoff, gbase, voff) do { _Pragma("unroll") for (int _i = 0; _i < 2; ++_i) \
;     __builtin_amdgcn_global_load_lds((const unsigned*)((const char*)(gbase) + (voff)[_i]), (LAS unsigned*)(lds + (bufoff) + ldsw + _i * 8192), 16, 0, 0); } while (0)
; #define PG8_LDA(dst, b, h) do { _Pragma("unroll") for (int m = 0; m < 4; ++m) _Pragma("unroll") for (int k = 0; k < 2; ++k) dst[m][k] = *(const LAS bf16x8*)(lds + PG8_SA(b, h) + aoff + m * 2048 + k * 1024); } while (0)
; #define PG8_LDB(dst, b, h) do { _Pragma("unroll") for (int n = 0; n < 2; ++n) _Pragma("unroll") for (int k = 0; k < 2; ++k) dst[n][k] = *(const LAS bf16x8*)(lds + PG8_SB(b, h) + boff + n * 2048 + k * 1024); } while (0)
; #define PG8_WAIT_V(n) asm volatile("s_waitcnt vmcnt(" #n ")" ::: "memory")
; #define PG8_WAIT_L(n) asm volatile("s_waitcnt lgkmcnt(" #n ")" ::: "memory")
; #define PG8_BAR __builtin_amdgcn_s_barrier()
; #define PG8_SCHED __builtin_amdgcn_sched_barrier(0)
;   DI void operator()(const f32x4 (&acc)[2][2][4][2], const Unit& u, int wr, int wc, int fr, int fq) const {
;     const int col = u.pn * 128 + wc * 32 + 8 * fq;
;     float w0[8], w1[8], w2[8], bb[8];
; #pragma unroll
;     for (int e = 0; e < 8; ++e) { w0[e] = cw[col + e]; w1[e] = cw[5632 + col + e]; w2[e] = cw[2 * 5632 + col + e]; bb[e] = cb[col + e]; }
; #pragma unroll
;     for (int ai = 0; ai < 2; ++ai) {
;       const int row0 = u.pm * BM + ai * HALF + wr * 64, span = row0 >> 6;
;       float rsv[4];
; #pragma unroll
;       for (int m = 0; m < 4; ++m) rsv[m] = row_rstd(ssq, row0 + 16 * m + fr, fq);
; template <class Epi, class Sched = StaticOrder>
; DI void gemm_phase(LAS unsigned char* lds, const Gemm g, const Sched& S, const Epi& E) {
;     ...
;       PG8_LDB(B0, 1, 0); PG8_SCHED; PG8_LDA(At, 1, 0); PG8_STAGE(PG8_SA(0, 1), a2 + hstep, voffA);
;       PG8_WAIT_L(8); PG8_BAR; PG8_WAIT_L(0); PG8_MMA(0, 0, At, B0); PG8_BAR; PG8_SCHED;
;       PG8_LDB(B1, 1, 1); PG8_STAGE(PG8_SB(1, 0), b3, voffB);
;       PG8_BAR; PG8_WAIT_L(0); PG8_MMA(0, 1, At, B1); PG8_BAR;
;       PG8_LDA(At, 1, 1); PG8_STAGE(PG8_SA(1, 0), a3, voffA);
;       PG8_BAR; PG8_WAIT_L(0); PG8_MMA(1, 0, At, B0); PG8_BAR; PG8_SCHED;
;       PG8_STAGE(PG8_SB(1, 1), b3 + hstep, voffB);
;       PG8_WAIT_V(6); PG8_BAR; PG8_MMA(1, 1, At, B1); PG8_BAR;
	s_waitcnt lgkmcnt(0)
	s_setprio 1
	v_mfma_f32_16x16x32_bf16 v[60:63], v[64:67], v[80:83], v[60:63]
	v_mfma_f32_16x16x32_bf16 v[48:51], v[72:75], v[80:83], v[48:51]
	v_mfma_f32_16x16x32_bf16 v[44:47], v[64:67], v[88:91], v[44:47]
	v_mfma_f32_16x16x32_bf16 v[36:39], v[72:75], v[88:91], v[36:39]
	v_mfma_f32_16x16x32_bf16 v[28:31], v[64:67], v[180:183], v[28:31]
	v_mfma_f32_16x16x32_bf16 v[20:23], v[72:75], v[180:183], v[20:23]
	v_mfma_f32_16x16x32_bf16 v[16:19], v[64:67], v[188:191], v[16:19]
	v_mfma_f32_16x16x32_bf16 v[12:15], v[72:75], v[188:191], v[12:15]
	v_mfma_f32_16x16x32_bf16 v[60:63], v[68:71], v[84:87], v[60:63]
	v_mfma_f32_16x16x32_bf16 v[48:51], v[76:79], v[84:87], v[48:51]
	v_mfma_f32_16x16x32_bf16 v[44:47], v[68:71], v[92:95], v[44:47]
	v_mfma_f32_16x16x32_bf16 v[36:39], v[76:79], v[92:95], v[36:39]
	v_mfma_f32_16x16x32_bf16 v[28:31], v[68:71], v[184:187], v[28:31]
	v_mfma_f32_16x16x32_bf16 v[20:23], v[76:79], v[184:187], v[20:23]
	v_mfma_f32_16x16x32_bf16 v[16:19], v[68:71], v[192:195], v[16:19]
	v_mfma_f32_16x16x32_bf16 v[12:15], v[76:79], v[192:195], v[12:15]
	s_barrier
	s_setprio 0
	s_add_u32 s48, s48, 0x80080
	s_addc_u32 s49, s49, 0
	s_add_i32 s50, s50, s62
	v_lshl_add_u64 v[64:65], s[48:49], 0, v[164:165]
	s_mov_b32 m0, s50
	s_nop 0
	global_load_lds_dwordx4 v[64:65], off
	v_lshl_add_u64 v[64:65], s[48:49], 0, v[160:161]
	s_add_i32 m0, s50, 0x2000
	s_nop 0
	global_load_lds_dwordx4 v[64:65], off
	ds_read_b128 v[64:67], v201
	ds_read_b128 v[68:71], v201 offset:1024
	ds_read_b128 v[72:75], v201 offset:2048
	ds_read_b128 v[76:79], v201 offset:3072
	s_waitcnt vmcnt(6)
	s_barrier
	s_setprio 1
	v_mfma_f32_16x16x32_bf16 v[56:59], v[216:219], v[80:83], v[56:59]
	v_mfma_f32_16x16x32_bf16 v[52:55], v[224:227], v[80:83], v[52:55]
	v_mfma_f32_16x16x32_bf16 v[40:43], v[216:219], v[88:91], v[40:43]
	v_mfma_f32_16x16x32_bf16 v[32:35], v[224:227], v[88:91], v[32:35]
	v_mfma_f32_16x16x32_bf16 v[24:27], v[216:219], v[180:183], v[24:27]
	v_mfma_f32_16x16x32_bf16 v[8:11], v[224:227], v[180:183], v[8:11]
	v_mfma_f32_16x16x32_bf16 v[4:7], v[216:219], v[188:191], v[4:7]
	v_mfma_f32_16x16x32_bf16 v[0:3], v[224:227], v[188:191], v[0:3]
	v_mfma_f32_16x16x32_bf16 v[56:59], v[220:223], v[84:87], v[56:59]
	v_mfma_f32_16x16x32_bf16 v[52:55], v[228:231], v[84:87], v[52:55]
	v_mfma_f32_16x16x32_bf16 v[40:43], v[220:223], v[92:95], v[40:43]
	v_mfma_f32_16x16x32_bf16 v[32:35], v[228:231], v[92:95], v[32:35]
	v_mfma_f32_16x16x32_bf16 v[24:27], v[220:223], v[184:187], v[24:27]
	v_mfma_f32_16x16x32_bf16 v[8:11], v[228:231], v[184:187], v[8:11]
	v_mfma_f32_16x16x32_bf16 v[4:7], v[220:223], v[192:195], v[4:7]
	v_mfma_f32_16x16x32_bf16 v[0:3], v[228:231], v[192:195], v[0:3]
	s_add_i32 s58, s58, 2
	s_add_u32 s14, s14, 0x100
	s_addc_u32 s15, s15, 0
	s_add_u32 s52, s52, 0x100
	s_addc_u32 s53, s53, 0
	s_cmp_gt_u32 s58, 29
	s_barrier
	s_setprio 0
	s_cbranch_scc0 .LBB0_1277
	s_waitcnt lgkmcnt(0)
	s_lshl_b32 s39, s12, 8
	s_add_i32 s39, s39, s54
	v_or_b32_e32 v190, s39, v179
	v_ashrrev_i32_e32 v191, 31, v190
	v_lshlrev_b64 v[64:65], 7, v[190:191]
	v_or_b32_e32 v188, 16, v190
	v_lshl_add_u64 v[64:65], v[168:169], 0, v[64:65]
	v_ashrrev_i32_e32 v189, 31, v188
	global_load_dwordx4 v[192:195], v[64:65], off
	global_load_dwordx4 v[206:209], v[64:65], off offset:16
	v_lshlrev_b64 v[64:65], 7, v[188:189]
	v_lshl_add_u64 v[64:65], v[168:169], 0, v[64:65]
	global_load_dwordx4 v[212:215], v[64:65], off
	global_load_dwordx4 v[216:219], v[64:65], off offset:16
	v_or_b32_e32 v186, 32, v190
	v_ashrrev_i32_e32 v187, 31, v186
	v_lshlrev_b64 v[64:65], 7, v[186:187]
	v_or_b32_e32 v184, 48, v190
	v_lshl_add_u64 v[64:65], v[168:169], 0, v[64:65]
	v_ashrrev_i32_e32 v185, 31, v184
	global_load_dwordx4 v[220:223], v[64:65], off
	global_load_dwordx4 v[224:227], v[64:65], off offset:16
	v_lshlrev_b64 v[64:65], 7, v[184:185]
	v_lshl_add_u64 v[64:65], v[168:169], 0, v[64:65]
	global_load_dwordx4 v[228:231], v[64:65], off
	global_load_dwordx4 v[232:235], v[64:65], off offset:16
	v_lshl_or_b32 v180, s13, 7, v200
	v_and_b32_e32 v65, 64, v204
	v_xor_b32_e32 v64, 16, v204
	v_ashrrev_i32_e32 v181, 31, v180
	v_add_u32_e32 v65, 64, v65
	v_xor_b32_e32 v66, 32, v204
	v_lshlrev_b64 v[182:183], 2, v[180:181]
	v_cmp_lt_i32_e32 vcc, v64, v65
	v_lshl_add_u64 v[88:89], s[16:17], 0, v[182:183]
	v_lshl_add_u64 v[72:73], s[18:19], 0, v[182:183]
	v_cndmask_b32_e32 v64, v204, v64, vcc
	v_cmp_lt_i32_e32 vcc, v66, v65
	v_lshl_add_u64 v[74:75], v[88:89], 0, s[30:31]
	v_lshl_add_u64 v[76:77], v[88:89], 0, s[34:35]
	v_cndmask_b32_e32 v65, v204, v66, vcc
	v_add_co_u32_e32 v90, vcc, 0x5000, v88
	v_lshlrev_b32_e32 v187, 2, v64
	s_nop 0
	v_addc_co_u32_e32 v91, vcc, 0, v89, vcc
	v_add_co_u32_e32 v92, vcc, 0xb000, v88
	v_lshlrev_b32_e32 v185, 2, v65
	s_nop 0
	v_addc_co_u32_e32 v93, vcc, 0, v89, vcc
	global_load_dwordx4 v[64:67], v[88:89], off offset:16
	global_load_dwordx4 v[80:83], v[88:89], off
	global_load_dwordx4 v[68:71], v[72:73], off offset:16
	global_load_dwordx4 v[84:87], v[72:73], off
	s_nop 0
	global_load_dwordx4 v[72:75], v[74:75], off offset:16
	s_nop 0
	global_load_dwordx4 v[76:79], v[76:77], off offset:16
	s_nop 0
	global_load_dwordx4 v[88:91], v[90:91], off offset:2048
	s_nop 0
	global_load_dwordx4 v[92:95], v[92:93], off
	v_mov_b32_e32 v211, 0
	v_mov_b32_e32 v205, 0
	s_waitcnt vmcnt(0)
; DI float dpp_ror1(float v) { return __int_as_float(__builtin_amdgcn_update_dpp(0, __float_as_int(v), 0x121, 0xf, 0xf, false)); }
; DI float dpp_ror2(float v) { return __int_as_float(__builtin_amdgcn_update_dpp(0, __float_as_int(v), 0x122, 0xf, 0xf, false)); }
; DI float row_rstd(const float* ssq, int row, int fq) {
;   const f32x4 a = *(const f32x4*)(ssq + (size_t)row * 32 + fq * 8), b = *(const f32x4*)(ssq + (size_t)row * 32 + fq * 8 + 4);
;   float sm = ((a[0] + a[1]) + (a[2] + a[3])) + ((b[0] + b[1]) + (b[2] + b[3]));
;   sm += __shfl_xor(sm, 16); sm += __shfl_xor(sm, 32);
;   return rsqrtf(sm * (1.0f / 2048.f) + 1e-6f);
;   DI void operator()(const f32x4 (&acc)[2][2][4][2], const Unit& u, int wr, int wc, int fr, int fq) const {
;     const int col = u.pn * 128 + wc * 32 + 8 * fq;
;     float w0[8], w1[8], w2[8], bb[8];
; #pragma unroll
;     for (int e = 0; e < 8; ++e) { w0[e] = cw[col + e]; w1[e] = cw[5632 + col + e]; w2[e] = cw[2 * 5632 + col + e]; bb[e] = cb[col + e]; }
; #pragma unroll
;     for (int ai = 0; ai < 2; ++ai) {
;       const int row0 = u.pm * BM + ai * HALF + wr * 64, span = row0 >> 6;
;       float rsv[4];
; #pragma unroll
;       for (int m = 0; m < 4; ++m) rsv[m] = row_rstd(ssq, row0 + 16 * m + fr, fq);
;       float p1[8], p2[8];
; #pragma unroll
;       for (int e = 0; e < 8; ++e) { p1[e] = 0.f; p2[e] = 0.f; }
; #pragma unroll
;       for (int m = 0; m < 4; ++m) {
;         float g[8], uu[8], a[8];
;         const float rs = rsv[m];
; #pragma unroll
;         for (int e = 0; e < 4; ++e) { g[e] = acc[ai][0][m][0][e] * rs; g[4 + e] = acc[ai][0][m][1][e] * rs; uu[e] = acc[ai][1][m][0][e] * rs; uu[4 + e] = acc[ai][1][m][1][e] * rs; }
; #pragma unroll
;         for (int e = 0; e < 8; ++e) {
;           const float x1 = dpp_ror1(g[e]), x2 = dpp_ror2(g[e]);
;           const float pr1 = (fr == 0) ? p1[e] : x1, pr2 = (fr < 2) ? p2[e] : x2;
;           a[e] = w2[e] * g[e] + w1[e] * pr1 + w0[e] * pr2 + bb[e];
;           p1[e] = x1; p2[e] = x2;
;         }
	v_mov_b32_e32 v196, v192
	v_mov_b32_e32 v197, v206
	v_mov_b32_e32 v206, v193
	v_mov_b32_e32 v192, v194
	v_mov_b32_e32 v193, v208
	v_mov_b32_e32 v208, v195
	v_pk_add_f32 v[194:195], v[196:197], v[206:207]
	v_pk_add_f32 v[192:193], v[192:193], v[208:209]
	v_mov_b32_e32 v196, v212
	v_mov_b32_e32 v197, v216
	v_mov_b32_e32 v216, v213
	v_mov_b32_e32 v206, v214
	v_mov_b32_e32 v207, v218
	v_mov_b32_e32 v218, v215
	v_pk_add_f32 v[192:193], v[194:195], v[192:193]
	v_pk_add_f32 v[194:195], v[196:197], v[216:217]
	v_pk_add_f32 v[196:197], v[206:207], v[218:219]
	v_mov_b32_e32 v208, v220
	v_pk_add_f32 v[194:195], v[194:195], v[196:197]
	v_mov_b32_e32 v197, v192
	v_mov_b32_e32 v196, v194
	v_mov_b32_e32 v192, v195
	v_pk_add_f32 v[192:193], v[196:197], v[192:193]
	ds_bpermute_b32 v195, v187, v193
	ds_bpermute_b32 v194, v187, v192
	v_mov_b32_e32 v209, v224
	v_mov_b32_e32 v224, v221
	v_mov_b32_e32 v212, v222
	v_mov_b32_e32 v213, v226
	s_waitcnt lgkmcnt(0)
	v_pk_add_f32 v[192:193], v[192:193], v[194:195]
	ds_bpermute_b32 v195, v185, v193
	ds_bpermute_b32 v194, v185, v192
	v_mov_b32_e32 v226, v223
	v_mov_b32_e32 v196, v228
	v_mov_b32_e32 v197, v232
	v_mov_b32_e32 v232, v229
	s_waitcnt lgkmcnt(0)
	v_pk_add_f32 v[192:193], v[192:193], v[194:195]
	v_mov_b32_e32 v206, v230
	v_pk_fma_f32 v[192:193], v[192:193], s[36:37], v[178:179] op_sel_hi:[1,0,0]
	v_mov_b32_e32 v207, v234
	v_mul_f32_e32 v189, 0x4b800000, v193
	v_cmp_gt_f32_e64 s[12:13], s74, v193
	v_mov_b32_e32 v234, v231
	v_pk_add_f32 v[208:209], v[208:209], v[224:225]
	v_cndmask_b32_e64 v189, v193, v189, s[12:13]
	v_rsq_f32_e32 v189, v189
	v_pk_add_f32 v[212:213], v[212:213], v[226:227]
	v_pk_add_f32 v[196:197], v[196:197], v[232:233]
	v_pk_add_f32 v[194:195], v[206:207], v[234:235]
	v_mul_f32_e32 v191, 0x45800000, v189
	v_cndmask_b32_e64 v220, v189, v191, s[12:13]
	v_pk_add_f32 v[208:209], v[208:209], v[212:213]
	v_pk_add_f32 v[194:195], v[196:197], v[194:195]
	v_pk_mul_f32 v[156:157], v[156:157], v[220:221] op_sel_hi:[1,0]
	v_mov_b32_e32 v216, 0
	v_mov_b32_e32 v218, 0
	v_mov_b32_e32 v196, v194
	v_mov_b32_e32 v197, v208
	v_mov_b32_e32 v208, v195
	v_mov_b32_dpp v216, v156 row_ror:1 row_mask:0xf bank_mask:0xf
	v_mov_b32_dpp v218, v157 row_ror:1 row_mask:0xf bank_mask:0xf
	v_pk_add_f32 v[194:195], v[196:197], v[208:209]
	v_cndmask_b32_e64 v207, v218, 0, s[0:1]
	v_cndmask_b32_e64 v206, v216, 0, s[0:1]
	v_pk_mul_f32 v[158:159], v[158:159], v[220:221] op_sel_hi:[1,0]
	v_mov_b32_e32 v212, 0
	v_mov_b32_e32 v214, 0
	ds_bpermute_b32 v197, v187, v195
	ds_bpermute_b32 v196, v187, v194
	v_mov_b32_e32 v215, 0
	v_mov_b32_e32 v217, 0
	v_pk_mul_f32 v[206:207], v[88:89], v[206:207]
	v_mov_b32_dpp v212, v158 row_ror:1 row_mask:0xf bank_mask:0xf
	v_mov_b32_dpp v214, v159 row_ror:1 row_mask:0xf bank_mask:0xf
	v_mov_b32_dpp v215, v156 row_ror:2 row_mask:0xf bank_mask:0xf
	v_mov_b32_dpp v217, v157 row_ror:2 row_mask:0xf bank_mask:0xf
	v_pk_fma_f32 v[156:157], v[92:93], v[156:157], v[206:207]
	v_mov_b32_e32 v213, 0
	v_cndmask_b32_e64 v207, v214, 0, s[0:1]
	v_cndmask_b32_e64 v206, v212, 0, s[0:1]
	v_cndmask_b32_e64 v209, v217, 0, s[4:5]
	v_cndmask_b32_e64 v208, v215, 0, s[4:5]
	v_mov_b32_dpp v211, v158 row_ror:2 row_mask:0xf bank_mask:0xf
	v_mov_b32_dpp v213, v159 row_ror:2 row_mask:0xf bank_mask:0xf
	v_pk_mul_f32 v[206:207], v[90:91], v[206:207]
	v_pk_fma_f32 v[156:157], v[80:81], v[208:209], v[156:157]
	v_cndmask_b32_e64 v209, v213, 0, s[4:5]
	v_cndmask_b32_e64 v208, v211, 0, s[4:5]
	v_pk_fma_f32 v[158:159], v[94:95], v[158:159], v[206:207]
	v_pk_mul_f32 v[144:145], v[144:145], v[220:221] op_sel_hi:[1,0]
	v_pk_fma_f32 v[158:159], v[82:83], v[208:209], v[158:159]
	v_mov_b32_e32 v207, 0
	v_mov_b32_e32 v209, 0
	v_pk_mul_f32 v[146:147], v[146:147], v[220:221] op_sel_hi:[1,0]
	v_mov_b32_e32 v191, 0
	s_waitcnt lgkmcnt(0)
	v_pk_add_f32 v[194:195], v[194:195], v[196:197]
	v_mov_b32_dpp v207, v144 row_ror:1 row_mask:0xf bank_mask:0xf
	v_mov_b32_dpp v209, v145 row_ror:1 row_mask:0xf bank_mask:0xf
	v_mov_b32_dpp v191, v146 row_ror:1 row_mask:0xf bank_mask:0xf
	v_mov_b32_dpp v205, v147 row_ror:1 row_mask:0xf bank_mask:0xf
	ds_bpermute_b32 v197, v185, v195
	ds_bpermute_b32 v196, v185, v194
	v_pk_mul_f32 v[152:153], v[152:153], v[220:221] op_sel_hi:[1,0]
	v_pk_mul_f32 v[148:149], v[148:149], v[220:221] op_sel_hi:[1,0]
	v_pk_mul_f32 v[154:155], v[154:155], v[220:221] op_sel_hi:[1,0]
	v_pk_mul_f32 v[150:151], v[150:151], v[220:221] op_sel_hi:[1,0]
	v_mov_b32_e32 v206, 0
	v_mov_b32_e32 v208, 0
	v_cndmask_b32_e64 v223, v209, 0, s[0:1]
	v_cndmask_b32_e64 v222, v207, 0, s[0:1]
	v_mov_b32_e32 v189, 0
	v_mov_b32_e32 v193, 0
	v_cndmask_b32_e64 v221, v205, 0, s[0:1]
	v_cndmask_b32_e64 v220, v191, 0, s[0:1]
	v_mov_b32_dpp v206, v144 row_ror:2 row_mask:0xf bank_mask:0xf
	v_mov_b32_dpp v208, v145 row_ror:2 row_mask:0xf bank_mask:0xf
	v_pk_mul_f32 v[222:223], v[72:73], v[222:223]
	v_mov_b32_dpp v189, v146 row_ror:2 row_mask:0xf bank_mask:0xf
	v_mov_b32_dpp v193, v147 row_ror:2 row_mask:0xf bank_mask:0xf
	v_pk_mul_f32 v[220:221], v[74:75], v[220:221]
	v_cndmask_b32_e64 v225, v208, 0, s[4:5]
	v_cndmask_b32_e64 v224, v206, 0, s[4:5]
	v_pk_fma_f32 v[144:145], v[76:77], v[144:145], v[222:223]
	v_cndmask_b32_e64 v223, v193, 0, s[4:5]
	v_cndmask_b32_e64 v222, v189, 0, s[4:5]
	v_pk_fma_f32 v[146:147], v[78:79], v[146:147], v[220:221]
	v_pk_fma_f32 v[144:145], v[64:65], v[224:225], v[144:145]
	v_pk_fma_f32 v[146:147], v[66:67], v[222:223], v[146:147]
	v_cmp_gt_f32_e32 vcc, s74, v192
	v_pk_add_f32 v[156:157], v[84:85], v[156:157]
	v_pk_add_f32 v[158:159], v[86:87], v[158:159]
	v_pk_add_f32 v[144:145], v[68:69], v[144:145]
	v_pk_add_f32 v[146:147], v[70:71], v[146:147]
	s_and_saveexec_b64 s[12:13], s[10:11]
	s_xor_b64 s[12:13], exec, s[12:13]
	s_cbranch_execz .LBB0_1280
; DI unsigned pack2(float lo, float hi) { f32x2 v = {lo, hi}; bf16v2 r = __builtin_convertvector(v, bf16v2); return __builtin_bit_cast(unsigned, r); }
; DI float silu_f(float x) { return x * sigmoid_f(x); }
;   DI void operator()(const f32x4 (&acc)[2][2][4][2], const Unit& u, int wr, int wc, int fr, int fq) const {
;     ...
;           u32x4 w;
;           w.x = pack2(silu_f(a[0]) * uu[0], silu_f(a[1]) * uu[1]);
;           w.y = pack2(silu_f(a[2]) * uu[2], silu_f(a[3]) * uu[3]);
;           w.z = pack2(silu_f(a[4]) * uu[4], silu_f(a[5]) * uu[5]);
;           w.w = pack2(silu_f(a[6]) * uu[6], silu_f(a[7]) * uu[7]);
;           *(u32x4*)(H + (size_t)(row0 + 16 * m + fr) * 5632 + col) = w;
	v_mul_f32_e32 v219, 0xbfb8aa3b, v156
	v_exp_f32_e32 v219, v219
	v_mul_f32_e32 v220, 0xbfb8aa3b, v157
	v_exp_f32_e32 v220, v220
	v_mul_f32_e32 v222, 0xbfb8aa3b, v159
	v_add_f32_e32 v219, 1.0, v219
	v_exp_f32_e32 v223, v222
	v_add_f32_e32 v221, 1.0, v220
	v_rcp_f32_e32 v220, v219
	v_mul_f32_e32 v219, 0xbfb8aa3b, v158
	v_exp_f32_e32 v219, v219
	v_rcp_f32_e32 v221, v221
	v_add_f32_e32 v219, 1.0, v219
	v_rcp_f32_e32 v222, v219
	v_add_f32_e32 v219, 1.0, v223
	v_rcp_f32_e32 v223, v219
	v_pk_mul_f32 v[156:157], v[156:157], v[220:221]
	s_nop 0
	v_pk_mul_f32 v[152:153], v[152:153], v[156:157]
	v_pk_mul_f32 v[156:157], v[158:159], v[222:223]
	v_cvt_pk_bf16_f32 v152, v152, v153
	v_mul_f32_e32 v153, 0xbfb8aa3b, v144
	v_pk_mul_f32 v[154:155], v[154:155], v[156:157]
	v_exp_f32_e32 v156, v153
	v_mul_f32_e32 v153, 0xbfb8aa3b, v145
	v_exp_f32_e32 v157, v153
	v_cvt_pk_bf16_f32 v153, v154, v155
	v_add_f32_e32 v154, 1.0, v156
	v_mul_f32_e32 v156, 0xbfb8aa3b, v146
	v_add_f32_e32 v155, 1.0, v157
	v_mul_f32_e32 v157, 0xbfb8aa3b, v147
	v_exp_f32_e32 v156, v156
	v_exp_f32_e32 v157, v157
	v_rcp_f32_e32 v154, v154
	v_rcp_f32_e32 v155, v155
	v_add_f32_e32 v156, 1.0, v156
	v_add_f32_e32 v157, 1.0, v157
	v_rcp_f32_e32 v156, v156
	v_rcp_f32_e32 v157, v157
	v_pk_mul_f32 v[144:145], v[144:145], v[154:155]
	s_nop 0
	v_pk_mul_f32 v[144:145], v[148:149], v[144:145]
	s_nop 0
	v_cvt_pk_bf16_f32 v154, v144, v145
	v_pk_mul_f32 v[144:145], v[146:147], v[156:157]
	s_nop 0
	v_pk_mul_f32 v[144:145], v[150:151], v[144:145]
	s_nop 0
	v_cvt_pk_bf16_f32 v155, v144, v145
	v_mov_b64_e32 v[144:145], s[20:21]
	v_mad_i64_i32 v[144:145], s[14:15], v190, s75, v[144:145]
	v_lshl_add_u64 v[144:145], v[180:181], 1, v[144:145]
	global_store_dwordx4 v[144:145], v[152:155], off

; #define PG8_STAGE(bufoff, gbase, voff) do { _Pragma("unroll") for (int _i = 0; _i < 2; ++_i) \
;     __builtin_amdgcn_global_load_lds((const unsigned*)((const char*)(gbase) + (voff)[_i]), (LAS unsigned*)(lds + (bufoff) + ldsw + _i * 8192), 16, 0, 0); } while (0)
; #define PG8_LDA(dst, b, h) do { _Pragma("unroll") for (int m = 0; m < 4; ++m) _Pragma("unroll") for (int k = 0; k < 2; ++k) dst[m][k] = *(const LAS bf16x8*)(lds + PG8_SA(b, h) + aoff + m * 2048 + k * 1024); } while (0)
; #define PG8_LDB(dst, b, h) do { _Pragma("unroll") for (int n = 0; n < 2; ++n) _Pragma("unroll") for (int k = 0; k < 2; ++k) dst[n][k] = *(const LAS bf16x8*)(lds + PG8_SB(b, h) + boff + n * 2048 + k * 1024); } while (0)
; #define PG8_MMA(ai, bj, At, Bt) do { __builtin_amdgcn_s_setprio(1); _Pragma("unroll") for (int m = 0; m < 4; ++m) _Pragma("unroll") for (int n = 0; n < 2; ++n) _Pragma("unroll") for (int k = 0; k < 2; ++k) \
;     acc[ai][bj][m][n] = __builtin_amdgcn_mfma_f32_16x16x32_bf16(Bt[n][k], At[m][k], acc[ai][bj][m][n], 0, 0, 0); __builtin_amdgcn_s_setprio(0); } while (0)
; #define PG8_WAIT_V(n) asm volatile("s_waitcnt vmcnt(" #n ")" ::: "memory")
; #define PG8_WAIT_L(n) asm volatile("s_waitcnt lgkmcnt(" #n ")" ::: "memory")
; #define PG8_BAR __builtin_amdgcn_s_barrier()
; #define PG8_SCHED __builtin_amdgcn_sched_barrier(0)
; template <class Epi, class Sched = StaticOrder>
; DI void gemm_phase(LAS unsigned char* lds, const Gemm g, const Sched& S, const Epi& E) {
;     ...
;       PG8_LDB(B0, 0, 0); PG8_SCHED; PG8_LDA(At, 0, 0); PG8_STAGE(PG8_SA(1, 1), a1 + hstep, voffA);
;       PG8_WAIT_L(8); PG8_BAR; PG8_WAIT_L(0); PG8_MMA(0, 0, At, B0); PG8_BAR; PG8_SCHED;
;       PG8_LDB(B1, 0, 1); PG8_STAGE(PG8_SB(0, 0), b2, voffB);
;       PG8_BAR; PG8_WAIT_L(0); PG8_MMA(0, 1, At, B1); PG8_BAR;
;       PG8_LDA(At, 0, 1); PG8_STAGE(PG8_SA(0, 0), a2, voffA);
;       PG8_BAR; PG8_WAIT_L(0); PG8_MMA(1, 0, At, B0); PG8_BAR; PG8_SCHED;
;       PG8_STAGE(PG8_SB(0, 1), b2 + hstep, voffB);
;       PG8_WAIT_V(6); PG8_BAR; PG8_MMA(1, 1, At, B1); PG8_BAR;
.LBB0_1424:
	s_add_u32 s18, s16, 0xffea0080
	s_addc_u32 s19, s17, -1
	s_cmpk_eq_i32 s47, 0x54
	s_cselect_b32 s21, s3, s19
	s_cselect_b32 s20, s2, s18
	s_cselect_b32 s19, s5, s46
	s_cselect_b32 s18, s4, s45
	v_lshl_add_u64 v[198:199], s[16:17], 0, v[136:137]
	s_add_i32 m0, s30, 0xc000
	ds_read_b128 v[166:169], v160
	ds_read_b128 v[170:173], v160 offset:1024
	ds_read_b128 v[174:177], v160 offset:2048
	ds_read_b128 v[178:181], v160 offset:3072
	ds_read_b128 v[182:185], v160 offset:4096
	ds_read_b128 v[186:189], v160 offset:5120
	ds_read_b128 v[190:193], v160 offset:6144
	ds_read_b128 v[194:197], v160 offset:7168
	global_load_lds_dwordx4 v[198:199], off
	v_lshl_add_u64 v[198:199], s[16:17], 0, v[138:139]
	s_add_i32 m0, s30, 0xe000
	s_nop 0
	global_load_lds_dwordx4 v[198:199], off
	s_waitcnt lgkmcnt(8)
	s_barrier
	s_waitcnt lgkmcnt(0)
	s_setprio 1
	v_mfma_f32_16x16x32_bf16 v[124:127], v[144:147], v[166:169], v[124:127]
	v_mfma_f32_16x16x32_bf16 v[120:123], v[152:155], v[166:169], v[120:123]
	v_mfma_f32_16x16x32_bf16 v[116:119], v[144:147], v[174:177], v[116:119]
	v_mfma_f32_16x16x32_bf16 v[112:115], v[152:155], v[174:177], v[112:115]
	v_mfma_f32_16x16x32_bf16 v[104:107], v[144:147], v[182:185], v[104:107]
	v_mfma_f32_16x16x32_bf16 v[96:99], v[152:155], v[182:185], v[96:99]
	v_mfma_f32_16x16x32_bf16 v[88:91], v[144:147], v[190:193], v[88:91]
	v_mfma_f32_16x16x32_bf16 v[80:83], v[152:155], v[190:193], v[80:83]
	v_mfma_f32_16x16x32_bf16 v[124:127], v[148:151], v[170:173], v[124:127]
	v_mfma_f32_16x16x32_bf16 v[120:123], v[162:165], v[170:173], v[120:123]
	v_mfma_f32_16x16x32_bf16 v[116:119], v[148:151], v[178:181], v[116:119]
	v_mfma_f32_16x16x32_bf16 v[112:115], v[162:165], v[178:181], v[112:115]
	v_mfma_f32_16x16x32_bf16 v[104:107], v[148:151], v[186:189], v[104:107]
	v_mfma_f32_16x16x32_bf16 v[96:99], v[162:165], v[186:189], v[96:99]
	v_mfma_f32_16x16x32_bf16 v[88:91], v[148:151], v[194:197], v[88:91]
	v_mfma_f32_16x16x32_bf16 v[80:83], v[162:165], v[194:197], v[80:83]
	s_barrier
	s_setprio 0
	s_add_i32 s48, s39, s28
	v_lshl_add_u64 v[214:215], s[18:19], 0, v[132:133]
	s_mov_b32 m0, s48
	ds_read_b128 v[198:201], v161
	ds_read_b128 v[202:205], v161 offset:1024
	ds_read_b128 v[206:209], v161 offset:2048
	ds_read_b128 v[210:213], v161 offset:3072
	global_load_lds_dwordx4 v[214:215], off
	v_lshl_add_u64 v[216:217], s[18:19], 0, v[128:129]
	s_add_i32 m0, s48, 0x2000
	s_nop 0
	global_load_lds_dwordx4 v[216:217], off
	s_barrier
	s_waitcnt lgkmcnt(0)
	s_setprio 1
	v_mfma_f32_16x16x32_bf16 v[108:111], v[198:201], v[166:169], v[108:111]
	v_mfma_f32_16x16x32_bf16 v[100:103], v[206:209], v[166:169], v[100:103]
	v_mfma_f32_16x16x32_bf16 v[92:95], v[198:201], v[174:177], v[92:95]
	v_mfma_f32_16x16x32_bf16 v[84:87], v[206:209], v[174:177], v[84:87]
	v_mfma_f32_16x16x32_bf16 v[76:79], v[198:201], v[182:185], v[76:79]
	v_mfma_f32_16x16x32_bf16 v[72:75], v[206:209], v[182:185], v[72:75]
	v_mfma_f32_16x16x32_bf16 v[68:71], v[198:201], v[190:193], v[68:71]
	v_mfma_f32_16x16x32_bf16 v[64:67], v[206:209], v[190:193], v[64:67]
	v_mfma_f32_16x16x32_bf16 v[108:111], v[202:205], v[170:173], v[108:111]
	v_mfma_f32_16x16x32_bf16 v[100:103], v[210:213], v[170:173], v[100:103]
	v_mfma_f32_16x16x32_bf16 v[92:95], v[202:205], v[178:181], v[92:95]
	v_mfma_f32_16x16x32_bf16 v[84:87], v[210:213], v[178:181], v[84:87]
	v_mfma_f32_16x16x32_bf16 v[76:79], v[202:205], v[186:189], v[76:79]
	v_mfma_f32_16x16x32_bf16 v[72:75], v[210:213], v[186:189], v[72:75]
	v_mfma_f32_16x16x32_bf16 v[68:71], v[202:205], v[194:197], v[68:71]
	v_mfma_f32_16x16x32_bf16 v[64:67], v[210:213], v[194:197], v[64:67]
	s_barrier
	s_setprio 0
	s_mov_b32 m0, s30
	v_lshl_add_u64 v[218:219], s[20:21], 0, v[134:135]
	ds_read_b128 v[166:169], v160 offset:16384
	ds_read_b128 v[170:173], v160 offset:17408
	ds_read_b128 v[174:177], v160 offset:18432
	ds_read_b128 v[178:181], v160 offset:19456
	ds_read_b128 v[182:185], v160 offset:20480
	ds_read_b128 v[186:189], v160 offset:21504
	ds_read_b128 v[190:193], v160 offset:22528
	ds_read_b128 v[194:197], v160 offset:23552
	global_load_lds_dwordx4 v[218:219], off
	v_lshl_add_u64 v[220:221], s[20:21], 0, v[130:131]
	s_mov_b32 m0, s31
	s_nop 0
	global_load_lds_dwordx4 v[220:221], off
	s_waitcnt vmcnt(10)
	s_barrier
	s_waitcnt lgkmcnt(0)
	s_setprio 1
	v_mfma_f32_16x16x32_bf16 v[60:63], v[144:147], v[166:169], v[60:63]
	v_mfma_f32_16x16x32_bf16 v[56:59], v[152:155], v[166:169], v[56:59]
	v_mfma_f32_16x16x32_bf16 v[52:55], v[144:147], v[174:177], v[52:55]
	v_mfma_f32_16x16x32_bf16 v[44:47], v[152:155], v[174:177], v[44:47]
	v_mfma_f32_16x16x32_bf16 v[36:39], v[144:147], v[182:185], v[36:39]
	v_mfma_f32_16x16x32_bf16 v[28:31], v[152:155], v[182:185], v[28:31]
	v_mfma_f32_16x16x32_bf16 v[20:23], v[144:147], v[190:193], v[20:23]
	v_mfma_f32_16x16x32_bf16 v[12:15], v[152:155], v[190:193], v[12:15]
	v_mfma_f32_16x16x32_bf16 v[60:63], v[148:151], v[170:173], v[60:63]
	v_mfma_f32_16x16x32_bf16 v[56:59], v[162:165], v[170:173], v[56:59]
	v_mfma_f32_16x16x32_bf16 v[52:55], v[148:151], v[178:181], v[52:55]
	v_mfma_f32_16x16x32_bf16 v[44:47], v[162:165], v[178:181], v[44:47]
	v_mfma_f32_16x16x32_bf16 v[36:39], v[148:151], v[186:189], v[36:39]
	v_mfma_f32_16x16x32_bf16 v[28:31], v[162:165], v[186:189], v[28:31]
	v_mfma_f32_16x16x32_bf16 v[20:23], v[148:151], v[194:197], v[20:23]
	v_mfma_f32_16x16x32_bf16 v[12:15], v[162:165], v[194:197], v[12:15]
	s_barrier
; #define PG8_STAGE(bufoff, gbase, voff) do { _Pragma("unroll") for (int _i = 0; _i < 2; ++_i) \
;     __builtin_amdgcn_global_load_lds((const unsigned*)((const char*)(gbase) + (voff)[_i]), (LAS unsigned*)(lds + (bufoff) + ldsw + _i * 8192), 16, 0, 0); } while (0)
; #define PG8_LDA(dst, b, h) do { _Pragma("unroll") for (int m = 0; m < 4; ++m) _Pragma("unroll") for (int k = 0; k < 2; ++k) dst[m][k] = *(const LAS bf16x8*)(lds + PG8_SA(b, h) + aoff + m * 2048 + k * 1024); } while (0)
; #define PG8_LDB(dst, b, h) do { _Pragma("unroll") for (int n = 0; n < 2; ++n) _Pragma("unroll") for (int k = 0; k < 2; ++k) dst[n][k] = *(const LAS bf16x8*)(lds + PG8_SB(b, h) + boff + n * 2048 + k * 1024); } while (0)
; #define PG8_MMA(ai, bj, At, Bt) do { __builtin_amdgcn_s_setprio(1); _Pragma("unroll") for (int m = 0; m < 4; ++m) _Pragma("unroll") for (int n = 0; n < 2; ++n) _Pragma("unroll") for (int k = 0; k < 2; ++k) \
;     acc[ai][bj][m][n] = __builtin_amdgcn_mfma_f32_16x16x32_bf16(Bt[n][k], At[m][k], acc[ai][bj][m][n], 0, 0, 0); __builtin_amdgcn_s_setprio(0); } while (0)
; #define PG8_WAIT_V(n) asm volatile("s_waitcnt vmcnt(" #n ")" ::: "memory")
; #define PG8_WAIT_L(n) asm volatile("s_waitcnt lgkmcnt(" #n ")" ::: "memory")
; #define PG8_BAR __builtin_amdgcn_s_barrier()
; #define PG8_SCHED __builtin_amdgcn_sched_barrier(0)
; template <class Epi, class Sched = StaticOrder>
; DI void gemm_phase(LAS unsigned char* lds, const Gemm g, const Sched& S, const Epi& E) {
;     ...
;       PG8_WAIT_V(6); PG8_BAR; PG8_MMA(1, 1, At, B1); PG8_BAR;
;       PG8_LDB(B0, 1, 0); PG8_SCHED; PG8_LDA(At, 1, 0); PG8_STAGE(PG8_SA(0, 1), a2 + hstep, voffA);
;       PG8_WAIT_L(8); PG8_BAR; PG8_WAIT_L(0); PG8_MMA(0, 0, At, B0); PG8_BAR; PG8_SCHED;
;       PG8_LDB(B1, 1, 1); PG8_STAGE(PG8_SB(1, 0), b3, voffB);
;       PG8_BAR; PG8_WAIT_L(0); PG8_MMA(0, 1, At, B1); PG8_BAR;
;       PG8_LDA(At, 1, 1); PG8_STAGE(PG8_SA(1, 0), a3, voffA);
	s_setprio 0
	s_add_u32 s48, s18, 0x160000
	s_addc_u32 s49, s19, 0
	s_add_i32 s50, s40, s28
	v_lshl_add_u64 v[144:145], s[48:49], 0, v[132:133]
	s_mov_b32 m0, s50
	s_nop 0
	global_load_lds_dwordx4 v[144:145], off
	v_lshl_add_u64 v[144:145], s[48:49], 0, v[128:129]
	s_add_i32 m0, s50, 0x2000
	s_nop 0
	global_load_lds_dwordx4 v[144:145], off
	s_add_i32 s48, 0, 0x18000
	v_add_u32_e32 v162, s48, v157
	ds_read_b128 v[144:147], v162
	ds_read_b128 v[148:151], v162 offset:1024
	ds_read_b128 v[152:155], v162 offset:2048
	ds_read_b128 v[162:165], v162 offset:3072
	s_waitcnt vmcnt(6)
	s_barrier
	s_setprio 1
	v_mfma_f32_16x16x32_bf16 v[48:51], v[198:201], v[166:169], v[48:51]
	v_mfma_f32_16x16x32_bf16 v[40:43], v[206:209], v[166:169], v[40:43]
	v_mfma_f32_16x16x32_bf16 v[32:35], v[198:201], v[174:177], v[32:35]
	v_mfma_f32_16x16x32_bf16 v[24:27], v[206:209], v[174:177], v[24:27]
	v_mfma_f32_16x16x32_bf16 v[16:19], v[198:201], v[182:185], v[16:19]
	v_mfma_f32_16x16x32_bf16 v[8:11], v[206:209], v[182:185], v[8:11]
	v_mfma_f32_16x16x32_bf16 v[4:7], v[198:201], v[190:193], v[4:7]
	v_mfma_f32_16x16x32_bf16 v[0:3], v[206:209], v[190:193], v[0:3]
	v_mfma_f32_16x16x32_bf16 v[48:51], v[202:205], v[170:173], v[48:51]
	v_mfma_f32_16x16x32_bf16 v[40:43], v[210:213], v[170:173], v[40:43]
	v_mfma_f32_16x16x32_bf16 v[32:35], v[202:205], v[178:181], v[32:35]
	v_mfma_f32_16x16x32_bf16 v[24:27], v[210:213], v[178:181], v[24:27]
	v_mfma_f32_16x16x32_bf16 v[16:19], v[202:205], v[186:189], v[16:19]
	v_mfma_f32_16x16x32_bf16 v[8:11], v[210:213], v[186:189], v[8:11]
	v_mfma_f32_16x16x32_bf16 v[4:7], v[202:205], v[194:197], v[4:7]
	v_mfma_f32_16x16x32_bf16 v[0:3], v[210:213], v[194:197], v[0:3]
	s_barrier
	s_setprio 0
	s_add_u32 s20, s20, 0x160000
	s_addc_u32 s21, s21, 0
	s_mov_b32 m0, s33
	v_lshl_add_u64 v[198:199], s[20:21], 0, v[134:135]
	ds_read_b128 v[166:169], v160 offset:32768
	ds_read_b128 v[170:173], v160 offset:33792
	ds_read_b128 v[174:177], v160 offset:34816
	ds_read_b128 v[178:181], v160 offset:35840
	ds_read_b128 v[182:185], v160 offset:36864
	ds_read_b128 v[186:189], v160 offset:37888
	ds_read_b128 v[190:193], v160 offset:38912
	ds_read_b128 v[194:197], v160 offset:39936
	global_load_lds_dwordx4 v[198:199], off
	v_lshl_add_u64 v[198:199], s[20:21], 0, v[130:131]
	s_mov_b32 m0, s34
	s_nop 0
	global_load_lds_dwordx4 v[198:199], off
	s_waitcnt lgkmcnt(8)
	s_barrier
	s_waitcnt lgkmcnt(0)
	s_setprio 1
	v_mfma_f32_16x16x32_bf16 v[124:127], v[144:147], v[166:169], v[124:127]
	v_mfma_f32_16x16x32_bf16 v[120:123], v[152:155], v[166:169], v[120:123]
	v_mfma_f32_16x16x32_bf16 v[116:119], v[144:147], v[174:177], v[116:119]
	v_mfma_f32_16x16x32_bf16 v[112:115], v[152:155], v[174:177], v[112:115]
	v_mfma_f32_16x16x32_bf16 v[104:107], v[144:147], v[182:185], v[104:107]
	v_mfma_f32_16x16x32_bf16 v[96:99], v[152:155], v[182:185], v[96:99]
	v_mfma_f32_16x16x32_bf16 v[88:91], v[144:147], v[190:193], v[88:91]
	v_mfma_f32_16x16x32_bf16 v[80:83], v[152:155], v[190:193], v[80:83]
	v_mfma_f32_16x16x32_bf16 v[124:127], v[148:151], v[170:173], v[124:127]
	v_mfma_f32_16x16x32_bf16 v[120:123], v[162:165], v[170:173], v[120:123]
	v_mfma_f32_16x16x32_bf16 v[116:119], v[148:151], v[178:181], v[116:119]
	v_mfma_f32_16x16x32_bf16 v[112:115], v[162:165], v[178:181], v[112:115]
	v_mfma_f32_16x16x32_bf16 v[104:107], v[148:151], v[186:189], v[104:107]
	v_mfma_f32_16x16x32_bf16 v[96:99], v[162:165], v[186:189], v[96:99]
	v_mfma_f32_16x16x32_bf16 v[88:91], v[148:151], v[194:197], v[88:91]
	v_mfma_f32_16x16x32_bf16 v[80:83], v[162:165], v[194:197], v[80:83]
	s_barrier
	s_setprio 0
	s_add_i32 s20, 0, 0x1c000
	s_add_i32 s21, s48, s28
	v_add_u32_e32 v210, s20, v157
	v_lshl_add_u64 v[214:215], v[214:215], 0, s[8:9]
	s_mov_b32 m0, s21
	ds_read_b128 v[198:201], v210
	ds_read_b128 v[202:205], v210 offset:1024
	ds_read_b128 v[206:209], v210 offset:2048
	ds_read_b128 v[210:213], v210 offset:3072
	global_load_lds_dwordx4 v[214:215], off
	v_lshl_add_u64 v[214:215], v[216:217], 0, s[8:9]
	s_add_i32 m0, s21, 0x2000
	s_nop 0
	global_load_lds_dwordx4 v[214:215], off
	s_barrier
	s_waitcnt lgkmcnt(0)
	s_setprio 1
	v_mfma_f32_16x16x32_bf16 v[108:111], v[198:201], v[166:169], v[108:111]
	v_mfma_f32_16x16x32_bf16 v[100:103], v[206:209], v[166:169], v[100:103]
	v_mfma_f32_16x16x32_bf16 v[92:95], v[198:201], v[174:177], v[92:95]
	v_mfma_f32_16x16x32_bf16 v[84:87], v[206:209], v[174:177], v[84:87]
	v_mfma_f32_16x16x32_bf16 v[76:79], v[198:201], v[182:185], v[76:79]
	v_mfma_f32_16x16x32_bf16 v[72:75], v[206:209], v[182:185], v[72:75]
	v_mfma_f32_16x16x32_bf16 v[68:71], v[198:201], v[190:193], v[68:71]
	v_mfma_f32_16x16x32_bf16 v[64:67], v[206:209], v[190:193], v[64:67]
	v_mfma_f32_16x16x32_bf16 v[108:111], v[202:205], v[170:173], v[108:111]
	v_mfma_f32_16x16x32_bf16 v[100:103], v[210:213], v[170:173], v[100:103]
	v_mfma_f32_16x16x32_bf16 v[92:95], v[202:205], v[178:181], v[92:95]
	v_mfma_f32_16x16x32_bf16 v[84:87], v[210:213], v[178:181], v[84:87]
	v_mfma_f32_16x16x32_bf16 v[76:79], v[202:205], v[186:189], v[76:79]
	v_mfma_f32_16x16x32_bf16 v[72:75], v[210:213], v[186:189], v[72:75]
	v_mfma_f32_16x16x32_bf16 v[68:71], v[202:205], v[194:197], v[68:71]
	v_mfma_f32_16x16x32_bf16 v[64:67], v[210:213], v[194:197], v[64:67]
	s_barrier
	s_setprio 0
	s_mov_b32 m0, s35
	v_lshl_add_u64 v[214:215], v[218:219], 0, s[8:9]
	ds_read_b128 v[166:169], v160 offset:49152
	ds_read_b128 v[170:173], v160 offset:50176
	ds_read_b128 v[174:177], v160 offset:51200
	ds_read_b128 v[178:181], v160 offset:52224
	ds_read_b128 v[182:185], v160 offset:53248
	ds_read_b128 v[186:189], v160 offset:54272
	ds_read_b128 v[190:193], v160 offset:55296
	ds_read_b128 v[194:197], v160 offset:56320
	global_load_lds_dwordx4 v[214:215], off
	v_lshl_add_u64 v[214:215], v[220:221], 0, s[8:9]
	s_mov_b32 m0, s36
	s_nop 0
	global_load_lds_dwordx4 v[214:215], off
	s_waitcnt vmcnt(10)
	s_barrier
; #define PG8_STAGE(bufoff, gbase, voff) do { _Pragma("unroll") for (int _i = 0; _i < 2; ++_i) \
;     __builtin_amdgcn_global_load_lds((const unsigned*)((const char*)(gbase) + (voff)[_i]), (LAS unsigned*)(lds + (bufoff) + ldsw + _i * 8192), 16, 0, 0); } while (0)
; #define PG8_MMA(ai, bj, At, Bt) do { __builtin_amdgcn_s_setprio(1); _Pragma("unroll") for (int m = 0; m < 4; ++m) _Pragma("unroll") for (int n = 0; n < 2; ++n) _Pragma("unroll") for (int k = 0; k < 2; ++k) \
;     acc[ai][bj][m][n] = __builtin_amdgcn_mfma_f32_16x16x32_bf16(Bt[n][k], At[m][k], acc[ai][bj][m][n], 0, 0, 0); __builtin_amdgcn_s_setprio(0); } while (0)
; #define PG8_WAIT_V(n) asm volatile("s_waitcnt vmcnt(" #n ")" ::: "memory")
; #define PG8_WAIT_L(n) asm volatile("s_waitcnt lgkmcnt(" #n ")" ::: "memory")
; #define PG8_BAR __builtin_amdgcn_s_barrier()
; #define PG8_SCHED __builtin_amdgcn_sched_barrier(0)
;   DI void operator()(const f32x4 (&acc)[2][2][4][2], const Unit& u, int wr, int wc, int fr, int fq) const {
;     const int row0 = u.pm * BM + wr * 64 + fr, col0 = u.pn * BM + wc * 32 + 8 * fq;
; #pragma unroll
;     for (int ai = 0; ai < 2; ++ai) {
;       f32x4 bv[4][2][2];
; #pragma unroll
;       for (int m = 0; m < 4; ++m)
; #pragma unroll
;         for (int bj = 0; bj < 2; ++bj) {
;           const float* bp = base + (size_t)(row0 + ai * HALF + m * 16) * 2048 + col0 + bj * HALF;
;           bv[m][bj][0] = *(const f32x4*)bp; bv[m][bj][1] = *(const f32x4*)(bp + 4);
;         }
; template <class Epi, class Sched = StaticOrder>
; DI void gemm_phase(LAS unsigned char* lds, const Gemm g, const Sched& S, const Epi& E) {
;     ...
;       PG8_BAR; PG8_WAIT_L(0); PG8_MMA(1, 0, At, B0); PG8_BAR; PG8_SCHED;
;       PG8_STAGE(PG8_SB(1, 1), b3 + hstep, voffB);
;       PG8_WAIT_V(6); PG8_BAR; PG8_MMA(1, 1, At, B1); PG8_BAR;
;     }
	s_waitcnt lgkmcnt(0)
	s_setprio 1
	v_mfma_f32_16x16x32_bf16 v[60:63], v[144:147], v[166:169], v[60:63]
	v_mfma_f32_16x16x32_bf16 v[56:59], v[152:155], v[166:169], v[56:59]
	v_mfma_f32_16x16x32_bf16 v[52:55], v[144:147], v[174:177], v[52:55]
	v_mfma_f32_16x16x32_bf16 v[44:47], v[152:155], v[174:177], v[44:47]
	v_mfma_f32_16x16x32_bf16 v[36:39], v[144:147], v[182:185], v[36:39]
	v_mfma_f32_16x16x32_bf16 v[28:31], v[152:155], v[182:185], v[28:31]
	v_mfma_f32_16x16x32_bf16 v[20:23], v[144:147], v[190:193], v[20:23]
	v_mfma_f32_16x16x32_bf16 v[12:15], v[152:155], v[190:193], v[12:15]
	v_mfma_f32_16x16x32_bf16 v[60:63], v[148:151], v[170:173], v[60:63]
	v_mfma_f32_16x16x32_bf16 v[56:59], v[162:165], v[170:173], v[56:59]
	v_mfma_f32_16x16x32_bf16 v[52:55], v[148:151], v[178:181], v[52:55]
	v_mfma_f32_16x16x32_bf16 v[44:47], v[162:165], v[178:181], v[44:47]
	v_mfma_f32_16x16x32_bf16 v[36:39], v[148:151], v[186:189], v[36:39]
	v_mfma_f32_16x16x32_bf16 v[28:31], v[162:165], v[186:189], v[28:31]
	v_mfma_f32_16x16x32_bf16 v[20:23], v[148:151], v[194:197], v[20:23]
	v_mfma_f32_16x16x32_bf16 v[12:15], v[162:165], v[194:197], v[12:15]
	s_barrier
	s_setprio 0
	s_add_u32 s18, s18, 0x160080
	s_addc_u32 s19, s19, 0
	s_add_i32 s20, s20, s28
	v_lshl_add_u64 v[144:145], s[18:19], 0, v[132:133]
	s_mov_b32 m0, s20
	s_nop 0
	global_load_lds_dwordx4 v[144:145], off
	v_lshl_add_u64 v[144:145], s[18:19], 0, v[128:129]
	s_add_i32 m0, s20, 0x2000
	s_nop 0
	global_load_lds_dwordx4 v[144:145], off
	ds_read_b128 v[144:147], v159
	ds_read_b128 v[148:151], v159 offset:1024
	ds_read_b128 v[152:155], v159 offset:2048
	ds_read_b128 v[162:165], v159 offset:3072
	s_waitcnt vmcnt(6)
	s_barrier
	s_setprio 1
	v_mfma_f32_16x16x32_bf16 v[48:51], v[198:201], v[166:169], v[48:51]
	v_mfma_f32_16x16x32_bf16 v[40:43], v[206:209], v[166:169], v[40:43]
	v_mfma_f32_16x16x32_bf16 v[32:35], v[198:201], v[174:177], v[32:35]
	v_mfma_f32_16x16x32_bf16 v[24:27], v[206:209], v[174:177], v[24:27]
	v_mfma_f32_16x16x32_bf16 v[16:19], v[198:201], v[182:185], v[16:19]
	v_mfma_f32_16x16x32_bf16 v[8:11], v[206:209], v[182:185], v[8:11]
	v_mfma_f32_16x16x32_bf16 v[4:7], v[198:201], v[190:193], v[4:7]
	v_mfma_f32_16x16x32_bf16 v[0:3], v[206:209], v[190:193], v[0:3]
	v_mfma_f32_16x16x32_bf16 v[48:51], v[202:205], v[170:173], v[48:51]
	v_mfma_f32_16x16x32_bf16 v[40:43], v[210:213], v[170:173], v[40:43]
	v_mfma_f32_16x16x32_bf16 v[32:35], v[202:205], v[178:181], v[32:35]
	v_mfma_f32_16x16x32_bf16 v[24:27], v[210:213], v[178:181], v[24:27]
	v_mfma_f32_16x16x32_bf16 v[16:19], v[202:205], v[186:189], v[16:19]
	v_mfma_f32_16x16x32_bf16 v[8:11], v[210:213], v[186:189], v[8:11]
	v_mfma_f32_16x16x32_bf16 v[4:7], v[202:205], v[194:197], v[4:7]
	v_mfma_f32_16x16x32_bf16 v[0:3], v[210:213], v[194:197], v[0:3]
	s_add_i32 s47, s47, 2
	s_add_u32 s16, s16, 0x100
	s_addc_u32 s17, s17, 0
	s_add_u32 s45, s45, 0x100
	s_addc_u32 s46, s46, 0
	s_cmpk_gt_u32 s47, 0x55
	s_barrier
	s_setprio 0
	s_cbranch_scc0 .LBB0_1424
	s_waitcnt lgkmcnt(0)
	v_lshl_or_b32 v144, s44, 8, v158
	v_lshl_add_u32 v154, s43, 8, v156
	v_ashrrev_i32_e32 v145, 31, v144
	v_lshlrev_b64 v[144:145], 2, v[144:145]
	v_ashrrev_i32_e32 v155, 31, v154
	v_lshl_add_u64 v[146:147], s[54:55], 0, v[144:145]
	v_lshlrev_b64 v[148:149], 13, v[154:155]
	v_or_b32_e32 v174, 16, v154
	v_lshl_add_u64 v[170:171], v[146:147], 0, v[148:149]
	v_ashrrev_i32_e32 v175, 31, v174
	global_load_dwordx4 v[150:153], v[170:171], off offset:16
	global_load_dwordx4 v[162:165], v[170:171], off
	global_load_dwordx4 v[166:169], v[170:171], off offset:528
	s_nop 0
	global_load_dwordx4 v[170:173], v[170:171], off offset:512
	v_lshlrev_b64 v[222:223], 13, v[174:175]
	v_or_b32_e32 v190, 32, v154
	v_lshl_add_u64 v[186:187], v[146:147], 0, v[222:223]
	v_ashrrev_i32_e32 v191, 31, v190
	global_load_dwordx4 v[174:177], v[186:187], off offset:16
	global_load_dwordx4 v[178:181], v[186:187], off
	global_load_dwordx4 v[182:185], v[186:187], off offset:528
	s_nop 0
	global_load_dwordx4 v[186:189], v[186:187], off offset:512
	v_lshlrev_b64 v[224:225], 13, v[190:191]
	v_or_b32_e32 v154, 48, v154
	v_lshl_add_u64 v[202:203], v[146:147], 0, v[224:225]
	v_ashrrev_i32_e32 v155, 31, v154
	global_load_dwordx4 v[190:193], v[202:203], off offset:16
	global_load_dwordx4 v[194:197], v[202:203], off
	global_load_dwordx4 v[198:201], v[202:203], off offset:528
	s_nop 0
	global_load_dwordx4 v[202:205], v[202:203], off offset:512
	v_lshlrev_b64 v[154:155], 13, v[154:155]
	v_lshl_add_u64 v[218:219], v[146:147], 0, v[154:155]
	global_load_dwordx4 v[206:209], v[218:219], off offset:16
	global_load_dwordx4 v[210:213], v[218:219], off
	global_load_dwordx4 v[214:217], v[218:219], off offset:528
	s_nop 0
	global_load_dwordx4 v[218:221], v[218:219], off offset:512
	s_and_b64 vcc, exec, s[0:1]
	s_mov_b32 s44, s41
	s_mov_b32 s43, s42
	s_mov_b64 s[18:19], s[4:5]
	s_mov_b64 s[16:17], s[2:3]
	s_waitcnt vmcnt(0)
; DI unsigned pack2(float lo, float hi) { f32x2 v = {lo, hi}; bf16v2 r = __builtin_convertvector(v, bf16v2); return __builtin_bit_cast(unsigned, r); }
; #define PG8_WAIT_V(n) asm volatile("s_waitcnt vmcnt(" #n ")" ::: "memory")
; #define PG8_BAR __builtin_amdgcn_s_barrier()
;   DI void operator()(const f32x4 (&acc)[2][2][4][2], const Unit& u, int wr, int wc, int fr, int fq) const {
;     ...
;     for (int ai = 0; ai < 2; ++ai) {
;       f32x4 bv[4][2][2];
; #pragma unroll
;       for (int m = 0; m < 4; ++m)
; #pragma unroll
;         for (int bj = 0; bj < 2; ++bj) {
;           const float* bp = base + (size_t)(row0 + ai * HALF + m * 16) * 2048 + col0 + bj * HALF;
;           bv[m][bj][0] = *(const f32x4*)bp; bv[m][bj][1] = *(const f32x4*)(bp + 4);
;         }
; #pragma unroll
;       for (int m = 0; m < 4; ++m) {
;         const int row = row0 + ai * HALF + m * 16;
;         const size_t off = (size_t)row * 2048 + col0;
;         float ss = 0.f;
; #pragma unroll
;         for (int bj = 0; bj < 2; ++bj) {
;           const f32x4 v0 = acc[ai][bj][m][0] + bv[m][bj][0], v1 = acc[ai][bj][m][1] + bv[m][bj][1];
;           *(f32x4*)(C + off + bj * HALF) = v0; *(f32x4*)(C + off + bj * HALF + 4) = v1;
;           if (xb) {
;             u32x4 w; w.x = pack2(v0[0], v0[1]); w.y = pack2(v0[2], v0[3]); w.z = pack2(v1[0], v1[1]); w.w = pack2(v1[2], v1[3]);
;             *(u32x4*)(xb + off + bj * HALF) = w;
;             ss += v0[0] * v0[0] + v0[1] * v0[1] + v0[2] * v0[2] + v0[3] * v0[3] + v1[0] * v1[0] + v1[1] * v1[1] + v1[2] * v1[2] + v1[3] * v1[3];
;           }
;         }
;         if (xb) {
;           ss += __shfl_xor(ss, 16); ss += __shfl_xor(ss, 32);
;           if (fq == 0) ssq[(size_t)row * 32 + u.pn * 4 + wc] = ss;
;         }
;       }
;     }
; template <class Epi, class Sched = StaticOrder>
; DI void gemm_phase(LAS unsigned char* lds, const Gemm g, const Sched& S, const Epi& E) {
;     ...
;     E(acc, cur, wr, wc, fr, fq);
;     if (!has_next) break;
; #pragma unroll
;     for (int a = 0; a < 2; ++a)
; #pragma unroll
;       for (int b = 0; b < 2; ++b)
; #pragma unroll
;         for (int m = 0; m < 4; ++m)
; #pragma unroll
;           for (int n = 0; n < 2; ++n) acc[a][b][m][n] = (f32x4){0.f, 0.f, 0.f, 0.f};
;     cur = nxt; cA = nA; cB = nB; ++ui;
;   }
;   PG8_WAIT_V(0);
;   if (wr == 0) PG8_BAR;
	v_pk_add_f32 v[120:121], v[120:121], v[150:151]
	v_lshl_add_u64 v[150:151], s[54:55], 0, v[148:149]
	v_pk_add_f32 v[126:127], v[126:127], v[164:165]
	v_pk_add_f32 v[124:125], v[124:125], v[162:163]
	v_lshl_add_u64 v[150:151], v[150:151], 0, v[144:145]
	v_pk_add_f32 v[110:111], v[110:111], v[172:173]
	v_pk_add_f32 v[108:109], v[108:109], v[170:171]
	v_pk_add_f32 v[122:123], v[122:123], v[152:153]
	global_store_dwordx4 v[150:151], v[124:127], off
	global_store_dwordx4 v[150:151], v[120:123], off offset:16
	v_pk_add_f32 v[102:103], v[102:103], v[168:169]
	v_pk_add_f32 v[100:101], v[100:101], v[166:167]
	global_store_dwordx4 v[150:151], v[108:111], off offset:512
	global_store_dwordx4 v[150:151], v[100:103], off offset:528
	v_pk_add_f32 v[94:95], v[94:95], v[188:189]
	v_pk_add_f32 v[108:109], v[112:113], v[174:175]
	v_lshl_add_u64 v[112:113], s[54:55], 0, v[222:223]
	v_pk_add_f32 v[102:103], v[118:119], v[180:181]
	v_pk_add_f32 v[100:101], v[116:117], v[178:179]
	v_lshl_add_u64 v[112:113], v[112:113], 0, v[144:145]
	v_pk_add_f32 v[92:93], v[92:93], v[186:187]
	v_pk_add_f32 v[110:111], v[114:115], v[176:177]
	global_store_dwordx4 v[112:113], v[100:103], off
	global_store_dwordx4 v[112:113], v[108:111], off offset:16
	v_pk_add_f32 v[86:87], v[86:87], v[184:185]
	v_pk_add_f32 v[84:85], v[84:85], v[182:183]
	global_store_dwordx4 v[112:113], v[92:95], off offset:512
	global_store_dwordx4 v[112:113], v[84:87], off offset:528
	v_pk_add_f32 v[78:79], v[78:79], v[204:205]
	v_pk_add_f32 v[92:93], v[96:97], v[190:191]
	v_lshl_add_u64 v[96:97], s[54:55], 0, v[224:225]
	v_pk_add_f32 v[86:87], v[106:107], v[196:197]
	v_pk_add_f32 v[84:85], v[104:105], v[194:195]
	v_lshl_add_u64 v[96:97], v[96:97], 0, v[144:145]
	v_pk_add_f32 v[76:77], v[76:77], v[202:203]
	v_pk_add_f32 v[94:95], v[98:99], v[192:193]
	global_store_dwordx4 v[96:97], v[84:87], off
	global_store_dwordx4 v[96:97], v[92:95], off offset:16
	v_pk_add_f32 v[74:75], v[74:75], v[200:201]
	v_pk_add_f32 v[72:73], v[72:73], v[198:199]
	global_store_dwordx4 v[96:97], v[76:79], off offset:512
	global_store_dwordx4 v[96:97], v[72:75], off offset:528
	v_pk_add_f32 v[70:71], v[70:71], v[220:221]
	v_pk_add_f32 v[76:77], v[80:81], v[206:207]
	v_lshl_add_u64 v[80:81], s[54:55], 0, v[154:155]
	v_pk_add_f32 v[74:75], v[90:91], v[212:213]
	v_pk_add_f32 v[72:73], v[88:89], v[210:211]
	v_lshl_add_u64 v[80:81], v[80:81], 0, v[144:145]
	v_pk_add_f32 v[68:69], v[68:69], v[218:219]
	v_pk_add_f32 v[64:65], v[64:65], v[214:215]
	v_lshl_add_u64 v[154:155], v[148:149], 0, s[10:11]
	v_pk_add_f32 v[78:79], v[82:83], v[208:209]
	global_store_dwordx4 v[80:81], v[72:75], off
	global_store_dwordx4 v[80:81], v[76:79], off offset:16
	v_pk_add_f32 v[66:67], v[66:67], v[216:217]
	global_store_dwordx4 v[80:81], v[68:71], off offset:512
	global_store_dwordx4 v[80:81], v[64:67], off offset:528
	v_lshl_add_u64 v[152:153], v[148:149], 0, s[12:13]
	v_lshl_add_u64 v[150:151], v[148:149], 0, s[14:15]
	v_lshl_add_u64 v[64:65], v[146:147], 0, v[154:155]
	global_load_dwordx4 v[108:111], v[64:65], off offset:16
	global_load_dwordx4 v[120:123], v[64:65], off
	global_load_dwordx4 v[92:95], v[64:65], off offset:528
	global_load_dwordx4 v[100:103], v[64:65], off offset:512
	v_lshl_add_u64 v[64:65], v[146:147], 0, v[152:153]
	global_load_dwordx4 v[88:91], v[64:65], off offset:16
	global_load_dwordx4 v[96:99], v[64:65], off
	global_load_dwordx4 v[76:79], v[64:65], off offset:528
	global_load_dwordx4 v[84:87], v[64:65], off offset:512
	v_lshl_add_u64 v[68:69], v[146:147], 0, v[150:151]
	global_load_dwordx4 v[72:75], v[68:69], off offset:16
	global_load_dwordx4 v[80:83], v[68:69], off
	global_load_dwordx4 v[64:67], v[68:69], off offset:528
	s_nop 0
	global_load_dwordx4 v[68:71], v[68:69], off offset:512
	v_lshl_add_u64 v[148:149], v[148:149], 0, s[6:7]
	v_lshl_add_u64 v[112:113], v[146:147], 0, v[148:149]
	global_load_dwordx4 v[116:119], v[112:113], off offset:16
	global_load_dwordx4 v[124:127], v[112:113], off
	global_load_dwordx4 v[104:107], v[112:113], off offset:528
	s_nop 0
	global_load_dwordx4 v[112:115], v[112:113], off offset:512
	s_waitcnt vmcnt(0)
	v_pk_add_f32 v[56:57], v[56:57], v[108:109]
	v_lshl_add_u64 v[108:109], s[54:55], 0, v[154:155]
	v_pk_add_f32 v[62:63], v[62:63], v[122:123]
	v_pk_add_f32 v[60:61], v[60:61], v[120:121]
	v_lshl_add_u64 v[108:109], v[108:109], 0, v[144:145]
	v_pk_add_f32 v[50:51], v[50:51], v[102:103]
	v_pk_add_f32 v[48:49], v[48:49], v[100:101]
	v_pk_add_f32 v[58:59], v[58:59], v[110:111]
	global_store_dwordx4 v[108:109], v[60:63], off
	global_store_dwordx4 v[108:109], v[56:59], off offset:16
	v_pk_add_f32 v[42:43], v[42:43], v[94:95]
	v_pk_add_f32 v[40:41], v[40:41], v[92:93]
	global_store_dwordx4 v[108:109], v[48:51], off offset:512
	global_store_dwordx4 v[108:109], v[40:43], off offset:528
	v_pk_add_f32 v[34:35], v[34:35], v[86:87]
	v_lshl_add_u64 v[48:49], s[54:55], 0, v[152:153]
	v_pk_add_f32 v[42:43], v[54:55], v[98:99]
	v_pk_add_f32 v[40:41], v[52:53], v[96:97]
	v_lshl_add_u64 v[48:49], v[48:49], 0, v[144:145]
	v_pk_add_f32 v[32:33], v[32:33], v[84:85]
	v_pk_add_f32 v[46:47], v[46:47], v[90:91]
	v_pk_add_f32 v[44:45], v[44:45], v[88:89]
	global_store_dwordx4 v[48:49], v[40:43], off
	global_store_dwordx4 v[48:49], v[44:47], off offset:16
	v_pk_add_f32 v[26:27], v[26:27], v[78:79]
	v_pk_add_f32 v[24:25], v[24:25], v[76:77]
	global_store_dwordx4 v[48:49], v[32:35], off offset:512
	global_store_dwordx4 v[48:49], v[24:27], off offset:528
	v_pk_add_f32 v[18:19], v[18:19], v[70:71]
	v_lshl_add_u64 v[32:33], s[54:55], 0, v[150:151]
	v_pk_add_f32 v[26:27], v[38:39], v[82:83]
	v_pk_add_f32 v[24:25], v[36:37], v[80:81]
	v_lshl_add_u64 v[32:33], v[32:33], 0, v[144:145]
	v_pk_add_f32 v[16:17], v[16:17], v[68:69]
	v_pk_add_f32 v[30:31], v[30:31], v[74:75]
	v_pk_add_f32 v[28:29], v[28:29], v[72:73]
	global_store_dwordx4 v[32:33], v[24:27], off
	global_store_dwordx4 v[32:33], v[28:31], off offset:16
	v_pk_add_f32 v[10:11], v[10:11], v[66:67]
	v_pk_add_f32 v[8:9], v[8:9], v[64:65]
	global_store_dwordx4 v[32:33], v[16:19], off offset:512
	global_store_dwordx4 v[32:33], v[8:11], off offset:528
	v_pk_add_f32 v[6:7], v[6:7], v[114:115]
	v_lshl_add_u64 v[16:17], s[54:55], 0, v[148:149]
	v_pk_add_f32 v[10:11], v[22:23], v[126:127]
	v_pk_add_f32 v[8:9], v[20:21], v[124:125]
	v_lshl_add_u64 v[16:17], v[16:17], 0, v[144:145]
	v_pk_add_f32 v[4:5], v[4:5], v[112:113]
	v_pk_add_f32 v[14:15], v[14:15], v[118:119]
	v_pk_add_f32 v[12:13], v[12:13], v[116:117]
	global_store_dwordx4 v[16:17], v[8:11], off
	global_store_dwordx4 v[16:17], v[12:15], off offset:16
	v_pk_add_f32 v[2:3], v[2:3], v[106:107]
	v_pk_add_f32 v[0:1], v[0:1], v[104:105]
	global_store_dwordx4 v[16:17], v[4:7], off offset:512
	global_store_dwordx4 v[16:17], v[0:3], off offset:528
	s_cbranch_vccz .LBB0_1417
	s_waitcnt vmcnt(0)
	s_cmpk_gt_u32 s23, 0xff
	s_cbranch_scc1 .LBB0_1428
	s_barrier
